# norm phases: residual-stream row loads marked non-temporal
# baseline (speedup 1.0000x reference)
; DI void norm_phase(const Args& A, int wave_s, int l, int which, int rows) {
;     ...
;     f32x4 g[4];
; #pragma unroll
;     for (int j = 0; j < 4; ++j) g[j] = *(const f32x4*)(gn + 4 * (C.lane + 64 * j));
;     for (int m0 = C.gw * 2; m0 < rows; m0 += C.NGW * 2) {
;         f32x4 xv[2][4];
;         const float* modp[2];
; #pragma unroll
;         for (int rr = 0; rr < 2; ++rr) {
;             const int m = m0 + rr; const float* xr; int v;
;             if (m < NLAT) { xr = (from_in ? C.x : C.out) + (size_t)m * 1024; v = m >> 13; }
;             else { xr = (from_in ? C.ctx : C.XC) + (size_t)(m - NLAT) * 1024; v = 4; }
;             modp[rr] = C.SM + SM_MOD + (l * 5 + v) * 6144 + (which == 1 ? 0 : 3072);
; #pragma unroll
;             for (int j = 0; j < 4; ++j) xv[rr][j] = ((const f32x4*)xr)[C.lane + 64 * j];
;         }
; #pragma unroll
;         for (int rr = 0; rr < 2; ++rr) {
;             const int m = m0 + rr;
;             f32x4 sh[4], sc[4];
; #pragma unroll
;             for (int j = 0; j < 4; ++j) { const int col = 4 * (C.lane + 64 * j); sh[j] = *(const f32x4*)(modp[rr] + col); sc[j] = *(const f32x4*)(modp[rr] + 1024 + col); }
.LBB0_55:
	s_lshl_b32 s4, s56, 10
	s_mov_b32 s5, s97
	v_writelane_b32 v255, s4, 32
	s_mul_i32 s45, s56, 5
	v_mbcnt_lo_u32_b32 v48, -1, 0
	v_mbcnt_hi_u32_b32 v48, -1, v48
	s_nop 0
	v_writelane_b32 v255, s5, 33
	v_mbcnt_lo_u32_b32 v0, -1, 0
	v_mbcnt_hi_u32_b32 v0, -1, v0
	v_readlane_b32 s6, v255, 32
	v_lshlrev_b32_e32 v1, 4, v0
	v_lshlrev_b32_e32 v2, 3, v0
	v_xor_b32_e32 v4, 1, v0
	v_xor_b32_e32 v5, 2, v0
	v_xor_b32_e32 v6, 4, v0
	v_xor_b32_e32 v7, 8, v0
	v_xor_b32_e32 v8, 16, v0
	v_xor_b32_e32 v9, 32, v0
	v_lshlrev_b32_e32 v4, 2, v4
	v_lshlrev_b32_e32 v5, 2, v5
	v_lshlrev_b32_e32 v6, 2, v6
	v_lshlrev_b32_e32 v7, 2, v7
	v_lshlrev_b32_e32 v8, 2, v8
	v_lshlrev_b32_e32 v9, 2, v9
	v_mov_b32_e32 v60, 0x358637bd
	s_lshr_b32 s6, s6, 10
	s_lshr_b32 s4, s94, 6
	s_lshl_b32 s5, s65, 3
	s_add_u32 s4, s4, s5
	s_lshr_b32 s5, s4, 9
	s_mul_i32 s7, s6, 5
	s_add_u32 s5, s7, s5
	s_mul_i32 s5, s5, 0x6000
	s_add_u32 s24, s88, 0x100000
	s_addc_u32 s25, s89, 0
	s_add_u32 s24, s24, s5
	s_addc_u32 s25, s25, 0
	s_add_u32 s26, s24, 0x1000
	s_addc_u32 s27, s25, 0
	v_readlane_b32 s28, v252, 46
	v_readlane_b32 s29, v252, 47
	s_lshl_b32 s7, s6, 12
	s_nop 1
	s_add_u32 s28, s28, s7
	s_addc_u32 s29, s29, 0
	v_readlane_b32 s8, v252, 31
	v_readlane_b32 s9, v252, 32
	s_add_u32 s30, s88, 0x3400000
	s_addc_u32 s31, s89, 0
	v_readlane_b32 s10, v252, 34
	v_readlane_b32 s11, v252, 35
	v_readlane_b32 s2, v252, 38
	v_readlane_b32 s32, v252, 39
	s_nop 1
	s_cmp_eq_u32 s6, 0
	s_cselect_b32 s8, s10, s8
	s_cselect_b32 s9, s11, s9
	s_cselect_b32 s30, s2, s30
	s_cselect_b32 s31, s32, s31
	s_mov_b32 s2, 1
	s_cmp_lt_u32 s4, 0x400
	s_cselect_b32 s2, s2, 0
	s_and_b32 s7, s4, 0x3ff
	s_lshl_b32 s5, s7, 12
	s_add_u32 s30, s30, s5
	s_addc_u32 s31, s31, 0
	s_lshl_b32 s5, s4, 16
	s_add_u32 s8, s8, s5
	s_addc_u32 s9, s9, 0
	s_add_u32 s10, s88, 0x3800000
	s_addc_u32 s11, s89, 0
	s_lshl_b32 s5, s4, 15
	s_add_u32 s10, s10, s5
	s_addc_u32 s11, s11, 0
	s_mov_b32 s32, 0x3a800000
	global_load_dwordx4 v[24:27], v1, s[28:29]
	global_load_dwordx4 v[28:31], v1, s[28:29] offset:1024
	global_load_dwordx4 v[32:35], v1, s[28:29] offset:2048
	global_load_dwordx4 v[36:39], v1, s[28:29] offset:3072
	global_load_dwordx4 v[40:43], v1, s[26:27]
	global_load_dwordx4 v[64:67], v1, s[26:27] offset:1024
	global_load_dwordx4 v[68:71], v1, s[26:27] offset:2048
	global_load_dwordx4 v[72:75], v1, s[26:27] offset:3072
	global_load_dwordx4 v[80:83], v1, s[24:25]
	global_load_dwordx4 v[84:87], v1, s[24:25] offset:1024
	global_load_dwordx4 v[88:91], v1, s[24:25] offset:2048
	global_load_dwordx4 v[92:95], v1, s[24:25] offset:3072
	global_load_dwordx4 v[96:99], v1, s[8:9] nt
	global_load_dwordx4 v[100:103], v1, s[8:9] offset:1024 nt
	global_load_dwordx4 v[104:107], v1, s[8:9] offset:2048 nt
	global_load_dwordx4 v[108:111], v1, s[8:9] offset:3072 nt
	s_add_u32 s8, s8, 0x1000
	s_addc_u32 s9, s9, 0
	global_load_dwordx4 v[112:115], v1, s[8:9] nt
	global_load_dwordx4 v[116:119], v1, s[8:9] offset:1024 nt
	global_load_dwordx4 v[120:123], v1, s[8:9] offset:2048 nt
	global_load_dwordx4 v[124:127], v1, s[8:9] offset:3072 nt
	s_add_u32 s8, s8, 0x1000
	s_addc_u32 s9, s9, 0
	global_load_dwordx4 v[128:131], v1, s[8:9] nt
	global_load_dwordx4 v[132:135], v1, s[8:9] offset:1024 nt
	global_load_dwordx4 v[136:139], v1, s[8:9] offset:2048 nt
	global_load_dwordx4 v[140:143], v1, s[8:9] offset:3072 nt
	s_add_u32 s8, s8, 0x1000
	s_addc_u32 s9, s9, 0
	global_load_dwordx4 v[144:147], v1, s[8:9] nt
	global_load_dwordx4 v[148:151], v1, s[8:9] offset:1024 nt
	global_load_dwordx4 v[152:155], v1, s[8:9] offset:2048 nt
	global_load_dwordx4 v[156:159], v1, s[8:9] offset:3072 nt
	s_add_u32 s8, s8, 0x1000
	s_addc_u32 s9, s9, 0
	global_load_dwordx4 v[164:167], v1, s[8:9] nt
	global_load_dwordx4 v[168:171], v1, s[8:9] offset:1024 nt
	global_load_dwordx4 v[172:175], v1, s[8:9] offset:2048 nt
	global_load_dwordx4 v[176:179], v1, s[8:9] offset:3072 nt
	s_add_u32 s8, s8, 0x1000
	s_addc_u32 s9, s9, 0
	global_load_dwordx4 v[180:183], v1, s[8:9] nt
	global_load_dwordx4 v[184:187], v1, s[8:9] offset:1024 nt
	global_load_dwordx4 v[188:191], v1, s[8:9] offset:2048 nt
	global_load_dwordx4 v[192:195], v1, s[8:9] offset:3072 nt
	s_add_u32 s8, s8, 0x1000
	s_addc_u32 s9, s9, 0
	global_load_dwordx4 v[196:199], v1, s[8:9] nt
	global_load_dwordx4 v[200:203], v1, s[8:9] offset:1024 nt
	global_load_dwordx4 v[204:207], v1, s[8:9] offset:2048 nt
	global_load_dwordx4 v[208:211], v1, s[8:9] offset:3072 nt
	s_add_u32 s8, s8, 0x1000
	s_addc_u32 s9, s9, 0
	global_load_dwordx4 v[212:215], v1, s[8:9] nt
	global_load_dwordx4 v[216:219], v1, s[8:9] offset:1024 nt
	global_load_dwordx4 v[220:223], v1, s[8:9] offset:2048 nt
	global_load_dwordx4 v[224:227], v1, s[8:9] offset:3072 nt
	s_add_u32 s8, s8, 0x1000
	s_addc_u32 s9, s9, 0
	s_waitcnt vmcnt(32)
	v_pk_add_f32 v[40:41], v[40:41], 1.0 op_sel_hi:[1,0]
	v_pk_add_f32 v[42:43], v[42:43], 1.0 op_sel_hi:[1,0]
	v_pk_add_f32 v[64:65], v[64:65], 1.0 op_sel_hi:[1,0]
	v_pk_add_f32 v[66:67], v[66:67], 1.0 op_sel_hi:[1,0]
	v_pk_add_f32 v[68:69], v[68:69], 1.0 op_sel_hi:[1,0]
	v_pk_add_f32 v[70:71], v[70:71], 1.0 op_sel_hi:[1,0]
	v_pk_add_f32 v[72:73], v[72:73], 1.0 op_sel_hi:[1,0]
	v_pk_add_f32 v[74:75], v[74:75], 1.0 op_sel_hi:[1,0]
	s_waitcnt vmcnt(16)
; DI unsigned pk2(float lo, float hi) { return f2bf(lo) | (f2bf(hi) << 16); }
; DI void norm_phase(const Args& A, int wave_s, int l, int which, int rows) {
;     ...
;             float ss = 0.f;
; #pragma unroll
;             for (int j = 0; j < 4; ++j) ss += (xv[rr][j].x * xv[rr][j].x + xv[rr][j].y * xv[rr][j].y) + (xv[rr][j].z * xv[rr][j].z + xv[rr][j].w * xv[rr][j].w);
;             ss = wave_sum(C.lane, ss);
;             const float rs = rsqrtf(ss * (1.f / 1024.f) + EPS);
; #pragma unroll
;             for (int j = 0; j < 4; ++j) { const int col = 4 * (C.lane + 64 * j);
;                 const f32x4 y = xv[rr][j] * rs * g[j] * (sc[j] + 1.f) + sh[j];
;                 v2u o; o.x = pk2(y.x, y.y); o.y = pk2(y.z, y.w);
;                 *(v2u*)(C.H + (size_t)m * 1024 + col) = o; }
	v_mul_f32_e32 v10, v96, v96
	v_fmac_f32_e32 v10, v97, v97
	v_fmac_f32_e32 v10, v98, v98
	v_fmac_f32_e32 v10, v99, v99
	v_fmac_f32_e32 v10, v100, v100
	v_fmac_f32_e32 v10, v101, v101
	v_fmac_f32_e32 v10, v102, v102
	v_fmac_f32_e32 v10, v103, v103
	v_fmac_f32_e32 v10, v104, v104
	v_fmac_f32_e32 v10, v105, v105
	v_fmac_f32_e32 v10, v106, v106
	v_fmac_f32_e32 v10, v107, v107
	v_fmac_f32_e32 v10, v108, v108
	v_fmac_f32_e32 v10, v109, v109
	v_fmac_f32_e32 v10, v110, v110
	v_fmac_f32_e32 v10, v111, v111
	v_mul_f32_e32 v11, v112, v112
	v_fmac_f32_e32 v11, v113, v113
	v_fmac_f32_e32 v11, v114, v114
	v_fmac_f32_e32 v11, v115, v115
	v_fmac_f32_e32 v11, v116, v116
	v_fmac_f32_e32 v11, v117, v117
	v_fmac_f32_e32 v11, v118, v118
	v_fmac_f32_e32 v11, v119, v119
	v_fmac_f32_e32 v11, v120, v120
	v_fmac_f32_e32 v11, v121, v121
	v_fmac_f32_e32 v11, v122, v122
	v_fmac_f32_e32 v11, v123, v123
	v_fmac_f32_e32 v11, v124, v124
	v_fmac_f32_e32 v11, v125, v125
	v_fmac_f32_e32 v11, v126, v126
	v_fmac_f32_e32 v11, v127, v127
	v_mul_f32_e32 v12, v128, v128
	v_fmac_f32_e32 v12, v129, v129
	v_fmac_f32_e32 v12, v130, v130
	v_fmac_f32_e32 v12, v131, v131
	v_fmac_f32_e32 v12, v132, v132
	v_fmac_f32_e32 v12, v133, v133
	v_fmac_f32_e32 v12, v134, v134
	v_fmac_f32_e32 v12, v135, v135
	v_fmac_f32_e32 v12, v136, v136
	v_fmac_f32_e32 v12, v137, v137
	v_fmac_f32_e32 v12, v138, v138
	v_fmac_f32_e32 v12, v139, v139
	v_fmac_f32_e32 v12, v140, v140
	v_fmac_f32_e32 v12, v141, v141
	v_fmac_f32_e32 v12, v142, v142
	v_fmac_f32_e32 v12, v143, v143
	v_mul_f32_e32 v13, v144, v144
	v_fmac_f32_e32 v13, v145, v145
	v_fmac_f32_e32 v13, v146, v146
	v_fmac_f32_e32 v13, v147, v147
	v_fmac_f32_e32 v13, v148, v148
	v_fmac_f32_e32 v13, v149, v149
	v_fmac_f32_e32 v13, v150, v150
	v_fmac_f32_e32 v13, v151, v151
	v_fmac_f32_e32 v13, v152, v152
	v_fmac_f32_e32 v13, v153, v153
	v_fmac_f32_e32 v13, v154, v154
	v_fmac_f32_e32 v13, v155, v155
	v_fmac_f32_e32 v13, v156, v156
	v_fmac_f32_e32 v13, v157, v157
	v_fmac_f32_e32 v13, v158, v158
	v_fmac_f32_e32 v13, v159, v159
	ds_bpermute_b32 v14, v4, v10
	ds_bpermute_b32 v15, v4, v11
	ds_bpermute_b32 v16, v4, v12
	ds_bpermute_b32 v17, v4, v13
	s_waitcnt lgkmcnt(0)
	v_add_f32_e32 v10, v10, v14
	v_add_f32_e32 v11, v11, v15
	v_add_f32_e32 v12, v12, v16
	v_add_f32_e32 v13, v13, v17
	ds_bpermute_b32 v14, v5, v10
	ds_bpermute_b32 v15, v5, v11
	ds_bpermute_b32 v16, v5, v12
	ds_bpermute_b32 v17, v5, v13
	s_waitcnt lgkmcnt(0)
	v_add_f32_e32 v10, v10, v14
	v_add_f32_e32 v11, v11, v15
	v_add_f32_e32 v12, v12, v16
	v_add_f32_e32 v13, v13, v17
	ds_bpermute_b32 v14, v6, v10
	ds_bpermute_b32 v15, v6, v11
	ds_bpermute_b32 v16, v6, v12
	ds_bpermute_b32 v17, v6, v13
	s_waitcnt lgkmcnt(0)
	v_add_f32_e32 v10, v10, v14
	v_add_f32_e32 v11, v11, v15
	v_add_f32_e32 v12, v12, v16
	v_add_f32_e32 v13, v13, v17
	ds_bpermute_b32 v14, v7, v10
	ds_bpermute_b32 v15, v7, v11
	ds_bpermute_b32 v16, v7, v12
	ds_bpermute_b32 v17, v7, v13
	s_waitcnt lgkmcnt(0)
	v_add_f32_e32 v10, v10, v14
	v_add_f32_e32 v11, v11, v15
	v_add_f32_e32 v12, v12, v16
	v_add_f32_e32 v13, v13, v17
	ds_bpermute_b32 v14, v8, v10
	ds_bpermute_b32 v15, v8, v11
	ds_bpermute_b32 v16, v8, v12
	ds_bpermute_b32 v17, v8, v13
	s_waitcnt lgkmcnt(0)
	v_add_f32_e32 v10, v10, v14
	v_add_f32_e32 v11, v11, v15
	v_add_f32_e32 v12, v12, v16
	v_add_f32_e32 v13, v13, v17
	ds_bpermute_b32 v14, v9, v10
	ds_bpermute_b32 v15, v9, v11
	ds_bpermute_b32 v16, v9, v12
	ds_bpermute_b32 v17, v9, v13
	s_waitcnt lgkmcnt(0)
	v_add_f32_e32 v10, v10, v14
	v_add_f32_e32 v11, v11, v15
	v_add_f32_e32 v12, v12, v16
	v_add_f32_e32 v13, v13, v17
	v_fma_f32 v10, v10, s32, v60
	v_fma_f32 v11, v11, s32, v60
	v_fma_f32 v12, v12, s32, v60
	v_fma_f32 v13, v13, s32, v60
	v_rsq_f32_e32 v18, v10
	v_rsq_f32_e32 v20, v11
	v_rsq_f32_e32 v22, v12
	v_rsq_f32_e32 v62, v13
	s_nop 0
	v_pk_mul_f32 v[96:97], v[96:97], v[18:19] op_sel_hi:[1,0]
	v_pk_mul_f32 v[98:99], v[98:99], v[18:19] op_sel_hi:[1,0]
	v_pk_mul_f32 v[100:101], v[100:101], v[18:19] op_sel_hi:[1,0]
	v_pk_mul_f32 v[102:103], v[102:103], v[18:19] op_sel_hi:[1,0]
	v_pk_mul_f32 v[104:105], v[104:105], v[18:19] op_sel_hi:[1,0]
	v_pk_mul_f32 v[106:107], v[106:107], v[18:19] op_sel_hi:[1,0]
	v_pk_mul_f32 v[108:109], v[108:109], v[18:19] op_sel_hi:[1,0]
	v_pk_mul_f32 v[110:111], v[110:111], v[18:19] op_sel_hi:[1,0]
	v_pk_mul_f32 v[96:97], v[24:25], v[96:97]
	v_pk_mul_f32 v[98:99], v[26:27], v[98:99]
	v_pk_mul_f32 v[100:101], v[28:29], v[100:101]
	v_pk_mul_f32 v[102:103], v[30:31], v[102:103]
	v_pk_mul_f32 v[104:105], v[32:33], v[104:105]
	v_pk_mul_f32 v[106:107], v[34:35], v[106:107]
	v_pk_mul_f32 v[108:109], v[36:37], v[108:109]
	v_pk_mul_f32 v[110:111], v[38:39], v[110:111]
	v_pk_fma_f32 v[96:97], v[40:41], v[96:97], v[80:81]
	v_pk_fma_f32 v[98:99], v[42:43], v[98:99], v[82:83]
	v_pk_fma_f32 v[100:101], v[64:65], v[100:101], v[84:85]
	v_pk_fma_f32 v[102:103], v[66:67], v[102:103], v[86:87]
	v_pk_fma_f32 v[104:105], v[68:69], v[104:105], v[88:89]
	v_pk_fma_f32 v[106:107], v[70:71], v[106:107], v[90:91]
	v_pk_fma_f32 v[108:109], v[72:73], v[108:109], v[92:93]
	v_pk_fma_f32 v[110:111], v[74:75], v[110:111], v[94:95]
	v_cvt_pk_bf16_f32 v96, v96, v97
	v_cvt_pk_bf16_f32 v97, v98, v99
	v_cvt_pk_bf16_f32 v100, v100, v101
	v_cvt_pk_bf16_f32 v101, v102, v103
	v_cvt_pk_bf16_f32 v104, v104, v105
	v_cvt_pk_bf16_f32 v105, v106, v107
	v_cvt_pk_bf16_f32 v108, v108, v109
	v_cvt_pk_bf16_f32 v109, v110, v111
	global_store_dwordx2 v2, v[96:97], s[10:11]
	global_store_dwordx2 v2, v[100:101], s[10:11] offset:512
	global_store_dwordx2 v2, v[104:105], s[10:11] offset:1024
	global_store_dwordx2 v2, v[108:109], s[10:11] offset:1536
	s_add_u32 s10, s10, 0x800
; DI unsigned pk2(float lo, float hi) { return f2bf(lo) | (f2bf(hi) << 16); }
; DI void norm_phase(const Args& A, int wave_s, int l, int which, int rows) {
;     ...
;             modp[rr] = C.SM + SM_MOD + (l * 5 + v) * 6144 + (which == 1 ? 0 : 3072);
; #pragma unroll
;             for (int j = 0; j < 4; ++j) xv[rr][j] = ((const f32x4*)xr)[C.lane + 64 * j];
;     ...
;             const float rs = rsqrtf(ss * (1.f / 1024.f) + EPS);
; #pragma unroll
;             for (int j = 0; j < 4; ++j) { const int col = 4 * (C.lane + 64 * j);
;                 const f32x4 y = xv[rr][j] * rs * g[j] * (sc[j] + 1.f) + sh[j];
;                 v2u o; o.x = pk2(y.x, y.y); o.y = pk2(y.z, y.w);
;                 *(v2u*)(C.H + (size_t)m * 1024 + col) = o; }
	s_addc_u32 s11, s11, 0
	v_pk_mul_f32 v[112:113], v[112:113], v[20:21] op_sel_hi:[1,0]
	v_pk_mul_f32 v[114:115], v[114:115], v[20:21] op_sel_hi:[1,0]
	v_pk_mul_f32 v[116:117], v[116:117], v[20:21] op_sel_hi:[1,0]
	v_pk_mul_f32 v[118:119], v[118:119], v[20:21] op_sel_hi:[1,0]
	v_pk_mul_f32 v[120:121], v[120:121], v[20:21] op_sel_hi:[1,0]
	v_pk_mul_f32 v[122:123], v[122:123], v[20:21] op_sel_hi:[1,0]
	v_pk_mul_f32 v[124:125], v[124:125], v[20:21] op_sel_hi:[1,0]
	v_pk_mul_f32 v[126:127], v[126:127], v[20:21] op_sel_hi:[1,0]
	v_pk_mul_f32 v[112:113], v[24:25], v[112:113]
	v_pk_mul_f32 v[114:115], v[26:27], v[114:115]
	v_pk_mul_f32 v[116:117], v[28:29], v[116:117]
	v_pk_mul_f32 v[118:119], v[30:31], v[118:119]
	v_pk_mul_f32 v[120:121], v[32:33], v[120:121]
	v_pk_mul_f32 v[122:123], v[34:35], v[122:123]
	v_pk_mul_f32 v[124:125], v[36:37], v[124:125]
	v_pk_mul_f32 v[126:127], v[38:39], v[126:127]
	v_pk_fma_f32 v[112:113], v[40:41], v[112:113], v[80:81]
	v_pk_fma_f32 v[114:115], v[42:43], v[114:115], v[82:83]
	v_pk_fma_f32 v[116:117], v[64:65], v[116:117], v[84:85]
	v_pk_fma_f32 v[118:119], v[66:67], v[118:119], v[86:87]
	v_pk_fma_f32 v[120:121], v[68:69], v[120:121], v[88:89]
	v_pk_fma_f32 v[122:123], v[70:71], v[122:123], v[90:91]
	v_pk_fma_f32 v[124:125], v[72:73], v[124:125], v[92:93]
	v_pk_fma_f32 v[126:127], v[74:75], v[126:127], v[94:95]
	v_cvt_pk_bf16_f32 v112, v112, v113
	v_cvt_pk_bf16_f32 v113, v114, v115
	v_cvt_pk_bf16_f32 v116, v116, v117
	v_cvt_pk_bf16_f32 v117, v118, v119
	v_cvt_pk_bf16_f32 v120, v120, v121
	v_cvt_pk_bf16_f32 v121, v122, v123
	v_cvt_pk_bf16_f32 v124, v124, v125
	v_cvt_pk_bf16_f32 v125, v126, v127
	global_store_dwordx2 v2, v[112:113], s[10:11]
	global_store_dwordx2 v2, v[116:117], s[10:11] offset:512
	global_store_dwordx2 v2, v[120:121], s[10:11] offset:1024
	global_store_dwordx2 v2, v[124:125], s[10:11] offset:1536
	s_add_u32 s10, s10, 0x800
	s_addc_u32 s11, s11, 0
	v_pk_mul_f32 v[128:129], v[128:129], v[22:23] op_sel_hi:[1,0]
	v_pk_mul_f32 v[130:131], v[130:131], v[22:23] op_sel_hi:[1,0]
	v_pk_mul_f32 v[132:133], v[132:133], v[22:23] op_sel_hi:[1,0]
	v_pk_mul_f32 v[134:135], v[134:135], v[22:23] op_sel_hi:[1,0]
	v_pk_mul_f32 v[136:137], v[136:137], v[22:23] op_sel_hi:[1,0]
	v_pk_mul_f32 v[138:139], v[138:139], v[22:23] op_sel_hi:[1,0]
	v_pk_mul_f32 v[140:141], v[140:141], v[22:23] op_sel_hi:[1,0]
	v_pk_mul_f32 v[142:143], v[142:143], v[22:23] op_sel_hi:[1,0]
	v_pk_mul_f32 v[128:129], v[24:25], v[128:129]
	v_pk_mul_f32 v[130:131], v[26:27], v[130:131]
	v_pk_mul_f32 v[132:133], v[28:29], v[132:133]
	v_pk_mul_f32 v[134:135], v[30:31], v[134:135]
	v_pk_mul_f32 v[136:137], v[32:33], v[136:137]
	v_pk_mul_f32 v[138:139], v[34:35], v[138:139]
	v_pk_mul_f32 v[140:141], v[36:37], v[140:141]
	v_pk_mul_f32 v[142:143], v[38:39], v[142:143]
	v_pk_fma_f32 v[128:129], v[40:41], v[128:129], v[80:81]
	v_pk_fma_f32 v[130:131], v[42:43], v[130:131], v[82:83]
	v_pk_fma_f32 v[132:133], v[64:65], v[132:133], v[84:85]
	v_pk_fma_f32 v[134:135], v[66:67], v[134:135], v[86:87]
	v_pk_fma_f32 v[136:137], v[68:69], v[136:137], v[88:89]
	v_pk_fma_f32 v[138:139], v[70:71], v[138:139], v[90:91]
	v_pk_fma_f32 v[140:141], v[72:73], v[140:141], v[92:93]
	v_pk_fma_f32 v[142:143], v[74:75], v[142:143], v[94:95]
	v_cvt_pk_bf16_f32 v128, v128, v129
	v_cvt_pk_bf16_f32 v129, v130, v131
	v_cvt_pk_bf16_f32 v132, v132, v133
	v_cvt_pk_bf16_f32 v133, v134, v135
	v_cvt_pk_bf16_f32 v136, v136, v137
	v_cvt_pk_bf16_f32 v137, v138, v139
	v_cvt_pk_bf16_f32 v140, v140, v141
	v_cvt_pk_bf16_f32 v141, v142, v143
	global_store_dwordx2 v2, v[128:129], s[10:11]
	global_store_dwordx2 v2, v[132:133], s[10:11] offset:512
	global_store_dwordx2 v2, v[136:137], s[10:11] offset:1024
	global_store_dwordx2 v2, v[140:141], s[10:11] offset:1536
	s_add_u32 s10, s10, 0x800
	s_addc_u32 s11, s11, 0
	v_pk_mul_f32 v[144:145], v[144:145], v[62:63] op_sel_hi:[1,0]
	v_pk_mul_f32 v[146:147], v[146:147], v[62:63] op_sel_hi:[1,0]
	v_pk_mul_f32 v[148:149], v[148:149], v[62:63] op_sel_hi:[1,0]
	v_pk_mul_f32 v[150:151], v[150:151], v[62:63] op_sel_hi:[1,0]
	v_pk_mul_f32 v[152:153], v[152:153], v[62:63] op_sel_hi:[1,0]
	v_pk_mul_f32 v[154:155], v[154:155], v[62:63] op_sel_hi:[1,0]
	v_pk_mul_f32 v[156:157], v[156:157], v[62:63] op_sel_hi:[1,0]
	v_pk_mul_f32 v[158:159], v[158:159], v[62:63] op_sel_hi:[1,0]
	v_pk_mul_f32 v[144:145], v[24:25], v[144:145]
	v_pk_mul_f32 v[146:147], v[26:27], v[146:147]
	v_pk_mul_f32 v[148:149], v[28:29], v[148:149]
	v_pk_mul_f32 v[150:151], v[30:31], v[150:151]
	v_pk_mul_f32 v[152:153], v[32:33], v[152:153]
	v_pk_mul_f32 v[154:155], v[34:35], v[154:155]
	v_pk_mul_f32 v[156:157], v[36:37], v[156:157]
	v_pk_mul_f32 v[158:159], v[38:39], v[158:159]
	v_pk_fma_f32 v[144:145], v[40:41], v[144:145], v[80:81]
	v_pk_fma_f32 v[146:147], v[42:43], v[146:147], v[82:83]
	v_pk_fma_f32 v[148:149], v[64:65], v[148:149], v[84:85]
	v_pk_fma_f32 v[150:151], v[66:67], v[150:151], v[86:87]
	v_pk_fma_f32 v[152:153], v[68:69], v[152:153], v[88:89]
	v_pk_fma_f32 v[154:155], v[70:71], v[154:155], v[90:91]
	v_pk_fma_f32 v[156:157], v[72:73], v[156:157], v[92:93]
	v_pk_fma_f32 v[158:159], v[74:75], v[158:159], v[94:95]
	v_cvt_pk_bf16_f32 v144, v144, v145
	v_cvt_pk_bf16_f32 v145, v146, v147
	v_cvt_pk_bf16_f32 v148, v148, v149
	v_cvt_pk_bf16_f32 v149, v150, v151
	v_cvt_pk_bf16_f32 v152, v152, v153
	v_cvt_pk_bf16_f32 v153, v154, v155
	v_cvt_pk_bf16_f32 v156, v156, v157
	v_cvt_pk_bf16_f32 v157, v158, v159
	global_store_dwordx2 v2, v[144:145], s[10:11]
	global_store_dwordx2 v2, v[148:149], s[10:11] offset:512
	global_store_dwordx2 v2, v[152:153], s[10:11] offset:1024
	global_store_dwordx2 v2, v[156:157], s[10:11] offset:1536
	s_add_u32 s10, s10, 0x800
	s_addc_u32 s11, s11, 0
	global_load_dwordx4 v[96:99], v1, s[8:9] nt
	global_load_dwordx4 v[100:103], v1, s[8:9] offset:1024 nt
	global_load_dwordx4 v[104:107], v1, s[8:9] offset:2048 nt
	global_load_dwordx4 v[108:111], v1, s[8:9] offset:3072 nt
	s_add_u32 s8, s8, 0x1000
	s_addc_u32 s9, s9, 0
	global_load_dwordx4 v[112:115], v1, s[8:9] nt
	global_load_dwordx4 v[116:119], v1, s[8:9] offset:1024 nt
	global_load_dwordx4 v[120:123], v1, s[8:9] offset:2048 nt
	global_load_dwordx4 v[124:127], v1, s[8:9] offset:3072 nt
	s_add_u32 s8, s8, 0x1000
	s_addc_u32 s9, s9, 0
	global_load_dwordx4 v[128:131], v1, s[8:9] nt
	global_load_dwordx4 v[132:135], v1, s[8:9] offset:1024 nt
	global_load_dwordx4 v[136:139], v1, s[8:9] offset:2048 nt
	global_load_dwordx4 v[140:143], v1, s[8:9] offset:3072 nt
	s_add_u32 s8, s8, 0x1000
	s_addc_u32 s9, s9, 0
	global_load_dwordx4 v[144:147], v1, s[8:9] nt
	global_load_dwordx4 v[148:151], v1, s[8:9] offset:1024 nt
	global_load_dwordx4 v[152:155], v1, s[8:9] offset:2048 nt
	global_load_dwordx4 v[156:159], v1, s[8:9] offset:3072 nt
	s_add_u32 s8, s8, 0x1000
	s_addc_u32 s9, s9, 0
	s_waitcnt vmcnt(32)
; DI unsigned pk2(float lo, float hi) { return f2bf(lo) | (f2bf(hi) << 16); }
; DI void norm_phase(const Args& A, int wave_s, int l, int which, int rows) {
;     ...
;             float ss = 0.f;
; #pragma unroll
;             for (int j = 0; j < 4; ++j) ss += (xv[rr][j].x * xv[rr][j].x + xv[rr][j].y * xv[rr][j].y) + (xv[rr][j].z * xv[rr][j].z + xv[rr][j].w * xv[rr][j].w);
;             ss = wave_sum(C.lane, ss);
;             const float rs = rsqrtf(ss * (1.f / 1024.f) + EPS);
; #pragma unroll
;             for (int j = 0; j < 4; ++j) { const int col = 4 * (C.lane + 64 * j);
;                 const f32x4 y = xv[rr][j] * rs * g[j] * (sc[j] + 1.f) + sh[j];
;                 v2u o; o.x = pk2(y.x, y.y); o.y = pk2(y.z, y.w);
;                 *(v2u*)(C.H + (size_t)m * 1024 + col) = o; }
	v_mul_f32_e32 v10, v164, v164
	v_fmac_f32_e32 v10, v165, v165
	v_fmac_f32_e32 v10, v166, v166
	v_fmac_f32_e32 v10, v167, v167
	v_fmac_f32_e32 v10, v168, v168
	v_fmac_f32_e32 v10, v169, v169
	v_fmac_f32_e32 v10, v170, v170
	v_fmac_f32_e32 v10, v171, v171
	v_fmac_f32_e32 v10, v172, v172
	v_fmac_f32_e32 v10, v173, v173
	v_fmac_f32_e32 v10, v174, v174
	v_fmac_f32_e32 v10, v175, v175
	v_fmac_f32_e32 v10, v176, v176
	v_fmac_f32_e32 v10, v177, v177
	v_fmac_f32_e32 v10, v178, v178
	v_fmac_f32_e32 v10, v179, v179
	v_mul_f32_e32 v11, v180, v180
	v_fmac_f32_e32 v11, v181, v181
	v_fmac_f32_e32 v11, v182, v182
	v_fmac_f32_e32 v11, v183, v183
	v_fmac_f32_e32 v11, v184, v184
	v_fmac_f32_e32 v11, v185, v185
	v_fmac_f32_e32 v11, v186, v186
	v_fmac_f32_e32 v11, v187, v187
	v_fmac_f32_e32 v11, v188, v188
	v_fmac_f32_e32 v11, v189, v189
	v_fmac_f32_e32 v11, v190, v190
	v_fmac_f32_e32 v11, v191, v191
	v_fmac_f32_e32 v11, v192, v192
	v_fmac_f32_e32 v11, v193, v193
	v_fmac_f32_e32 v11, v194, v194
	v_fmac_f32_e32 v11, v195, v195
	v_mul_f32_e32 v12, v196, v196
	v_fmac_f32_e32 v12, v197, v197
	v_fmac_f32_e32 v12, v198, v198
	v_fmac_f32_e32 v12, v199, v199
	v_fmac_f32_e32 v12, v200, v200
	v_fmac_f32_e32 v12, v201, v201
	v_fmac_f32_e32 v12, v202, v202
	v_fmac_f32_e32 v12, v203, v203
	v_fmac_f32_e32 v12, v204, v204
	v_fmac_f32_e32 v12, v205, v205
	v_fmac_f32_e32 v12, v206, v206
	v_fmac_f32_e32 v12, v207, v207
	v_fmac_f32_e32 v12, v208, v208
	v_fmac_f32_e32 v12, v209, v209
	v_fmac_f32_e32 v12, v210, v210
	v_fmac_f32_e32 v12, v211, v211
	v_mul_f32_e32 v13, v212, v212
	v_fmac_f32_e32 v13, v213, v213
	v_fmac_f32_e32 v13, v214, v214
	v_fmac_f32_e32 v13, v215, v215
	v_fmac_f32_e32 v13, v216, v216
	v_fmac_f32_e32 v13, v217, v217
	v_fmac_f32_e32 v13, v218, v218
	v_fmac_f32_e32 v13, v219, v219
	v_fmac_f32_e32 v13, v220, v220
	v_fmac_f32_e32 v13, v221, v221
	v_fmac_f32_e32 v13, v222, v222
	v_fmac_f32_e32 v13, v223, v223
	v_fmac_f32_e32 v13, v224, v224
	v_fmac_f32_e32 v13, v225, v225
	v_fmac_f32_e32 v13, v226, v226
	v_fmac_f32_e32 v13, v227, v227
	ds_bpermute_b32 v14, v4, v10
	ds_bpermute_b32 v15, v4, v11
	ds_bpermute_b32 v16, v4, v12
	ds_bpermute_b32 v17, v4, v13
	s_waitcnt lgkmcnt(0)
	v_add_f32_e32 v10, v10, v14
	v_add_f32_e32 v11, v11, v15
	v_add_f32_e32 v12, v12, v16
	v_add_f32_e32 v13, v13, v17
	ds_bpermute_b32 v14, v5, v10
	ds_bpermute_b32 v15, v5, v11
	ds_bpermute_b32 v16, v5, v12
	ds_bpermute_b32 v17, v5, v13
	s_waitcnt lgkmcnt(0)
	v_add_f32_e32 v10, v10, v14
	v_add_f32_e32 v11, v11, v15
	v_add_f32_e32 v12, v12, v16
	v_add_f32_e32 v13, v13, v17
	ds_bpermute_b32 v14, v6, v10
	ds_bpermute_b32 v15, v6, v11
	ds_bpermute_b32 v16, v6, v12
	ds_bpermute_b32 v17, v6, v13
	s_waitcnt lgkmcnt(0)
	v_add_f32_e32 v10, v10, v14
	v_add_f32_e32 v11, v11, v15
	v_add_f32_e32 v12, v12, v16
	v_add_f32_e32 v13, v13, v17
	ds_bpermute_b32 v14, v7, v10
	ds_bpermute_b32 v15, v7, v11
	ds_bpermute_b32 v16, v7, v12
	ds_bpermute_b32 v17, v7, v13
	s_waitcnt lgkmcnt(0)
	v_add_f32_e32 v10, v10, v14
	v_add_f32_e32 v11, v11, v15
	v_add_f32_e32 v12, v12, v16
	v_add_f32_e32 v13, v13, v17
	ds_bpermute_b32 v14, v8, v10
	ds_bpermute_b32 v15, v8, v11
	ds_bpermute_b32 v16, v8, v12
	ds_bpermute_b32 v17, v8, v13
	s_waitcnt lgkmcnt(0)
	v_add_f32_e32 v10, v10, v14
	v_add_f32_e32 v11, v11, v15
	v_add_f32_e32 v12, v12, v16
	v_add_f32_e32 v13, v13, v17
	ds_bpermute_b32 v14, v9, v10
	ds_bpermute_b32 v15, v9, v11
	ds_bpermute_b32 v16, v9, v12
	ds_bpermute_b32 v17, v9, v13
	s_waitcnt lgkmcnt(0)
	v_add_f32_e32 v10, v10, v14
	v_add_f32_e32 v11, v11, v15
	v_add_f32_e32 v12, v12, v16
	v_add_f32_e32 v13, v13, v17
	v_fma_f32 v10, v10, s32, v60
	v_fma_f32 v11, v11, s32, v60
	v_fma_f32 v12, v12, s32, v60
	v_fma_f32 v13, v13, s32, v60
	v_rsq_f32_e32 v18, v10
	v_rsq_f32_e32 v20, v11
	v_rsq_f32_e32 v22, v12
	v_rsq_f32_e32 v62, v13
	s_nop 0
	v_pk_mul_f32 v[164:165], v[164:165], v[18:19] op_sel_hi:[1,0]
	v_pk_mul_f32 v[166:167], v[166:167], v[18:19] op_sel_hi:[1,0]
	v_pk_mul_f32 v[168:169], v[168:169], v[18:19] op_sel_hi:[1,0]
	v_pk_mul_f32 v[170:171], v[170:171], v[18:19] op_sel_hi:[1,0]
	v_pk_mul_f32 v[172:173], v[172:173], v[18:19] op_sel_hi:[1,0]
	v_pk_mul_f32 v[174:175], v[174:175], v[18:19] op_sel_hi:[1,0]
	v_pk_mul_f32 v[176:177], v[176:177], v[18:19] op_sel_hi:[1,0]
	v_pk_mul_f32 v[178:179], v[178:179], v[18:19] op_sel_hi:[1,0]
	v_pk_mul_f32 v[164:165], v[24:25], v[164:165]
	v_pk_mul_f32 v[166:167], v[26:27], v[166:167]
	v_pk_mul_f32 v[168:169], v[28:29], v[168:169]
	v_pk_mul_f32 v[170:171], v[30:31], v[170:171]
	v_pk_mul_f32 v[172:173], v[32:33], v[172:173]
	v_pk_mul_f32 v[174:175], v[34:35], v[174:175]
	v_pk_mul_f32 v[176:177], v[36:37], v[176:177]
	v_pk_mul_f32 v[178:179], v[38:39], v[178:179]
	v_pk_fma_f32 v[164:165], v[40:41], v[164:165], v[80:81]
	v_pk_fma_f32 v[166:167], v[42:43], v[166:167], v[82:83]
	v_pk_fma_f32 v[168:169], v[64:65], v[168:169], v[84:85]
	v_pk_fma_f32 v[170:171], v[66:67], v[170:171], v[86:87]
	v_pk_fma_f32 v[172:173], v[68:69], v[172:173], v[88:89]
	v_pk_fma_f32 v[174:175], v[70:71], v[174:175], v[90:91]
	v_pk_fma_f32 v[176:177], v[72:73], v[176:177], v[92:93]
	v_pk_fma_f32 v[178:179], v[74:75], v[178:179], v[94:95]
	v_cvt_pk_bf16_f32 v164, v164, v165
	v_cvt_pk_bf16_f32 v165, v166, v167
	v_cvt_pk_bf16_f32 v168, v168, v169
	v_cvt_pk_bf16_f32 v169, v170, v171
	v_cvt_pk_bf16_f32 v172, v172, v173
	v_cvt_pk_bf16_f32 v173, v174, v175
	v_cvt_pk_bf16_f32 v176, v176, v177
	v_cvt_pk_bf16_f32 v177, v178, v179
	global_store_dwordx2 v2, v[164:165], s[10:11]
	global_store_dwordx2 v2, v[168:169], s[10:11] offset:512
	global_store_dwordx2 v2, v[172:173], s[10:11] offset:1024
	global_store_dwordx2 v2, v[176:177], s[10:11] offset:1536
; DI unsigned pk2(float lo, float hi) { return f2bf(lo) | (f2bf(hi) << 16); }
; DI void norm_phase(const Args& A, int wave_s, int l, int which, int rows) {
;     ...
;             modp[rr] = C.SM + SM_MOD + (l * 5 + v) * 6144 + (which == 1 ? 0 : 3072);
; #pragma unroll
;             for (int j = 0; j < 4; ++j) xv[rr][j] = ((const f32x4*)xr)[C.lane + 64 * j];
;     ...
;             const float rs = rsqrtf(ss * (1.f / 1024.f) + EPS);
; #pragma unroll
;             for (int j = 0; j < 4; ++j) { const int col = 4 * (C.lane + 64 * j);
;                 const f32x4 y = xv[rr][j] * rs * g[j] * (sc[j] + 1.f) + sh[j];
;                 v2u o; o.x = pk2(y.x, y.y); o.y = pk2(y.z, y.w);
;                 *(v2u*)(C.H + (size_t)m * 1024 + col) = o; }
	s_add_u32 s10, s10, 0x800
	s_addc_u32 s11, s11, 0
	v_pk_mul_f32 v[180:181], v[180:181], v[20:21] op_sel_hi:[1,0]
	v_pk_mul_f32 v[182:183], v[182:183], v[20:21] op_sel_hi:[1,0]
	v_pk_mul_f32 v[184:185], v[184:185], v[20:21] op_sel_hi:[1,0]
	v_pk_mul_f32 v[186:187], v[186:187], v[20:21] op_sel_hi:[1,0]
	v_pk_mul_f32 v[188:189], v[188:189], v[20:21] op_sel_hi:[1,0]
	v_pk_mul_f32 v[190:191], v[190:191], v[20:21] op_sel_hi:[1,0]
	v_pk_mul_f32 v[192:193], v[192:193], v[20:21] op_sel_hi:[1,0]
	v_pk_mul_f32 v[194:195], v[194:195], v[20:21] op_sel_hi:[1,0]
	v_pk_mul_f32 v[180:181], v[24:25], v[180:181]
	v_pk_mul_f32 v[182:183], v[26:27], v[182:183]
	v_pk_mul_f32 v[184:185], v[28:29], v[184:185]
	v_pk_mul_f32 v[186:187], v[30:31], v[186:187]
	v_pk_mul_f32 v[188:189], v[32:33], v[188:189]
	v_pk_mul_f32 v[190:191], v[34:35], v[190:191]
	v_pk_mul_f32 v[192:193], v[36:37], v[192:193]
	v_pk_mul_f32 v[194:195], v[38:39], v[194:195]
	v_pk_fma_f32 v[180:181], v[40:41], v[180:181], v[80:81]
	v_pk_fma_f32 v[182:183], v[42:43], v[182:183], v[82:83]
	v_pk_fma_f32 v[184:185], v[64:65], v[184:185], v[84:85]
	v_pk_fma_f32 v[186:187], v[66:67], v[186:187], v[86:87]
	v_pk_fma_f32 v[188:189], v[68:69], v[188:189], v[88:89]
	v_pk_fma_f32 v[190:191], v[70:71], v[190:191], v[90:91]
	v_pk_fma_f32 v[192:193], v[72:73], v[192:193], v[92:93]
	v_pk_fma_f32 v[194:195], v[74:75], v[194:195], v[94:95]
	v_cvt_pk_bf16_f32 v180, v180, v181
	v_cvt_pk_bf16_f32 v181, v182, v183
	v_cvt_pk_bf16_f32 v184, v184, v185
	v_cvt_pk_bf16_f32 v185, v186, v187
	v_cvt_pk_bf16_f32 v188, v188, v189
	v_cvt_pk_bf16_f32 v189, v190, v191
	v_cvt_pk_bf16_f32 v192, v192, v193
	v_cvt_pk_bf16_f32 v193, v194, v195
	global_store_dwordx2 v2, v[180:181], s[10:11]
	global_store_dwordx2 v2, v[184:185], s[10:11] offset:512
	global_store_dwordx2 v2, v[188:189], s[10:11] offset:1024
	global_store_dwordx2 v2, v[192:193], s[10:11] offset:1536
	s_add_u32 s10, s10, 0x800
	s_addc_u32 s11, s11, 0
	v_pk_mul_f32 v[196:197], v[196:197], v[22:23] op_sel_hi:[1,0]
	v_pk_mul_f32 v[198:199], v[198:199], v[22:23] op_sel_hi:[1,0]
	v_pk_mul_f32 v[200:201], v[200:201], v[22:23] op_sel_hi:[1,0]
	v_pk_mul_f32 v[202:203], v[202:203], v[22:23] op_sel_hi:[1,0]
	v_pk_mul_f32 v[204:205], v[204:205], v[22:23] op_sel_hi:[1,0]
	v_pk_mul_f32 v[206:207], v[206:207], v[22:23] op_sel_hi:[1,0]
	v_pk_mul_f32 v[208:209], v[208:209], v[22:23] op_sel_hi:[1,0]
	v_pk_mul_f32 v[210:211], v[210:211], v[22:23] op_sel_hi:[1,0]
	v_pk_mul_f32 v[196:197], v[24:25], v[196:197]
	v_pk_mul_f32 v[198:199], v[26:27], v[198:199]
	v_pk_mul_f32 v[200:201], v[28:29], v[200:201]
	v_pk_mul_f32 v[202:203], v[30:31], v[202:203]
	v_pk_mul_f32 v[204:205], v[32:33], v[204:205]
	v_pk_mul_f32 v[206:207], v[34:35], v[206:207]
	v_pk_mul_f32 v[208:209], v[36:37], v[208:209]
	v_pk_mul_f32 v[210:211], v[38:39], v[210:211]
	v_pk_fma_f32 v[196:197], v[40:41], v[196:197], v[80:81]
	v_pk_fma_f32 v[198:199], v[42:43], v[198:199], v[82:83]
	v_pk_fma_f32 v[200:201], v[64:65], v[200:201], v[84:85]
	v_pk_fma_f32 v[202:203], v[66:67], v[202:203], v[86:87]
	v_pk_fma_f32 v[204:205], v[68:69], v[204:205], v[88:89]
	v_pk_fma_f32 v[206:207], v[70:71], v[206:207], v[90:91]
	v_pk_fma_f32 v[208:209], v[72:73], v[208:209], v[92:93]
	v_pk_fma_f32 v[210:211], v[74:75], v[210:211], v[94:95]
	v_cvt_pk_bf16_f32 v196, v196, v197
	v_cvt_pk_bf16_f32 v197, v198, v199
	v_cvt_pk_bf16_f32 v200, v200, v201
	v_cvt_pk_bf16_f32 v201, v202, v203
	v_cvt_pk_bf16_f32 v204, v204, v205
	v_cvt_pk_bf16_f32 v205, v206, v207
	v_cvt_pk_bf16_f32 v208, v208, v209
	v_cvt_pk_bf16_f32 v209, v210, v211
	global_store_dwordx2 v2, v[196:197], s[10:11]
	global_store_dwordx2 v2, v[200:201], s[10:11] offset:512
	global_store_dwordx2 v2, v[204:205], s[10:11] offset:1024
	global_store_dwordx2 v2, v[208:209], s[10:11] offset:1536
	s_add_u32 s10, s10, 0x800
	s_addc_u32 s11, s11, 0
	v_pk_mul_f32 v[212:213], v[212:213], v[62:63] op_sel_hi:[1,0]
	v_pk_mul_f32 v[214:215], v[214:215], v[62:63] op_sel_hi:[1,0]
	v_pk_mul_f32 v[216:217], v[216:217], v[62:63] op_sel_hi:[1,0]
	v_pk_mul_f32 v[218:219], v[218:219], v[62:63] op_sel_hi:[1,0]
	v_pk_mul_f32 v[220:221], v[220:221], v[62:63] op_sel_hi:[1,0]
	v_pk_mul_f32 v[222:223], v[222:223], v[62:63] op_sel_hi:[1,0]
	v_pk_mul_f32 v[224:225], v[224:225], v[62:63] op_sel_hi:[1,0]
	v_pk_mul_f32 v[226:227], v[226:227], v[62:63] op_sel_hi:[1,0]
	v_pk_mul_f32 v[212:213], v[24:25], v[212:213]
	v_pk_mul_f32 v[214:215], v[26:27], v[214:215]
	v_pk_mul_f32 v[216:217], v[28:29], v[216:217]
	v_pk_mul_f32 v[218:219], v[30:31], v[218:219]
	v_pk_mul_f32 v[220:221], v[32:33], v[220:221]
	v_pk_mul_f32 v[222:223], v[34:35], v[222:223]
	v_pk_mul_f32 v[224:225], v[36:37], v[224:225]
	v_pk_mul_f32 v[226:227], v[38:39], v[226:227]
	v_pk_fma_f32 v[212:213], v[40:41], v[212:213], v[80:81]
	v_pk_fma_f32 v[214:215], v[42:43], v[214:215], v[82:83]
	v_pk_fma_f32 v[216:217], v[64:65], v[216:217], v[84:85]
	v_pk_fma_f32 v[218:219], v[66:67], v[218:219], v[86:87]
	v_pk_fma_f32 v[220:221], v[68:69], v[220:221], v[88:89]
	v_pk_fma_f32 v[222:223], v[70:71], v[222:223], v[90:91]
	v_pk_fma_f32 v[224:225], v[72:73], v[224:225], v[92:93]
	v_pk_fma_f32 v[226:227], v[74:75], v[226:227], v[94:95]
	v_cvt_pk_bf16_f32 v212, v212, v213
	v_cvt_pk_bf16_f32 v213, v214, v215
	v_cvt_pk_bf16_f32 v216, v216, v217
	v_cvt_pk_bf16_f32 v217, v218, v219
	v_cvt_pk_bf16_f32 v220, v220, v221
	v_cvt_pk_bf16_f32 v221, v222, v223
	v_cvt_pk_bf16_f32 v224, v224, v225
	v_cvt_pk_bf16_f32 v225, v226, v227
	global_store_dwordx2 v2, v[212:213], s[10:11]
	global_store_dwordx2 v2, v[216:217], s[10:11] offset:512
	global_store_dwordx2 v2, v[220:221], s[10:11] offset:1024
	global_store_dwordx2 v2, v[224:225], s[10:11] offset:1536
	s_add_u32 s10, s10, 0x800
	s_addc_u32 s11, s11, 0
	global_load_dwordx4 v[164:167], v1, s[8:9] nt
	global_load_dwordx4 v[168:171], v1, s[8:9] offset:1024 nt
	global_load_dwordx4 v[172:175], v1, s[8:9] offset:2048 nt
	global_load_dwordx4 v[176:179], v1, s[8:9] offset:3072 nt
	s_add_u32 s8, s8, 0x1000
	s_addc_u32 s9, s9, 0
	global_load_dwordx4 v[180:183], v1, s[8:9] nt
	global_load_dwordx4 v[184:187], v1, s[8:9] offset:1024 nt
	global_load_dwordx4 v[188:191], v1, s[8:9] offset:2048 nt
	global_load_dwordx4 v[192:195], v1, s[8:9] offset:3072 nt
	s_add_u32 s8, s8, 0x1000
	s_addc_u32 s9, s9, 0
	global_load_dwordx4 v[196:199], v1, s[8:9] nt
	global_load_dwordx4 v[200:203], v1, s[8:9] offset:1024 nt
	global_load_dwordx4 v[204:207], v1, s[8:9] offset:2048 nt
	global_load_dwordx4 v[208:211], v1, s[8:9] offset:3072 nt
	s_add_u32 s8, s8, 0x1000
	s_addc_u32 s9, s9, 0
	global_load_dwordx4 v[212:215], v1, s[8:9] nt
	global_load_dwordx4 v[216:219], v1, s[8:9] offset:1024 nt
	global_load_dwordx4 v[220:223], v1, s[8:9] offset:2048 nt
	global_load_dwordx4 v[224:227], v1, s[8:9] offset:3072 nt
	s_add_u32 s8, s8, 0x1000
	s_addc_u32 s9, s9, 0
	s_waitcnt vmcnt(32)
; DI unsigned pk2(float lo, float hi) { return f2bf(lo) | (f2bf(hi) << 16); }
; DI void norm_phase(const Args& A, int wave_s, int l, int which, int rows) {
;     ...
;             float ss = 0.f;
; #pragma unroll
;             for (int j = 0; j < 4; ++j) ss += (xv[rr][j].x * xv[rr][j].x + xv[rr][j].y * xv[rr][j].y) + (xv[rr][j].z * xv[rr][j].z + xv[rr][j].w * xv[rr][j].w);
;             ss = wave_sum(C.lane, ss);
;             const float rs = rsqrtf(ss * (1.f / 1024.f) + EPS);
; #pragma unroll
;             for (int j = 0; j < 4; ++j) { const int col = 4 * (C.lane + 64 * j);
;                 const f32x4 y = xv[rr][j] * rs * g[j] * (sc[j] + 1.f) + sh[j];
;                 v2u o; o.x = pk2(y.x, y.y); o.y = pk2(y.z, y.w);
;                 *(v2u*)(C.H + (size_t)m * 1024 + col) = o; }
	v_mul_f32_e32 v10, v96, v96
	v_fmac_f32_e32 v10, v97, v97
	v_fmac_f32_e32 v10, v98, v98
	v_fmac_f32_e32 v10, v99, v99
	v_fmac_f32_e32 v10, v100, v100
	v_fmac_f32_e32 v10, v101, v101
	v_fmac_f32_e32 v10, v102, v102
	v_fmac_f32_e32 v10, v103, v103
	v_fmac_f32_e32 v10, v104, v104
	v_fmac_f32_e32 v10, v105, v105
	v_fmac_f32_e32 v10, v106, v106
	v_fmac_f32_e32 v10, v107, v107
	v_fmac_f32_e32 v10, v108, v108
	v_fmac_f32_e32 v10, v109, v109
	v_fmac_f32_e32 v10, v110, v110
	v_fmac_f32_e32 v10, v111, v111
	v_mul_f32_e32 v11, v112, v112
	v_fmac_f32_e32 v11, v113, v113
	v_fmac_f32_e32 v11, v114, v114
	v_fmac_f32_e32 v11, v115, v115
	v_fmac_f32_e32 v11, v116, v116
	v_fmac_f32_e32 v11, v117, v117
	v_fmac_f32_e32 v11, v118, v118
	v_fmac_f32_e32 v11, v119, v119
	v_fmac_f32_e32 v11, v120, v120
	v_fmac_f32_e32 v11, v121, v121
	v_fmac_f32_e32 v11, v122, v122
	v_fmac_f32_e32 v11, v123, v123
	v_fmac_f32_e32 v11, v124, v124
	v_fmac_f32_e32 v11, v125, v125
	v_fmac_f32_e32 v11, v126, v126
	v_fmac_f32_e32 v11, v127, v127
	v_mul_f32_e32 v12, v128, v128
	v_fmac_f32_e32 v12, v129, v129
	v_fmac_f32_e32 v12, v130, v130
	v_fmac_f32_e32 v12, v131, v131
	v_fmac_f32_e32 v12, v132, v132
	v_fmac_f32_e32 v12, v133, v133
	v_fmac_f32_e32 v12, v134, v134
	v_fmac_f32_e32 v12, v135, v135
	v_fmac_f32_e32 v12, v136, v136
	v_fmac_f32_e32 v12, v137, v137
	v_fmac_f32_e32 v12, v138, v138
	v_fmac_f32_e32 v12, v139, v139
	v_fmac_f32_e32 v12, v140, v140
	v_fmac_f32_e32 v12, v141, v141
	v_fmac_f32_e32 v12, v142, v142
	v_fmac_f32_e32 v12, v143, v143
	v_mul_f32_e32 v13, v144, v144
	v_fmac_f32_e32 v13, v145, v145
	v_fmac_f32_e32 v13, v146, v146
	v_fmac_f32_e32 v13, v147, v147
	v_fmac_f32_e32 v13, v148, v148
	v_fmac_f32_e32 v13, v149, v149
	v_fmac_f32_e32 v13, v150, v150
	v_fmac_f32_e32 v13, v151, v151
	v_fmac_f32_e32 v13, v152, v152
	v_fmac_f32_e32 v13, v153, v153
	v_fmac_f32_e32 v13, v154, v154
	v_fmac_f32_e32 v13, v155, v155
	v_fmac_f32_e32 v13, v156, v156
	v_fmac_f32_e32 v13, v157, v157
	v_fmac_f32_e32 v13, v158, v158
	v_fmac_f32_e32 v13, v159, v159
	ds_bpermute_b32 v14, v4, v10
	ds_bpermute_b32 v15, v4, v11
	ds_bpermute_b32 v16, v4, v12
	ds_bpermute_b32 v17, v4, v13
	s_waitcnt lgkmcnt(0)
	v_add_f32_e32 v10, v10, v14
	v_add_f32_e32 v11, v11, v15
	v_add_f32_e32 v12, v12, v16
	v_add_f32_e32 v13, v13, v17
	ds_bpermute_b32 v14, v5, v10
	ds_bpermute_b32 v15, v5, v11
	ds_bpermute_b32 v16, v5, v12
	ds_bpermute_b32 v17, v5, v13
	s_waitcnt lgkmcnt(0)
	v_add_f32_e32 v10, v10, v14
	v_add_f32_e32 v11, v11, v15
	v_add_f32_e32 v12, v12, v16
	v_add_f32_e32 v13, v13, v17
	ds_bpermute_b32 v14, v6, v10
	ds_bpermute_b32 v15, v6, v11
	ds_bpermute_b32 v16, v6, v12
	ds_bpermute_b32 v17, v6, v13
	s_waitcnt lgkmcnt(0)
	v_add_f32_e32 v10, v10, v14
	v_add_f32_e32 v11, v11, v15
	v_add_f32_e32 v12, v12, v16
	v_add_f32_e32 v13, v13, v17
	ds_bpermute_b32 v14, v7, v10
	ds_bpermute_b32 v15, v7, v11
	ds_bpermute_b32 v16, v7, v12
	ds_bpermute_b32 v17, v7, v13
	s_waitcnt lgkmcnt(0)
	v_add_f32_e32 v10, v10, v14
	v_add_f32_e32 v11, v11, v15
	v_add_f32_e32 v12, v12, v16
	v_add_f32_e32 v13, v13, v17
	ds_bpermute_b32 v14, v8, v10
	ds_bpermute_b32 v15, v8, v11
	ds_bpermute_b32 v16, v8, v12
	ds_bpermute_b32 v17, v8, v13
	s_waitcnt lgkmcnt(0)
	v_add_f32_e32 v10, v10, v14
	v_add_f32_e32 v11, v11, v15
	v_add_f32_e32 v12, v12, v16
	v_add_f32_e32 v13, v13, v17
	ds_bpermute_b32 v14, v9, v10
	ds_bpermute_b32 v15, v9, v11
	ds_bpermute_b32 v16, v9, v12
	ds_bpermute_b32 v17, v9, v13
	s_waitcnt lgkmcnt(0)
	v_add_f32_e32 v10, v10, v14
	v_add_f32_e32 v11, v11, v15
	v_add_f32_e32 v12, v12, v16
	v_add_f32_e32 v13, v13, v17
	v_fma_f32 v10, v10, s32, v60
	v_fma_f32 v11, v11, s32, v60
	v_fma_f32 v12, v12, s32, v60
	v_fma_f32 v13, v13, s32, v60
	v_rsq_f32_e32 v18, v10
	v_rsq_f32_e32 v20, v11
	v_rsq_f32_e32 v22, v12
	v_rsq_f32_e32 v62, v13
	s_nop 0
	v_pk_mul_f32 v[96:97], v[96:97], v[18:19] op_sel_hi:[1,0]
	v_pk_mul_f32 v[98:99], v[98:99], v[18:19] op_sel_hi:[1,0]
	v_pk_mul_f32 v[100:101], v[100:101], v[18:19] op_sel_hi:[1,0]
	v_pk_mul_f32 v[102:103], v[102:103], v[18:19] op_sel_hi:[1,0]
	v_pk_mul_f32 v[104:105], v[104:105], v[18:19] op_sel_hi:[1,0]
	v_pk_mul_f32 v[106:107], v[106:107], v[18:19] op_sel_hi:[1,0]
	v_pk_mul_f32 v[108:109], v[108:109], v[18:19] op_sel_hi:[1,0]
	v_pk_mul_f32 v[110:111], v[110:111], v[18:19] op_sel_hi:[1,0]
	v_pk_mul_f32 v[96:97], v[24:25], v[96:97]
	v_pk_mul_f32 v[98:99], v[26:27], v[98:99]
	v_pk_mul_f32 v[100:101], v[28:29], v[100:101]
	v_pk_mul_f32 v[102:103], v[30:31], v[102:103]
	v_pk_mul_f32 v[104:105], v[32:33], v[104:105]
	v_pk_mul_f32 v[106:107], v[34:35], v[106:107]
	v_pk_mul_f32 v[108:109], v[36:37], v[108:109]
	v_pk_mul_f32 v[110:111], v[38:39], v[110:111]
	v_pk_fma_f32 v[96:97], v[40:41], v[96:97], v[80:81]
	v_pk_fma_f32 v[98:99], v[42:43], v[98:99], v[82:83]
	v_pk_fma_f32 v[100:101], v[64:65], v[100:101], v[84:85]
	v_pk_fma_f32 v[102:103], v[66:67], v[102:103], v[86:87]
	v_pk_fma_f32 v[104:105], v[68:69], v[104:105], v[88:89]
	v_pk_fma_f32 v[106:107], v[70:71], v[106:107], v[90:91]
	v_pk_fma_f32 v[108:109], v[72:73], v[108:109], v[92:93]
	v_pk_fma_f32 v[110:111], v[74:75], v[110:111], v[94:95]
	v_cvt_pk_bf16_f32 v96, v96, v97
	v_cvt_pk_bf16_f32 v97, v98, v99
	v_cvt_pk_bf16_f32 v100, v100, v101
	v_cvt_pk_bf16_f32 v101, v102, v103
	v_cvt_pk_bf16_f32 v104, v104, v105
	v_cvt_pk_bf16_f32 v105, v106, v107
	v_cvt_pk_bf16_f32 v108, v108, v109
	v_cvt_pk_bf16_f32 v109, v110, v111
	global_store_dwordx2 v2, v[96:97], s[10:11]
	global_store_dwordx2 v2, v[100:101], s[10:11] offset:512
	global_store_dwordx2 v2, v[104:105], s[10:11] offset:1024
	global_store_dwordx2 v2, v[108:109], s[10:11] offset:1536
	s_add_u32 s10, s10, 0x800
; DI void norm_phase(const Args& A, int wave_s, int l, int which, int rows) {
;     ...
;             if (m < NLAT) { xr = (from_in ? C.x : C.out) + (size_t)m * 1024; v = m >> 13; }
;             else { xr = (from_in ? C.ctx : C.XC) + (size_t)(m - NLAT) * 1024; v = 4; }
;             modp[rr] = C.SM + SM_MOD + (l * 5 + v) * 6144 + (which == 1 ? 0 : 3072);
; #pragma unroll
;             for (int j = 0; j < 4; ++j) xv[rr][j] = ((const f32x4*)xr)[C.lane + 64 * j];
;         }
; #pragma unroll
;         for (int rr = 0; rr < 2; ++rr) {
;             const int m = m0 + rr;
;             f32x4 sh[4], sc[4];
; #pragma unroll
;             for (int j = 0; j < 4; ++j) { const int col = 4 * (C.lane + 64 * j); sh[j] = *(const f32x4*)(modp[rr] + col); sc[j] = *(const f32x4*)(modp[rr] + 1024 + col); }
	s_addc_u32 s11, s11, 0
	v_pk_mul_f32 v[112:113], v[112:113], v[20:21] op_sel_hi:[1,0]
	v_pk_mul_f32 v[114:115], v[114:115], v[20:21] op_sel_hi:[1,0]
	v_pk_mul_f32 v[116:117], v[116:117], v[20:21] op_sel_hi:[1,0]
	v_pk_mul_f32 v[118:119], v[118:119], v[20:21] op_sel_hi:[1,0]
	v_pk_mul_f32 v[120:121], v[120:121], v[20:21] op_sel_hi:[1,0]
	v_pk_mul_f32 v[122:123], v[122:123], v[20:21] op_sel_hi:[1,0]
	v_pk_mul_f32 v[124:125], v[124:125], v[20:21] op_sel_hi:[1,0]
	v_pk_mul_f32 v[126:127], v[126:127], v[20:21] op_sel_hi:[1,0]
	v_pk_mul_f32 v[112:113], v[24:25], v[112:113]
	v_pk_mul_f32 v[114:115], v[26:27], v[114:115]
	v_pk_mul_f32 v[116:117], v[28:29], v[116:117]
	v_pk_mul_f32 v[118:119], v[30:31], v[118:119]
	v_pk_mul_f32 v[120:121], v[32:33], v[120:121]
	v_pk_mul_f32 v[122:123], v[34:35], v[122:123]
	v_pk_mul_f32 v[124:125], v[36:37], v[124:125]
	v_pk_mul_f32 v[126:127], v[38:39], v[126:127]
	v_pk_fma_f32 v[112:113], v[40:41], v[112:113], v[80:81]
	v_pk_fma_f32 v[114:115], v[42:43], v[114:115], v[82:83]
	v_pk_fma_f32 v[116:117], v[64:65], v[116:117], v[84:85]
	v_pk_fma_f32 v[118:119], v[66:67], v[118:119], v[86:87]
	v_pk_fma_f32 v[120:121], v[68:69], v[120:121], v[88:89]
	v_pk_fma_f32 v[122:123], v[70:71], v[122:123], v[90:91]
	v_pk_fma_f32 v[124:125], v[72:73], v[124:125], v[92:93]
	v_pk_fma_f32 v[126:127], v[74:75], v[126:127], v[94:95]
	v_cvt_pk_bf16_f32 v112, v112, v113
	v_cvt_pk_bf16_f32 v113, v114, v115
	v_cvt_pk_bf16_f32 v116, v116, v117
	v_cvt_pk_bf16_f32 v117, v118, v119
	v_cvt_pk_bf16_f32 v120, v120, v121
	v_cvt_pk_bf16_f32 v121, v122, v123
	v_cvt_pk_bf16_f32 v124, v124, v125
	v_cvt_pk_bf16_f32 v125, v126, v127
	global_store_dwordx2 v2, v[112:113], s[10:11]
	global_store_dwordx2 v2, v[116:117], s[10:11] offset:512
	global_store_dwordx2 v2, v[120:121], s[10:11] offset:1024
	global_store_dwordx2 v2, v[124:125], s[10:11] offset:1536
	s_add_u32 s10, s10, 0x800
	s_addc_u32 s11, s11, 0
	v_pk_mul_f32 v[128:129], v[128:129], v[22:23] op_sel_hi:[1,0]
	v_pk_mul_f32 v[130:131], v[130:131], v[22:23] op_sel_hi:[1,0]
	v_pk_mul_f32 v[132:133], v[132:133], v[22:23] op_sel_hi:[1,0]
	v_pk_mul_f32 v[134:135], v[134:135], v[22:23] op_sel_hi:[1,0]
	v_pk_mul_f32 v[136:137], v[136:137], v[22:23] op_sel_hi:[1,0]
	v_pk_mul_f32 v[138:139], v[138:139], v[22:23] op_sel_hi:[1,0]
	v_pk_mul_f32 v[140:141], v[140:141], v[22:23] op_sel_hi:[1,0]
	v_pk_mul_f32 v[142:143], v[142:143], v[22:23] op_sel_hi:[1,0]
	v_pk_mul_f32 v[128:129], v[24:25], v[128:129]
	v_pk_mul_f32 v[130:131], v[26:27], v[130:131]
	v_pk_mul_f32 v[132:133], v[28:29], v[132:133]
	v_pk_mul_f32 v[134:135], v[30:31], v[134:135]
	v_pk_mul_f32 v[136:137], v[32:33], v[136:137]
	v_pk_mul_f32 v[138:139], v[34:35], v[138:139]
	v_pk_mul_f32 v[140:141], v[36:37], v[140:141]
	v_pk_mul_f32 v[142:143], v[38:39], v[142:143]
	v_pk_fma_f32 v[128:129], v[40:41], v[128:129], v[80:81]
	v_pk_fma_f32 v[130:131], v[42:43], v[130:131], v[82:83]
	v_pk_fma_f32 v[132:133], v[64:65], v[132:133], v[84:85]
	v_pk_fma_f32 v[134:135], v[66:67], v[134:135], v[86:87]
	v_pk_fma_f32 v[136:137], v[68:69], v[136:137], v[88:89]
	v_pk_fma_f32 v[138:139], v[70:71], v[138:139], v[90:91]
	v_pk_fma_f32 v[140:141], v[72:73], v[140:141], v[92:93]
	v_pk_fma_f32 v[142:143], v[74:75], v[142:143], v[94:95]
	v_cvt_pk_bf16_f32 v128, v128, v129
	v_cvt_pk_bf16_f32 v129, v130, v131
	v_cvt_pk_bf16_f32 v132, v132, v133
	v_cvt_pk_bf16_f32 v133, v134, v135
	v_cvt_pk_bf16_f32 v136, v136, v137
	v_cvt_pk_bf16_f32 v137, v138, v139
	v_cvt_pk_bf16_f32 v140, v140, v141
	v_cvt_pk_bf16_f32 v141, v142, v143
	global_store_dwordx2 v2, v[128:129], s[10:11]
	global_store_dwordx2 v2, v[132:133], s[10:11] offset:512
	global_store_dwordx2 v2, v[136:137], s[10:11] offset:1024
	global_store_dwordx2 v2, v[140:141], s[10:11] offset:1536
	s_add_u32 s10, s10, 0x800
	s_addc_u32 s11, s11, 0
	v_pk_mul_f32 v[144:145], v[144:145], v[62:63] op_sel_hi:[1,0]
	v_pk_mul_f32 v[146:147], v[146:147], v[62:63] op_sel_hi:[1,0]
	v_pk_mul_f32 v[148:149], v[148:149], v[62:63] op_sel_hi:[1,0]
	v_pk_mul_f32 v[150:151], v[150:151], v[62:63] op_sel_hi:[1,0]
	v_pk_mul_f32 v[152:153], v[152:153], v[62:63] op_sel_hi:[1,0]
	v_pk_mul_f32 v[154:155], v[154:155], v[62:63] op_sel_hi:[1,0]
	v_pk_mul_f32 v[156:157], v[156:157], v[62:63] op_sel_hi:[1,0]
	v_pk_mul_f32 v[158:159], v[158:159], v[62:63] op_sel_hi:[1,0]
	v_pk_mul_f32 v[144:145], v[24:25], v[144:145]
	v_pk_mul_f32 v[146:147], v[26:27], v[146:147]
	v_pk_mul_f32 v[148:149], v[28:29], v[148:149]
	v_pk_mul_f32 v[150:151], v[30:31], v[150:151]
	v_pk_mul_f32 v[152:153], v[32:33], v[152:153]
	v_pk_mul_f32 v[154:155], v[34:35], v[154:155]
	v_pk_mul_f32 v[156:157], v[36:37], v[156:157]
	v_pk_mul_f32 v[158:159], v[38:39], v[158:159]
	v_pk_fma_f32 v[144:145], v[40:41], v[144:145], v[80:81]
	v_pk_fma_f32 v[146:147], v[42:43], v[146:147], v[82:83]
	v_pk_fma_f32 v[148:149], v[64:65], v[148:149], v[84:85]
	v_pk_fma_f32 v[150:151], v[66:67], v[150:151], v[86:87]
	v_pk_fma_f32 v[152:153], v[68:69], v[152:153], v[88:89]
	v_pk_fma_f32 v[154:155], v[70:71], v[154:155], v[90:91]
	v_pk_fma_f32 v[156:157], v[72:73], v[156:157], v[92:93]
	v_pk_fma_f32 v[158:159], v[74:75], v[158:159], v[94:95]
	v_cvt_pk_bf16_f32 v144, v144, v145
	v_cvt_pk_bf16_f32 v145, v146, v147
	v_cvt_pk_bf16_f32 v148, v148, v149
	v_cvt_pk_bf16_f32 v149, v150, v151
	v_cvt_pk_bf16_f32 v152, v152, v153
	v_cvt_pk_bf16_f32 v153, v154, v155
	v_cvt_pk_bf16_f32 v156, v156, v157
	v_cvt_pk_bf16_f32 v157, v158, v159
	global_store_dwordx2 v2, v[144:145], s[10:11]
	global_store_dwordx2 v2, v[148:149], s[10:11] offset:512
	global_store_dwordx2 v2, v[152:153], s[10:11] offset:1024
	global_store_dwordx2 v2, v[156:157], s[10:11] offset:1536
	s_add_u32 s10, s10, 0x800
	s_addc_u32 s11, s11, 0
	s_mul_i32 s5, s6, 5
	s_add_u32 s5, s5, 4
	s_mul_i32 s5, s5, 0x6000
	s_add_u32 s24, s88, 0x100000
	s_addc_u32 s25, s89, 0
	s_add_u32 s24, s24, s5
	s_addc_u32 s25, s25, 0
	s_add_u32 s26, s24, 0x1000
	s_addc_u32 s27, s25, 0
	global_load_dwordx4 v[96:99], v1, s[30:31] nt
	global_load_dwordx4 v[100:103], v1, s[30:31] offset:1024 nt
	global_load_dwordx4 v[104:107], v1, s[30:31] offset:2048 nt
	global_load_dwordx4 v[108:111], v1, s[30:31] offset:3072 nt
	global_load_dwordx4 v[112:115], v1, s[26:27]
	global_load_dwordx4 v[116:119], v1, s[26:27] offset:1024
	global_load_dwordx4 v[120:123], v1, s[26:27] offset:2048
	global_load_dwordx4 v[124:127], v1, s[26:27] offset:3072
	global_load_dwordx4 v[128:131], v1, s[24:25]
	global_load_dwordx4 v[132:135], v1, s[24:25] offset:1024
	global_load_dwordx4 v[136:139], v1, s[24:25] offset:2048
	global_load_dwordx4 v[140:143], v1, s[24:25] offset:3072
	s_waitcnt vmcnt(28)
; DI unsigned pk2(float lo, float hi) { return f2bf(lo) | (f2bf(hi) << 16); }
; DI void norm_phase(const Args& A, int wave_s, int l, int which, int rows) {
;     ...
;             float ss = 0.f;
; #pragma unroll
;             for (int j = 0; j < 4; ++j) ss += (xv[rr][j].x * xv[rr][j].x + xv[rr][j].y * xv[rr][j].y) + (xv[rr][j].z * xv[rr][j].z + xv[rr][j].w * xv[rr][j].w);
;             ss = wave_sum(C.lane, ss);
;             const float rs = rsqrtf(ss * (1.f / 1024.f) + EPS);
; #pragma unroll
;             for (int j = 0; j < 4; ++j) { const int col = 4 * (C.lane + 64 * j);
;                 const f32x4 y = xv[rr][j] * rs * g[j] * (sc[j] + 1.f) + sh[j];
;                 v2u o; o.x = pk2(y.x, y.y); o.y = pk2(y.z, y.w);
;                 *(v2u*)(C.H + (size_t)m * 1024 + col) = o; }
	v_mul_f32_e32 v10, v164, v164
	v_fmac_f32_e32 v10, v165, v165
	v_fmac_f32_e32 v10, v166, v166
	v_fmac_f32_e32 v10, v167, v167
	v_fmac_f32_e32 v10, v168, v168
	v_fmac_f32_e32 v10, v169, v169
	v_fmac_f32_e32 v10, v170, v170
	v_fmac_f32_e32 v10, v171, v171
	v_fmac_f32_e32 v10, v172, v172
	v_fmac_f32_e32 v10, v173, v173
	v_fmac_f32_e32 v10, v174, v174
	v_fmac_f32_e32 v10, v175, v175
	v_fmac_f32_e32 v10, v176, v176
	v_fmac_f32_e32 v10, v177, v177
	v_fmac_f32_e32 v10, v178, v178
	v_fmac_f32_e32 v10, v179, v179
	v_mul_f32_e32 v11, v180, v180
	v_fmac_f32_e32 v11, v181, v181
	v_fmac_f32_e32 v11, v182, v182
	v_fmac_f32_e32 v11, v183, v183
	v_fmac_f32_e32 v11, v184, v184
	v_fmac_f32_e32 v11, v185, v185
	v_fmac_f32_e32 v11, v186, v186
	v_fmac_f32_e32 v11, v187, v187
	v_fmac_f32_e32 v11, v188, v188
	v_fmac_f32_e32 v11, v189, v189
	v_fmac_f32_e32 v11, v190, v190
	v_fmac_f32_e32 v11, v191, v191
	v_fmac_f32_e32 v11, v192, v192
	v_fmac_f32_e32 v11, v193, v193
	v_fmac_f32_e32 v11, v194, v194
	v_fmac_f32_e32 v11, v195, v195
	v_mul_f32_e32 v12, v196, v196
	v_fmac_f32_e32 v12, v197, v197
	v_fmac_f32_e32 v12, v198, v198
	v_fmac_f32_e32 v12, v199, v199
	v_fmac_f32_e32 v12, v200, v200
	v_fmac_f32_e32 v12, v201, v201
	v_fmac_f32_e32 v12, v202, v202
	v_fmac_f32_e32 v12, v203, v203
	v_fmac_f32_e32 v12, v204, v204
	v_fmac_f32_e32 v12, v205, v205
	v_fmac_f32_e32 v12, v206, v206
	v_fmac_f32_e32 v12, v207, v207
	v_fmac_f32_e32 v12, v208, v208
	v_fmac_f32_e32 v12, v209, v209
	v_fmac_f32_e32 v12, v210, v210
	v_fmac_f32_e32 v12, v211, v211
	v_mul_f32_e32 v13, v212, v212
	v_fmac_f32_e32 v13, v213, v213
	v_fmac_f32_e32 v13, v214, v214
	v_fmac_f32_e32 v13, v215, v215
	v_fmac_f32_e32 v13, v216, v216
	v_fmac_f32_e32 v13, v217, v217
	v_fmac_f32_e32 v13, v218, v218
	v_fmac_f32_e32 v13, v219, v219
	v_fmac_f32_e32 v13, v220, v220
	v_fmac_f32_e32 v13, v221, v221
	v_fmac_f32_e32 v13, v222, v222
	v_fmac_f32_e32 v13, v223, v223
	v_fmac_f32_e32 v13, v224, v224
	v_fmac_f32_e32 v13, v225, v225
	v_fmac_f32_e32 v13, v226, v226
	v_fmac_f32_e32 v13, v227, v227
	ds_bpermute_b32 v14, v4, v10
	ds_bpermute_b32 v15, v4, v11
	ds_bpermute_b32 v16, v4, v12
	ds_bpermute_b32 v17, v4, v13
	s_waitcnt lgkmcnt(0)
	v_add_f32_e32 v10, v10, v14
	v_add_f32_e32 v11, v11, v15
	v_add_f32_e32 v12, v12, v16
	v_add_f32_e32 v13, v13, v17
	ds_bpermute_b32 v14, v5, v10
	ds_bpermute_b32 v15, v5, v11
	ds_bpermute_b32 v16, v5, v12
	ds_bpermute_b32 v17, v5, v13
	s_waitcnt lgkmcnt(0)
	v_add_f32_e32 v10, v10, v14
	v_add_f32_e32 v11, v11, v15
	v_add_f32_e32 v12, v12, v16
	v_add_f32_e32 v13, v13, v17
	ds_bpermute_b32 v14, v6, v10
	ds_bpermute_b32 v15, v6, v11
	ds_bpermute_b32 v16, v6, v12
	ds_bpermute_b32 v17, v6, v13
	s_waitcnt lgkmcnt(0)
	v_add_f32_e32 v10, v10, v14
	v_add_f32_e32 v11, v11, v15
	v_add_f32_e32 v12, v12, v16
	v_add_f32_e32 v13, v13, v17
	ds_bpermute_b32 v14, v7, v10
	ds_bpermute_b32 v15, v7, v11
	ds_bpermute_b32 v16, v7, v12
	ds_bpermute_b32 v17, v7, v13
	s_waitcnt lgkmcnt(0)
	v_add_f32_e32 v10, v10, v14
	v_add_f32_e32 v11, v11, v15
	v_add_f32_e32 v12, v12, v16
	v_add_f32_e32 v13, v13, v17
	ds_bpermute_b32 v14, v8, v10
	ds_bpermute_b32 v15, v8, v11
	ds_bpermute_b32 v16, v8, v12
	ds_bpermute_b32 v17, v8, v13
	s_waitcnt lgkmcnt(0)
	v_add_f32_e32 v10, v10, v14
	v_add_f32_e32 v11, v11, v15
	v_add_f32_e32 v12, v12, v16
	v_add_f32_e32 v13, v13, v17
	ds_bpermute_b32 v14, v9, v10
	ds_bpermute_b32 v15, v9, v11
	ds_bpermute_b32 v16, v9, v12
	ds_bpermute_b32 v17, v9, v13
	s_waitcnt lgkmcnt(0)
	v_add_f32_e32 v10, v10, v14
	v_add_f32_e32 v11, v11, v15
	v_add_f32_e32 v12, v12, v16
	v_add_f32_e32 v13, v13, v17
	v_fma_f32 v10, v10, s32, v60
	v_fma_f32 v11, v11, s32, v60
	v_fma_f32 v12, v12, s32, v60
	v_fma_f32 v13, v13, s32, v60
	v_rsq_f32_e32 v18, v10
	v_rsq_f32_e32 v20, v11
	v_rsq_f32_e32 v22, v12
	v_rsq_f32_e32 v62, v13
	s_nop 0
	v_pk_mul_f32 v[164:165], v[164:165], v[18:19] op_sel_hi:[1,0]
	v_pk_mul_f32 v[166:167], v[166:167], v[18:19] op_sel_hi:[1,0]
	v_pk_mul_f32 v[168:169], v[168:169], v[18:19] op_sel_hi:[1,0]
	v_pk_mul_f32 v[170:171], v[170:171], v[18:19] op_sel_hi:[1,0]
	v_pk_mul_f32 v[172:173], v[172:173], v[18:19] op_sel_hi:[1,0]
	v_pk_mul_f32 v[174:175], v[174:175], v[18:19] op_sel_hi:[1,0]
	v_pk_mul_f32 v[176:177], v[176:177], v[18:19] op_sel_hi:[1,0]
	v_pk_mul_f32 v[178:179], v[178:179], v[18:19] op_sel_hi:[1,0]
	v_pk_mul_f32 v[164:165], v[24:25], v[164:165]
	v_pk_mul_f32 v[166:167], v[26:27], v[166:167]
	v_pk_mul_f32 v[168:169], v[28:29], v[168:169]
	v_pk_mul_f32 v[170:171], v[30:31], v[170:171]
	v_pk_mul_f32 v[172:173], v[32:33], v[172:173]
	v_pk_mul_f32 v[174:175], v[34:35], v[174:175]
	v_pk_mul_f32 v[176:177], v[36:37], v[176:177]
	v_pk_mul_f32 v[178:179], v[38:39], v[178:179]
	v_pk_fma_f32 v[164:165], v[40:41], v[164:165], v[80:81]
	v_pk_fma_f32 v[166:167], v[42:43], v[166:167], v[82:83]
	v_pk_fma_f32 v[168:169], v[64:65], v[168:169], v[84:85]
	v_pk_fma_f32 v[170:171], v[66:67], v[170:171], v[86:87]
	v_pk_fma_f32 v[172:173], v[68:69], v[172:173], v[88:89]
	v_pk_fma_f32 v[174:175], v[70:71], v[174:175], v[90:91]
	v_pk_fma_f32 v[176:177], v[72:73], v[176:177], v[92:93]
	v_pk_fma_f32 v[178:179], v[74:75], v[178:179], v[94:95]
	v_cvt_pk_bf16_f32 v164, v164, v165
	v_cvt_pk_bf16_f32 v165, v166, v167
	v_cvt_pk_bf16_f32 v168, v168, v169
	v_cvt_pk_bf16_f32 v169, v170, v171
	v_cvt_pk_bf16_f32 v172, v172, v173
	v_cvt_pk_bf16_f32 v173, v174, v175
	v_cvt_pk_bf16_f32 v176, v176, v177
	v_cvt_pk_bf16_f32 v177, v178, v179
	global_store_dwordx2 v2, v[164:165], s[10:11]
	global_store_dwordx2 v2, v[168:169], s[10:11] offset:512
	global_store_dwordx2 v2, v[172:173], s[10:11] offset:1024
	global_store_dwordx2 v2, v[176:177], s[10:11] offset:1536
; DI unsigned pk2(float lo, float hi) { return f2bf(lo) | (f2bf(hi) << 16); }
; DI void norm_phase(const Args& A, int wave_s, int l, int which, int rows) {
;     ...
;         for (int rr = 0; rr < 2; ++rr) {
;             const int m = m0 + rr; const float* xr; int v;
;             if (m < NLAT) { xr = (from_in ? C.x : C.out) + (size_t)m * 1024; v = m >> 13; }
;             else { xr = (from_in ? C.ctx : C.XC) + (size_t)(m - NLAT) * 1024; v = 4; }
;             modp[rr] = C.SM + SM_MOD + (l * 5 + v) * 6144 + (which == 1 ? 0 : 3072);
; #pragma unroll
;             for (int j = 0; j < 4; ++j) xv[rr][j] = ((const f32x4*)xr)[C.lane + 64 * j];
;         }
; #pragma unroll
;         for (int rr = 0; rr < 2; ++rr) {
;             const int m = m0 + rr;
;             f32x4 sh[4], sc[4];
; #pragma unroll
;             for (int j = 0; j < 4; ++j) { const int col = 4 * (C.lane + 64 * j); sh[j] = *(const f32x4*)(modp[rr] + col); sc[j] = *(const f32x4*)(modp[rr] + 1024 + col); }
;             float ss = 0.f;
; #pragma unroll
;             for (int j = 0; j < 4; ++j) ss += (xv[rr][j].x * xv[rr][j].x + xv[rr][j].y * xv[rr][j].y) + (xv[rr][j].z * xv[rr][j].z + xv[rr][j].w * xv[rr][j].w);
;             ss = wave_sum(C.lane, ss);
;             const float rs = rsqrtf(ss * (1.f / 1024.f) + EPS);
; #pragma unroll
;             for (int j = 0; j < 4; ++j) { const int col = 4 * (C.lane + 64 * j);
;                 const f32x4 y = xv[rr][j] * rs * g[j] * (sc[j] + 1.f) + sh[j];
;                 v2u o; o.x = pk2(y.x, y.y); o.y = pk2(y.z, y.w);
;                 *(v2u*)(C.H + (size_t)m * 1024 + col) = o; }
	s_add_u32 s10, s10, 0x800
	s_addc_u32 s11, s11, 0
	v_pk_mul_f32 v[180:181], v[180:181], v[20:21] op_sel_hi:[1,0]
	v_pk_mul_f32 v[182:183], v[182:183], v[20:21] op_sel_hi:[1,0]
	v_pk_mul_f32 v[184:185], v[184:185], v[20:21] op_sel_hi:[1,0]
	v_pk_mul_f32 v[186:187], v[186:187], v[20:21] op_sel_hi:[1,0]
	v_pk_mul_f32 v[188:189], v[188:189], v[20:21] op_sel_hi:[1,0]
	v_pk_mul_f32 v[190:191], v[190:191], v[20:21] op_sel_hi:[1,0]
	v_pk_mul_f32 v[192:193], v[192:193], v[20:21] op_sel_hi:[1,0]
	v_pk_mul_f32 v[194:195], v[194:195], v[20:21] op_sel_hi:[1,0]
	v_pk_mul_f32 v[180:181], v[24:25], v[180:181]
	v_pk_mul_f32 v[182:183], v[26:27], v[182:183]
	v_pk_mul_f32 v[184:185], v[28:29], v[184:185]
	v_pk_mul_f32 v[186:187], v[30:31], v[186:187]
	v_pk_mul_f32 v[188:189], v[32:33], v[188:189]
	v_pk_mul_f32 v[190:191], v[34:35], v[190:191]
	v_pk_mul_f32 v[192:193], v[36:37], v[192:193]
	v_pk_mul_f32 v[194:195], v[38:39], v[194:195]
	v_pk_fma_f32 v[180:181], v[40:41], v[180:181], v[80:81]
	v_pk_fma_f32 v[182:183], v[42:43], v[182:183], v[82:83]
	v_pk_fma_f32 v[184:185], v[64:65], v[184:185], v[84:85]
	v_pk_fma_f32 v[186:187], v[66:67], v[186:187], v[86:87]
	v_pk_fma_f32 v[188:189], v[68:69], v[188:189], v[88:89]
	v_pk_fma_f32 v[190:191], v[70:71], v[190:191], v[90:91]
	v_pk_fma_f32 v[192:193], v[72:73], v[192:193], v[92:93]
	v_pk_fma_f32 v[194:195], v[74:75], v[194:195], v[94:95]
	v_cvt_pk_bf16_f32 v180, v180, v181
	v_cvt_pk_bf16_f32 v181, v182, v183
	v_cvt_pk_bf16_f32 v184, v184, v185
	v_cvt_pk_bf16_f32 v185, v186, v187
	v_cvt_pk_bf16_f32 v188, v188, v189
	v_cvt_pk_bf16_f32 v189, v190, v191
	v_cvt_pk_bf16_f32 v192, v192, v193
	v_cvt_pk_bf16_f32 v193, v194, v195
	global_store_dwordx2 v2, v[180:181], s[10:11]
	global_store_dwordx2 v2, v[184:185], s[10:11] offset:512
	global_store_dwordx2 v2, v[188:189], s[10:11] offset:1024
	global_store_dwordx2 v2, v[192:193], s[10:11] offset:1536
	s_add_u32 s10, s10, 0x800
	s_addc_u32 s11, s11, 0
	v_pk_mul_f32 v[196:197], v[196:197], v[22:23] op_sel_hi:[1,0]
	v_pk_mul_f32 v[198:199], v[198:199], v[22:23] op_sel_hi:[1,0]
	v_pk_mul_f32 v[200:201], v[200:201], v[22:23] op_sel_hi:[1,0]
	v_pk_mul_f32 v[202:203], v[202:203], v[22:23] op_sel_hi:[1,0]
	v_pk_mul_f32 v[204:205], v[204:205], v[22:23] op_sel_hi:[1,0]
	v_pk_mul_f32 v[206:207], v[206:207], v[22:23] op_sel_hi:[1,0]
	v_pk_mul_f32 v[208:209], v[208:209], v[22:23] op_sel_hi:[1,0]
	v_pk_mul_f32 v[210:211], v[210:211], v[22:23] op_sel_hi:[1,0]
	v_pk_mul_f32 v[196:197], v[24:25], v[196:197]
	v_pk_mul_f32 v[198:199], v[26:27], v[198:199]
	v_pk_mul_f32 v[200:201], v[28:29], v[200:201]
	v_pk_mul_f32 v[202:203], v[30:31], v[202:203]
	v_pk_mul_f32 v[204:205], v[32:33], v[204:205]
	v_pk_mul_f32 v[206:207], v[34:35], v[206:207]
	v_pk_mul_f32 v[208:209], v[36:37], v[208:209]
	v_pk_mul_f32 v[210:211], v[38:39], v[210:211]
	v_pk_fma_f32 v[196:197], v[40:41], v[196:197], v[80:81]
	v_pk_fma_f32 v[198:199], v[42:43], v[198:199], v[82:83]
	v_pk_fma_f32 v[200:201], v[64:65], v[200:201], v[84:85]
	v_pk_fma_f32 v[202:203], v[66:67], v[202:203], v[86:87]
	v_pk_fma_f32 v[204:205], v[68:69], v[204:205], v[88:89]
	v_pk_fma_f32 v[206:207], v[70:71], v[206:207], v[90:91]
	v_pk_fma_f32 v[208:209], v[72:73], v[208:209], v[92:93]
	v_pk_fma_f32 v[210:211], v[74:75], v[210:211], v[94:95]
	v_cvt_pk_bf16_f32 v196, v196, v197
	v_cvt_pk_bf16_f32 v197, v198, v199
	v_cvt_pk_bf16_f32 v200, v200, v201
	v_cvt_pk_bf16_f32 v201, v202, v203
	v_cvt_pk_bf16_f32 v204, v204, v205
	v_cvt_pk_bf16_f32 v205, v206, v207
	v_cvt_pk_bf16_f32 v208, v208, v209
	v_cvt_pk_bf16_f32 v209, v210, v211
	global_store_dwordx2 v2, v[196:197], s[10:11]
	global_store_dwordx2 v2, v[200:201], s[10:11] offset:512
	global_store_dwordx2 v2, v[204:205], s[10:11] offset:1024
	global_store_dwordx2 v2, v[208:209], s[10:11] offset:1536
	s_add_u32 s10, s10, 0x800
	s_addc_u32 s11, s11, 0
	v_pk_mul_f32 v[212:213], v[212:213], v[62:63] op_sel_hi:[1,0]
	v_pk_mul_f32 v[214:215], v[214:215], v[62:63] op_sel_hi:[1,0]
	v_pk_mul_f32 v[216:217], v[216:217], v[62:63] op_sel_hi:[1,0]
	v_pk_mul_f32 v[218:219], v[218:219], v[62:63] op_sel_hi:[1,0]
	v_pk_mul_f32 v[220:221], v[220:221], v[62:63] op_sel_hi:[1,0]
	v_pk_mul_f32 v[222:223], v[222:223], v[62:63] op_sel_hi:[1,0]
	v_pk_mul_f32 v[224:225], v[224:225], v[62:63] op_sel_hi:[1,0]
	v_pk_mul_f32 v[226:227], v[226:227], v[62:63] op_sel_hi:[1,0]
	v_pk_mul_f32 v[212:213], v[24:25], v[212:213]
	v_pk_mul_f32 v[214:215], v[26:27], v[214:215]
	v_pk_mul_f32 v[216:217], v[28:29], v[216:217]
	v_pk_mul_f32 v[218:219], v[30:31], v[218:219]
	v_pk_mul_f32 v[220:221], v[32:33], v[220:221]
	v_pk_mul_f32 v[222:223], v[34:35], v[222:223]
	v_pk_mul_f32 v[224:225], v[36:37], v[224:225]
	v_pk_mul_f32 v[226:227], v[38:39], v[226:227]
	v_pk_fma_f32 v[212:213], v[40:41], v[212:213], v[80:81]
	v_pk_fma_f32 v[214:215], v[42:43], v[214:215], v[82:83]
	v_pk_fma_f32 v[216:217], v[64:65], v[216:217], v[84:85]
	v_pk_fma_f32 v[218:219], v[66:67], v[218:219], v[86:87]
	v_pk_fma_f32 v[220:221], v[68:69], v[220:221], v[88:89]
	v_pk_fma_f32 v[222:223], v[70:71], v[222:223], v[90:91]
	v_pk_fma_f32 v[224:225], v[72:73], v[224:225], v[92:93]
	v_pk_fma_f32 v[226:227], v[74:75], v[226:227], v[94:95]
	v_cvt_pk_bf16_f32 v212, v212, v213
	v_cvt_pk_bf16_f32 v213, v214, v215
	v_cvt_pk_bf16_f32 v216, v216, v217
	v_cvt_pk_bf16_f32 v217, v218, v219
	v_cvt_pk_bf16_f32 v220, v220, v221
	v_cvt_pk_bf16_f32 v221, v222, v223
	v_cvt_pk_bf16_f32 v224, v224, v225
	v_cvt_pk_bf16_f32 v225, v226, v227
	global_store_dwordx2 v2, v[212:213], s[10:11]
	global_store_dwordx2 v2, v[216:217], s[10:11] offset:512
	global_store_dwordx2 v2, v[220:221], s[10:11] offset:1024
	global_store_dwordx2 v2, v[224:225], s[10:11] offset:1536
	s_add_u32 s10, s10, 0x800
	s_addc_u32 s11, s11, 0
	s_add_u32 s10, s88, 0x3800000
	s_addc_u32 s11, s89, 0
	s_add_u32 s10, s10, 0x4000000
	s_addc_u32 s11, s11, 0
	s_lshl_b32 s5, s7, 11
	s_add_u32 s10, s10, s5
	s_addc_u32 s11, s11, 0
	s_waitcnt vmcnt(16)
	v_pk_add_f32 v[112:113], v[112:113], 1.0 op_sel_hi:[1,0]
	v_pk_add_f32 v[114:115], v[114:115], 1.0 op_sel_hi:[1,0]
	v_pk_add_f32 v[116:117], v[116:117], 1.0 op_sel_hi:[1,0]
	v_pk_add_f32 v[118:119], v[118:119], 1.0 op_sel_hi:[1,0]
	v_pk_add_f32 v[120:121], v[120:121], 1.0 op_sel_hi:[1,0]
	v_pk_add_f32 v[122:123], v[122:123], 1.0 op_sel_hi:[1,0]
	v_pk_add_f32 v[124:125], v[124:125], 1.0 op_sel_hi:[1,0]
	v_pk_add_f32 v[126:127], v[126:127], 1.0 op_sel_hi:[1,0]
	s_cmp_eq_u32 s2, 0
	s_cbranch_scc1 .Lnorm_n1_done
; DI unsigned pk2(float lo, float hi) { return f2bf(lo) | (f2bf(hi) << 16); }
; DI void norm_phase(const Args& A, int wave_s, int l, int which, int rows) {
;     ...
;         for (int rr = 0; rr < 2; ++rr) {
;             const int m = m0 + rr;
;             f32x4 sh[4], sc[4];
; #pragma unroll
;             for (int j = 0; j < 4; ++j) { const int col = 4 * (C.lane + 64 * j); sh[j] = *(const f32x4*)(modp[rr] + col); sc[j] = *(const f32x4*)(modp[rr] + 1024 + col); }
;             float ss = 0.f;
; #pragma unroll
;             for (int j = 0; j < 4; ++j) ss += (xv[rr][j].x * xv[rr][j].x + xv[rr][j].y * xv[rr][j].y) + (xv[rr][j].z * xv[rr][j].z + xv[rr][j].w * xv[rr][j].w);
;             ss = wave_sum(C.lane, ss);
;             const float rs = rsqrtf(ss * (1.f / 1024.f) + EPS);
; #pragma unroll
;             for (int j = 0; j < 4; ++j) { const int col = 4 * (C.lane + 64 * j);
;                 const f32x4 y = xv[rr][j] * rs * g[j] * (sc[j] + 1.f) + sh[j];
;                 v2u o; o.x = pk2(y.x, y.y); o.y = pk2(y.z, y.w);
;                 *(v2u*)(C.H + (size_t)m * 1024 + col) = o; }
	v_mul_f32_e32 v10, v96, v96
	v_fmac_f32_e32 v10, v97, v97
	v_fmac_f32_e32 v10, v98, v98
	v_fmac_f32_e32 v10, v99, v99
	v_fmac_f32_e32 v10, v100, v100
	v_fmac_f32_e32 v10, v101, v101
	v_fmac_f32_e32 v10, v102, v102
	v_fmac_f32_e32 v10, v103, v103
	v_fmac_f32_e32 v10, v104, v104
	v_fmac_f32_e32 v10, v105, v105
	v_fmac_f32_e32 v10, v106, v106
	v_fmac_f32_e32 v10, v107, v107
	v_fmac_f32_e32 v10, v108, v108
	v_fmac_f32_e32 v10, v109, v109
	v_fmac_f32_e32 v10, v110, v110
	v_fmac_f32_e32 v10, v111, v111
	ds_bpermute_b32 v14, v4, v10
	s_waitcnt lgkmcnt(0)
	v_add_f32_e32 v10, v10, v14
	ds_bpermute_b32 v14, v5, v10
	s_waitcnt lgkmcnt(0)
	v_add_f32_e32 v10, v10, v14
	ds_bpermute_b32 v14, v6, v10
	s_waitcnt lgkmcnt(0)
	v_add_f32_e32 v10, v10, v14
	ds_bpermute_b32 v14, v7, v10
	s_waitcnt lgkmcnt(0)
	v_add_f32_e32 v10, v10, v14
	ds_bpermute_b32 v14, v8, v10
	s_waitcnt lgkmcnt(0)
	v_add_f32_e32 v10, v10, v14
	ds_bpermute_b32 v14, v9, v10
	s_waitcnt lgkmcnt(0)
	v_add_f32_e32 v10, v10, v14
	v_fma_f32 v10, v10, s32, v60
	v_rsq_f32_e32 v18, v10
	s_nop 0
	v_pk_mul_f32 v[96:97], v[96:97], v[18:19] op_sel_hi:[1,0]
	v_pk_mul_f32 v[98:99], v[98:99], v[18:19] op_sel_hi:[1,0]
	v_pk_mul_f32 v[100:101], v[100:101], v[18:19] op_sel_hi:[1,0]
	v_pk_mul_f32 v[102:103], v[102:103], v[18:19] op_sel_hi:[1,0]
	v_pk_mul_f32 v[104:105], v[104:105], v[18:19] op_sel_hi:[1,0]
	v_pk_mul_f32 v[106:107], v[106:107], v[18:19] op_sel_hi:[1,0]
	v_pk_mul_f32 v[108:109], v[108:109], v[18:19] op_sel_hi:[1,0]
	v_pk_mul_f32 v[110:111], v[110:111], v[18:19] op_sel_hi:[1,0]
	v_pk_mul_f32 v[96:97], v[24:25], v[96:97]
	v_pk_mul_f32 v[98:99], v[26:27], v[98:99]
	v_pk_mul_f32 v[100:101], v[28:29], v[100:101]
	v_pk_mul_f32 v[102:103], v[30:31], v[102:103]
	v_pk_mul_f32 v[104:105], v[32:33], v[104:105]
	v_pk_mul_f32 v[106:107], v[34:35], v[106:107]
	v_pk_mul_f32 v[108:109], v[36:37], v[108:109]
	v_pk_mul_f32 v[110:111], v[38:39], v[110:111]
	v_pk_fma_f32 v[96:97], v[112:113], v[96:97], v[128:129]
	v_pk_fma_f32 v[98:99], v[114:115], v[98:99], v[130:131]
	v_pk_fma_f32 v[100:101], v[116:117], v[100:101], v[132:133]
	v_pk_fma_f32 v[102:103], v[118:119], v[102:103], v[134:135]
	v_pk_fma_f32 v[104:105], v[120:121], v[104:105], v[136:137]
	v_pk_fma_f32 v[106:107], v[122:123], v[106:107], v[138:139]
	v_pk_fma_f32 v[108:109], v[124:125], v[108:109], v[140:141]
	v_pk_fma_f32 v[110:111], v[126:127], v[110:111], v[142:143]
	v_cvt_pk_bf16_f32 v96, v96, v97
	v_cvt_pk_bf16_f32 v97, v98, v99
	v_cvt_pk_bf16_f32 v100, v100, v101
	v_cvt_pk_bf16_f32 v101, v102, v103
	v_cvt_pk_bf16_f32 v104, v104, v105
	v_cvt_pk_bf16_f32 v105, v106, v107
	v_cvt_pk_bf16_f32 v108, v108, v109
	v_cvt_pk_bf16_f32 v109, v110, v111
	global_store_dwordx2 v2, v[96:97], s[10:11]
	global_store_dwordx2 v2, v[100:101], s[10:11] offset:512
	global_store_dwordx2 v2, v[104:105], s[10:11] offset:1024
	global_store_dwordx2 v2, v[108:109], s[10:11] offset:1536

; DI void norm_phase(const Args& A, int wave_s, int l, int which, int rows) {
;     ...
;     const float* gn = (which == 1 ? C.n1g : C.n2g) + l * 1024;
;     const bool from_in = (l == 0 && which == 1);
;     f32x4 g[4];
; #pragma unroll
;     for (int j = 0; j < 4; ++j) g[j] = *(const f32x4*)(gn + 4 * (C.lane + 64 * j));
;     for (int m0 = C.gw * 2; m0 < rows; m0 += C.NGW * 2) {
;         f32x4 xv[2][4];
;         const float* modp[2];
; #pragma unroll
;         for (int rr = 0; rr < 2; ++rr) {
;             const int m = m0 + rr; const float* xr; int v;
;             if (m < NLAT) { xr = (from_in ? C.x : C.out) + (size_t)m * 1024; v = m >> 13; }
;             else { xr = (from_in ? C.ctx : C.XC) + (size_t)(m - NLAT) * 1024; v = 4; }
;             modp[rr] = C.SM + SM_MOD + (l * 5 + v) * 6144 + (which == 1 ? 0 : 3072);
; #pragma unroll
;             for (int j = 0; j < 4; ++j) xv[rr][j] = ((const f32x4*)xr)[C.lane + 64 * j];
;         }
; #pragma unroll
;         for (int rr = 0; rr < 2; ++rr) {
;             const int m = m0 + rr;
;             f32x4 sh[4], sc[4];
; #pragma unroll
;             for (int j = 0; j < 4; ++j) { const int col = 4 * (C.lane + 64 * j); sh[j] = *(const f32x4*)(modp[rr] + col); sc[j] = *(const f32x4*)(modp[rr] + 1024 + col); }
.LBB0_528:
	s_or_b64 exec, exec, s[4:5]
	v_readlane_b32 s4, v254, 41
	s_cmp_ge_i32 s4, s42
	s_waitcnt lgkmcnt(0)
	s_barrier
	v_readlane_b32 s5, v254, 42
	v_mbcnt_lo_u32_b32 v48, -1, 0
	v_mbcnt_hi_u32_b32 v48, -1, v48
	v_mbcnt_lo_u32_b32 v0, -1, 0
	v_mbcnt_hi_u32_b32 v0, -1, v0
	v_readlane_b32 s6, v255, 32
	v_lshlrev_b32_e32 v1, 4, v0
	v_lshlrev_b32_e32 v2, 3, v0
	v_xor_b32_e32 v4, 1, v0
	v_xor_b32_e32 v5, 2, v0
	v_xor_b32_e32 v6, 4, v0
	v_xor_b32_e32 v7, 8, v0
	v_xor_b32_e32 v8, 16, v0
	v_xor_b32_e32 v9, 32, v0
	v_lshlrev_b32_e32 v4, 2, v4
	v_lshlrev_b32_e32 v5, 2, v5
	v_lshlrev_b32_e32 v6, 2, v6
	v_lshlrev_b32_e32 v7, 2, v7
	v_lshlrev_b32_e32 v8, 2, v8
	v_lshlrev_b32_e32 v9, 2, v9
	v_mov_b32_e32 v60, 0x358637bd
	s_lshr_b32 s6, s6, 10
	s_lshr_b32 s4, s94, 6
	s_lshl_b32 s5, s65, 3
	s_add_u32 s4, s4, s5
	s_lshr_b32 s5, s4, 9
	s_mul_i32 s7, s6, 5
	s_add_u32 s5, s7, s5
	s_mul_i32 s5, s5, 0x6000
	s_add_u32 s24, s88, 0x103000
	s_addc_u32 s25, s89, 0
	s_add_u32 s24, s24, s5
	s_addc_u32 s25, s25, 0
	s_add_u32 s26, s24, 0x1000
	s_addc_u32 s27, s25, 0
	v_readlane_b32 s28, v252, 48
	v_readlane_b32 s29, v252, 49
	s_lshl_b32 s7, s6, 12
	s_nop 1
	s_add_u32 s28, s28, s7
	s_addc_u32 s29, s29, 0
	v_readlane_b32 s8, v252, 31
	v_readlane_b32 s9, v252, 32
	s_add_u32 s30, s88, 0x3400000
	s_addc_u32 s31, s89, 0
	s_nop 1
	s_cmp_gt_u32 s42, 0x8000
	s_cselect_b32 s2, 1, 0
	s_cmp_lt_u32 s4, 0x400
	s_cselect_b32 s2, s2, 0
	s_and_b32 s7, s4, 0x3ff
	s_lshl_b32 s5, s7, 12
	s_add_u32 s30, s30, s5
	s_addc_u32 s31, s31, 0
	s_lshl_b32 s5, s4, 16
	s_add_u32 s8, s8, s5
	s_addc_u32 s9, s9, 0
	s_add_u32 s10, s88, 0x3800000
	s_addc_u32 s11, s89, 0
	s_lshl_b32 s5, s4, 15
	s_add_u32 s10, s10, s5
	s_addc_u32 s11, s11, 0
	s_mov_b32 s32, 0x3a800000
	global_load_dwordx4 v[24:27], v1, s[28:29]
	global_load_dwordx4 v[28:31], v1, s[28:29] offset:1024
	global_load_dwordx4 v[32:35], v1, s[28:29] offset:2048
	global_load_dwordx4 v[36:39], v1, s[28:29] offset:3072
	global_load_dwordx4 v[40:43], v1, s[26:27]
	global_load_dwordx4 v[64:67], v1, s[26:27] offset:1024
	global_load_dwordx4 v[68:71], v1, s[26:27] offset:2048
	global_load_dwordx4 v[72:75], v1, s[26:27] offset:3072
	global_load_dwordx4 v[80:83], v1, s[24:25]
	global_load_dwordx4 v[84:87], v1, s[24:25] offset:1024
	global_load_dwordx4 v[88:91], v1, s[24:25] offset:2048
	global_load_dwordx4 v[92:95], v1, s[24:25] offset:3072
	global_load_dwordx4 v[96:99], v1, s[8:9] nt
	global_load_dwordx4 v[100:103], v1, s[8:9] offset:1024 nt
	global_load_dwordx4 v[104:107], v1, s[8:9] offset:2048 nt
	global_load_dwordx4 v[108:111], v1, s[8:9] offset:3072 nt
	s_add_u32 s8, s8, 0x1000
	s_addc_u32 s9, s9, 0
	global_load_dwordx4 v[112:115], v1, s[8:9] nt
	global_load_dwordx4 v[116:119], v1, s[8:9] offset:1024 nt
	global_load_dwordx4 v[120:123], v1, s[8:9] offset:2048 nt
	global_load_dwordx4 v[124:127], v1, s[8:9] offset:3072 nt
	s_add_u32 s8, s8, 0x1000
	s_addc_u32 s9, s9, 0
	global_load_dwordx4 v[128:131], v1, s[8:9] nt
	global_load_dwordx4 v[132:135], v1, s[8:9] offset:1024 nt
	global_load_dwordx4 v[136:139], v1, s[8:9] offset:2048 nt
	global_load_dwordx4 v[140:143], v1, s[8:9] offset:3072 nt
	s_add_u32 s8, s8, 0x1000
	s_addc_u32 s9, s9, 0
	global_load_dwordx4 v[144:147], v1, s[8:9] nt
	global_load_dwordx4 v[148:151], v1, s[8:9] offset:1024 nt
	global_load_dwordx4 v[152:155], v1, s[8:9] offset:2048 nt
	global_load_dwordx4 v[156:159], v1, s[8:9] offset:3072 nt
	s_add_u32 s8, s8, 0x1000
	s_addc_u32 s9, s9, 0
	global_load_dwordx4 v[164:167], v1, s[8:9] nt
	global_load_dwordx4 v[168:171], v1, s[8:9] offset:1024 nt
	global_load_dwordx4 v[172:175], v1, s[8:9] offset:2048 nt
	global_load_dwordx4 v[176:179], v1, s[8:9] offset:3072 nt
	s_add_u32 s8, s8, 0x1000
	s_addc_u32 s9, s9, 0
	global_load_dwordx4 v[180:183], v1, s[8:9] nt
	global_load_dwordx4 v[184:187], v1, s[8:9] offset:1024 nt
	global_load_dwordx4 v[188:191], v1, s[8:9] offset:2048 nt
	global_load_dwordx4 v[192:195], v1, s[8:9] offset:3072 nt
	s_add_u32 s8, s8, 0x1000
	s_addc_u32 s9, s9, 0
	global_load_dwordx4 v[196:199], v1, s[8:9] nt
	global_load_dwordx4 v[200:203], v1, s[8:9] offset:1024 nt
	global_load_dwordx4 v[204:207], v1, s[8:9] offset:2048 nt
	global_load_dwordx4 v[208:211], v1, s[8:9] offset:3072 nt
	s_add_u32 s8, s8, 0x1000
	s_addc_u32 s9, s9, 0
	global_load_dwordx4 v[212:215], v1, s[8:9] nt
	global_load_dwordx4 v[216:219], v1, s[8:9] offset:1024 nt
	global_load_dwordx4 v[220:223], v1, s[8:9] offset:2048 nt
	global_load_dwordx4 v[224:227], v1, s[8:9] offset:3072 nt
	s_add_u32 s8, s8, 0x1000
	s_addc_u32 s9, s9, 0
	s_waitcnt vmcnt(32)
	v_pk_add_f32 v[40:41], v[40:41], 1.0 op_sel_hi:[1,0]
	v_pk_add_f32 v[42:43], v[42:43], 1.0 op_sel_hi:[1,0]
	v_pk_add_f32 v[64:65], v[64:65], 1.0 op_sel_hi:[1,0]
	v_pk_add_f32 v[66:67], v[66:67], 1.0 op_sel_hi:[1,0]
	v_pk_add_f32 v[68:69], v[68:69], 1.0 op_sel_hi:[1,0]
	v_pk_add_f32 v[70:71], v[70:71], 1.0 op_sel_hi:[1,0]
	v_pk_add_f32 v[72:73], v[72:73], 1.0 op_sel_hi:[1,0]
	v_pk_add_f32 v[74:75], v[74:75], 1.0 op_sel_hi:[1,0]
	s_waitcnt vmcnt(16)
; DI unsigned pk2(float lo, float hi) { return f2bf(lo) | (f2bf(hi) << 16); }
; DI void norm_phase(const Args& A, int wave_s, int l, int which, int rows) {
;     ...
;             float ss = 0.f;
; #pragma unroll
;             for (int j = 0; j < 4; ++j) ss += (xv[rr][j].x * xv[rr][j].x + xv[rr][j].y * xv[rr][j].y) + (xv[rr][j].z * xv[rr][j].z + xv[rr][j].w * xv[rr][j].w);
;             ss = wave_sum(C.lane, ss);
;             const float rs = rsqrtf(ss * (1.f / 1024.f) + EPS);
; #pragma unroll
;             for (int j = 0; j < 4; ++j) { const int col = 4 * (C.lane + 64 * j);
;                 const f32x4 y = xv[rr][j] * rs * g[j] * (sc[j] + 1.f) + sh[j];
;                 v2u o; o.x = pk2(y.x, y.y); o.y = pk2(y.z, y.w);
;                 *(v2u*)(C.H + (size_t)m * 1024 + col) = o; }
	v_mul_f32_e32 v10, v96, v96
	v_fmac_f32_e32 v10, v97, v97
	v_fmac_f32_e32 v10, v98, v98
	v_fmac_f32_e32 v10, v99, v99
	v_fmac_f32_e32 v10, v100, v100
	v_fmac_f32_e32 v10, v101, v101
	v_fmac_f32_e32 v10, v102, v102
	v_fmac_f32_e32 v10, v103, v103
	v_fmac_f32_e32 v10, v104, v104
	v_fmac_f32_e32 v10, v105, v105
	v_fmac_f32_e32 v10, v106, v106
	v_fmac_f32_e32 v10, v107, v107
	v_fmac_f32_e32 v10, v108, v108
	v_fmac_f32_e32 v10, v109, v109
	v_fmac_f32_e32 v10, v110, v110
	v_fmac_f32_e32 v10, v111, v111
	v_mul_f32_e32 v11, v112, v112
	v_fmac_f32_e32 v11, v113, v113
	v_fmac_f32_e32 v11, v114, v114
	v_fmac_f32_e32 v11, v115, v115
	v_fmac_f32_e32 v11, v116, v116
	v_fmac_f32_e32 v11, v117, v117
	v_fmac_f32_e32 v11, v118, v118
	v_fmac_f32_e32 v11, v119, v119
	v_fmac_f32_e32 v11, v120, v120
	v_fmac_f32_e32 v11, v121, v121
	v_fmac_f32_e32 v11, v122, v122
	v_fmac_f32_e32 v11, v123, v123
	v_fmac_f32_e32 v11, v124, v124
	v_fmac_f32_e32 v11, v125, v125
	v_fmac_f32_e32 v11, v126, v126
	v_fmac_f32_e32 v11, v127, v127
	v_mul_f32_e32 v12, v128, v128
	v_fmac_f32_e32 v12, v129, v129
	v_fmac_f32_e32 v12, v130, v130
	v_fmac_f32_e32 v12, v131, v131
	v_fmac_f32_e32 v12, v132, v132
	v_fmac_f32_e32 v12, v133, v133
	v_fmac_f32_e32 v12, v134, v134
	v_fmac_f32_e32 v12, v135, v135
	v_fmac_f32_e32 v12, v136, v136
	v_fmac_f32_e32 v12, v137, v137
	v_fmac_f32_e32 v12, v138, v138
	v_fmac_f32_e32 v12, v139, v139
	v_fmac_f32_e32 v12, v140, v140
	v_fmac_f32_e32 v12, v141, v141
	v_fmac_f32_e32 v12, v142, v142
	v_fmac_f32_e32 v12, v143, v143
	v_mul_f32_e32 v13, v144, v144
	v_fmac_f32_e32 v13, v145, v145
	v_fmac_f32_e32 v13, v146, v146
	v_fmac_f32_e32 v13, v147, v147
	v_fmac_f32_e32 v13, v148, v148
	v_fmac_f32_e32 v13, v149, v149
	v_fmac_f32_e32 v13, v150, v150
	v_fmac_f32_e32 v13, v151, v151
	v_fmac_f32_e32 v13, v152, v152
	v_fmac_f32_e32 v13, v153, v153
	v_fmac_f32_e32 v13, v154, v154
	v_fmac_f32_e32 v13, v155, v155
	v_fmac_f32_e32 v13, v156, v156
	v_fmac_f32_e32 v13, v157, v157
	v_fmac_f32_e32 v13, v158, v158
	v_fmac_f32_e32 v13, v159, v159
	ds_bpermute_b32 v14, v4, v10
	ds_bpermute_b32 v15, v4, v11
	ds_bpermute_b32 v16, v4, v12
	ds_bpermute_b32 v17, v4, v13
	s_waitcnt lgkmcnt(0)
	v_add_f32_e32 v10, v10, v14
	v_add_f32_e32 v11, v11, v15
	v_add_f32_e32 v12, v12, v16
	v_add_f32_e32 v13, v13, v17
	ds_bpermute_b32 v14, v5, v10
	ds_bpermute_b32 v15, v5, v11
	ds_bpermute_b32 v16, v5, v12
	ds_bpermute_b32 v17, v5, v13
	s_waitcnt lgkmcnt(0)
	v_add_f32_e32 v10, v10, v14
	v_add_f32_e32 v11, v11, v15
	v_add_f32_e32 v12, v12, v16
	v_add_f32_e32 v13, v13, v17
	ds_bpermute_b32 v14, v6, v10
	ds_bpermute_b32 v15, v6, v11
	ds_bpermute_b32 v16, v6, v12
	ds_bpermute_b32 v17, v6, v13
	s_waitcnt lgkmcnt(0)
	v_add_f32_e32 v10, v10, v14
	v_add_f32_e32 v11, v11, v15
	v_add_f32_e32 v12, v12, v16
	v_add_f32_e32 v13, v13, v17
	ds_bpermute_b32 v14, v7, v10
	ds_bpermute_b32 v15, v7, v11
	ds_bpermute_b32 v16, v7, v12
	ds_bpermute_b32 v17, v7, v13
	s_waitcnt lgkmcnt(0)
	v_add_f32_e32 v10, v10, v14
	v_add_f32_e32 v11, v11, v15
	v_add_f32_e32 v12, v12, v16
	v_add_f32_e32 v13, v13, v17
	ds_bpermute_b32 v14, v8, v10
	ds_bpermute_b32 v15, v8, v11
	ds_bpermute_b32 v16, v8, v12
	ds_bpermute_b32 v17, v8, v13
	s_waitcnt lgkmcnt(0)
	v_add_f32_e32 v10, v10, v14
	v_add_f32_e32 v11, v11, v15
	v_add_f32_e32 v12, v12, v16
	v_add_f32_e32 v13, v13, v17
	ds_bpermute_b32 v14, v9, v10
	ds_bpermute_b32 v15, v9, v11
	ds_bpermute_b32 v16, v9, v12
	ds_bpermute_b32 v17, v9, v13
	s_waitcnt lgkmcnt(0)
	v_add_f32_e32 v10, v10, v14
	v_add_f32_e32 v11, v11, v15
	v_add_f32_e32 v12, v12, v16
	v_add_f32_e32 v13, v13, v17
	v_fma_f32 v10, v10, s32, v60
	v_fma_f32 v11, v11, s32, v60
	v_fma_f32 v12, v12, s32, v60
	v_fma_f32 v13, v13, s32, v60
	v_rsq_f32_e32 v18, v10
	v_rsq_f32_e32 v20, v11
	v_rsq_f32_e32 v22, v12
	v_rsq_f32_e32 v62, v13
	s_nop 0
	v_pk_mul_f32 v[96:97], v[96:97], v[18:19] op_sel_hi:[1,0]
	v_pk_mul_f32 v[98:99], v[98:99], v[18:19] op_sel_hi:[1,0]
	v_pk_mul_f32 v[100:101], v[100:101], v[18:19] op_sel_hi:[1,0]
	v_pk_mul_f32 v[102:103], v[102:103], v[18:19] op_sel_hi:[1,0]
	v_pk_mul_f32 v[104:105], v[104:105], v[18:19] op_sel_hi:[1,0]
	v_pk_mul_f32 v[106:107], v[106:107], v[18:19] op_sel_hi:[1,0]
	v_pk_mul_f32 v[108:109], v[108:109], v[18:19] op_sel_hi:[1,0]
	v_pk_mul_f32 v[110:111], v[110:111], v[18:19] op_sel_hi:[1,0]
	v_pk_mul_f32 v[96:97], v[24:25], v[96:97]
	v_pk_mul_f32 v[98:99], v[26:27], v[98:99]
	v_pk_mul_f32 v[100:101], v[28:29], v[100:101]
	v_pk_mul_f32 v[102:103], v[30:31], v[102:103]
	v_pk_mul_f32 v[104:105], v[32:33], v[104:105]
	v_pk_mul_f32 v[106:107], v[34:35], v[106:107]
	v_pk_mul_f32 v[108:109], v[36:37], v[108:109]
	v_pk_mul_f32 v[110:111], v[38:39], v[110:111]
	v_pk_fma_f32 v[96:97], v[40:41], v[96:97], v[80:81]
	v_pk_fma_f32 v[98:99], v[42:43], v[98:99], v[82:83]
	v_pk_fma_f32 v[100:101], v[64:65], v[100:101], v[84:85]
	v_pk_fma_f32 v[102:103], v[66:67], v[102:103], v[86:87]
	v_pk_fma_f32 v[104:105], v[68:69], v[104:105], v[88:89]
	v_pk_fma_f32 v[106:107], v[70:71], v[106:107], v[90:91]
	v_pk_fma_f32 v[108:109], v[72:73], v[108:109], v[92:93]
	v_pk_fma_f32 v[110:111], v[74:75], v[110:111], v[94:95]
	v_cvt_pk_bf16_f32 v96, v96, v97
	v_cvt_pk_bf16_f32 v97, v98, v99
	v_cvt_pk_bf16_f32 v100, v100, v101
	v_cvt_pk_bf16_f32 v101, v102, v103
	v_cvt_pk_bf16_f32 v104, v104, v105
	v_cvt_pk_bf16_f32 v105, v106, v107
	v_cvt_pk_bf16_f32 v108, v108, v109
	v_cvt_pk_bf16_f32 v109, v110, v111
	global_store_dwordx2 v2, v[96:97], s[10:11]
	global_store_dwordx2 v2, v[100:101], s[10:11] offset:512
	global_store_dwordx2 v2, v[104:105], s[10:11] offset:1024
	global_store_dwordx2 v2, v[108:109], s[10:11] offset:1536
	s_add_u32 s10, s10, 0x800
; DI unsigned pk2(float lo, float hi) { return f2bf(lo) | (f2bf(hi) << 16); }
; DI void norm_phase(const Args& A, int wave_s, int l, int which, int rows) {
;     ...
;         for (int rr = 0; rr < 2; ++rr) {
;             const int m = m0 + rr; const float* xr; int v;
;             if (m < NLAT) { xr = (from_in ? C.x : C.out) + (size_t)m * 1024; v = m >> 13; }
;             else { xr = (from_in ? C.ctx : C.XC) + (size_t)(m - NLAT) * 1024; v = 4; }
;             modp[rr] = C.SM + SM_MOD + (l * 5 + v) * 6144 + (which == 1 ? 0 : 3072);
; #pragma unroll
;             for (int j = 0; j < 4; ++j) xv[rr][j] = ((const f32x4*)xr)[C.lane + 64 * j];
;     ...
; #pragma unroll
;             for (int j = 0; j < 4; ++j) { const int col = 4 * (C.lane + 64 * j);
;                 const f32x4 y = xv[rr][j] * rs * g[j] * (sc[j] + 1.f) + sh[j];
;                 v2u o; o.x = pk2(y.x, y.y); o.y = pk2(y.z, y.w);
;                 *(v2u*)(C.H + (size_t)m * 1024 + col) = o; }
	s_addc_u32 s11, s11, 0
	v_pk_mul_f32 v[112:113], v[112:113], v[20:21] op_sel_hi:[1,0]
	v_pk_mul_f32 v[114:115], v[114:115], v[20:21] op_sel_hi:[1,0]
	v_pk_mul_f32 v[116:117], v[116:117], v[20:21] op_sel_hi:[1,0]
	v_pk_mul_f32 v[118:119], v[118:119], v[20:21] op_sel_hi:[1,0]
	v_pk_mul_f32 v[120:121], v[120:121], v[20:21] op_sel_hi:[1,0]
	v_pk_mul_f32 v[122:123], v[122:123], v[20:21] op_sel_hi:[1,0]
	v_pk_mul_f32 v[124:125], v[124:125], v[20:21] op_sel_hi:[1,0]
	v_pk_mul_f32 v[126:127], v[126:127], v[20:21] op_sel_hi:[1,0]
	v_pk_mul_f32 v[112:113], v[24:25], v[112:113]
	v_pk_mul_f32 v[114:115], v[26:27], v[114:115]
	v_pk_mul_f32 v[116:117], v[28:29], v[116:117]
	v_pk_mul_f32 v[118:119], v[30:31], v[118:119]
	v_pk_mul_f32 v[120:121], v[32:33], v[120:121]
	v_pk_mul_f32 v[122:123], v[34:35], v[122:123]
	v_pk_mul_f32 v[124:125], v[36:37], v[124:125]
	v_pk_mul_f32 v[126:127], v[38:39], v[126:127]
	v_pk_fma_f32 v[112:113], v[40:41], v[112:113], v[80:81]
	v_pk_fma_f32 v[114:115], v[42:43], v[114:115], v[82:83]
	v_pk_fma_f32 v[116:117], v[64:65], v[116:117], v[84:85]
	v_pk_fma_f32 v[118:119], v[66:67], v[118:119], v[86:87]
	v_pk_fma_f32 v[120:121], v[68:69], v[120:121], v[88:89]
	v_pk_fma_f32 v[122:123], v[70:71], v[122:123], v[90:91]
	v_pk_fma_f32 v[124:125], v[72:73], v[124:125], v[92:93]
	v_pk_fma_f32 v[126:127], v[74:75], v[126:127], v[94:95]
	v_cvt_pk_bf16_f32 v112, v112, v113
	v_cvt_pk_bf16_f32 v113, v114, v115
	v_cvt_pk_bf16_f32 v116, v116, v117
	v_cvt_pk_bf16_f32 v117, v118, v119
	v_cvt_pk_bf16_f32 v120, v120, v121
	v_cvt_pk_bf16_f32 v121, v122, v123
	v_cvt_pk_bf16_f32 v124, v124, v125
	v_cvt_pk_bf16_f32 v125, v126, v127
	global_store_dwordx2 v2, v[112:113], s[10:11]
	global_store_dwordx2 v2, v[116:117], s[10:11] offset:512
	global_store_dwordx2 v2, v[120:121], s[10:11] offset:1024
	global_store_dwordx2 v2, v[124:125], s[10:11] offset:1536
	s_add_u32 s10, s10, 0x800
	s_addc_u32 s11, s11, 0
	v_pk_mul_f32 v[128:129], v[128:129], v[22:23] op_sel_hi:[1,0]
	v_pk_mul_f32 v[130:131], v[130:131], v[22:23] op_sel_hi:[1,0]
	v_pk_mul_f32 v[132:133], v[132:133], v[22:23] op_sel_hi:[1,0]
	v_pk_mul_f32 v[134:135], v[134:135], v[22:23] op_sel_hi:[1,0]
	v_pk_mul_f32 v[136:137], v[136:137], v[22:23] op_sel_hi:[1,0]
	v_pk_mul_f32 v[138:139], v[138:139], v[22:23] op_sel_hi:[1,0]
	v_pk_mul_f32 v[140:141], v[140:141], v[22:23] op_sel_hi:[1,0]
	v_pk_mul_f32 v[142:143], v[142:143], v[22:23] op_sel_hi:[1,0]
	v_pk_mul_f32 v[128:129], v[24:25], v[128:129]
	v_pk_mul_f32 v[130:131], v[26:27], v[130:131]
	v_pk_mul_f32 v[132:133], v[28:29], v[132:133]
	v_pk_mul_f32 v[134:135], v[30:31], v[134:135]
	v_pk_mul_f32 v[136:137], v[32:33], v[136:137]
	v_pk_mul_f32 v[138:139], v[34:35], v[138:139]
	v_pk_mul_f32 v[140:141], v[36:37], v[140:141]
	v_pk_mul_f32 v[142:143], v[38:39], v[142:143]
	v_pk_fma_f32 v[128:129], v[40:41], v[128:129], v[80:81]
	v_pk_fma_f32 v[130:131], v[42:43], v[130:131], v[82:83]
	v_pk_fma_f32 v[132:133], v[64:65], v[132:133], v[84:85]
	v_pk_fma_f32 v[134:135], v[66:67], v[134:135], v[86:87]
	v_pk_fma_f32 v[136:137], v[68:69], v[136:137], v[88:89]
	v_pk_fma_f32 v[138:139], v[70:71], v[138:139], v[90:91]
	v_pk_fma_f32 v[140:141], v[72:73], v[140:141], v[92:93]
	v_pk_fma_f32 v[142:143], v[74:75], v[142:143], v[94:95]
	v_cvt_pk_bf16_f32 v128, v128, v129
	v_cvt_pk_bf16_f32 v129, v130, v131
	v_cvt_pk_bf16_f32 v132, v132, v133
	v_cvt_pk_bf16_f32 v133, v134, v135
	v_cvt_pk_bf16_f32 v136, v136, v137
	v_cvt_pk_bf16_f32 v137, v138, v139
	v_cvt_pk_bf16_f32 v140, v140, v141
	v_cvt_pk_bf16_f32 v141, v142, v143
	global_store_dwordx2 v2, v[128:129], s[10:11]
	global_store_dwordx2 v2, v[132:133], s[10:11] offset:512
	global_store_dwordx2 v2, v[136:137], s[10:11] offset:1024
	global_store_dwordx2 v2, v[140:141], s[10:11] offset:1536
	s_add_u32 s10, s10, 0x800
	s_addc_u32 s11, s11, 0
	v_pk_mul_f32 v[144:145], v[144:145], v[62:63] op_sel_hi:[1,0]
	v_pk_mul_f32 v[146:147], v[146:147], v[62:63] op_sel_hi:[1,0]
	v_pk_mul_f32 v[148:149], v[148:149], v[62:63] op_sel_hi:[1,0]
	v_pk_mul_f32 v[150:151], v[150:151], v[62:63] op_sel_hi:[1,0]
	v_pk_mul_f32 v[152:153], v[152:153], v[62:63] op_sel_hi:[1,0]
	v_pk_mul_f32 v[154:155], v[154:155], v[62:63] op_sel_hi:[1,0]
	v_pk_mul_f32 v[156:157], v[156:157], v[62:63] op_sel_hi:[1,0]
	v_pk_mul_f32 v[158:159], v[158:159], v[62:63] op_sel_hi:[1,0]
	v_pk_mul_f32 v[144:145], v[24:25], v[144:145]
	v_pk_mul_f32 v[146:147], v[26:27], v[146:147]
	v_pk_mul_f32 v[148:149], v[28:29], v[148:149]
	v_pk_mul_f32 v[150:151], v[30:31], v[150:151]
	v_pk_mul_f32 v[152:153], v[32:33], v[152:153]
	v_pk_mul_f32 v[154:155], v[34:35], v[154:155]
	v_pk_mul_f32 v[156:157], v[36:37], v[156:157]
	v_pk_mul_f32 v[158:159], v[38:39], v[158:159]
	v_pk_fma_f32 v[144:145], v[40:41], v[144:145], v[80:81]
	v_pk_fma_f32 v[146:147], v[42:43], v[146:147], v[82:83]
	v_pk_fma_f32 v[148:149], v[64:65], v[148:149], v[84:85]
	v_pk_fma_f32 v[150:151], v[66:67], v[150:151], v[86:87]
	v_pk_fma_f32 v[152:153], v[68:69], v[152:153], v[88:89]
	v_pk_fma_f32 v[154:155], v[70:71], v[154:155], v[90:91]
	v_pk_fma_f32 v[156:157], v[72:73], v[156:157], v[92:93]
	v_pk_fma_f32 v[158:159], v[74:75], v[158:159], v[94:95]
	v_cvt_pk_bf16_f32 v144, v144, v145
	v_cvt_pk_bf16_f32 v145, v146, v147
	v_cvt_pk_bf16_f32 v148, v148, v149
	v_cvt_pk_bf16_f32 v149, v150, v151
	v_cvt_pk_bf16_f32 v152, v152, v153
	v_cvt_pk_bf16_f32 v153, v154, v155
	v_cvt_pk_bf16_f32 v156, v156, v157
	v_cvt_pk_bf16_f32 v157, v158, v159
	global_store_dwordx2 v2, v[144:145], s[10:11]
	global_store_dwordx2 v2, v[148:149], s[10:11] offset:512
	global_store_dwordx2 v2, v[152:153], s[10:11] offset:1024
	global_store_dwordx2 v2, v[156:157], s[10:11] offset:1536
	s_add_u32 s10, s10, 0x800
	s_addc_u32 s11, s11, 0
	global_load_dwordx4 v[96:99], v1, s[8:9] nt
	global_load_dwordx4 v[100:103], v1, s[8:9] offset:1024 nt
	global_load_dwordx4 v[104:107], v1, s[8:9] offset:2048 nt
	global_load_dwordx4 v[108:111], v1, s[8:9] offset:3072 nt
	s_add_u32 s8, s8, 0x1000
	s_addc_u32 s9, s9, 0
	global_load_dwordx4 v[112:115], v1, s[8:9] nt
	global_load_dwordx4 v[116:119], v1, s[8:9] offset:1024 nt
	global_load_dwordx4 v[120:123], v1, s[8:9] offset:2048 nt
	global_load_dwordx4 v[124:127], v1, s[8:9] offset:3072 nt
	s_add_u32 s8, s8, 0x1000
	s_addc_u32 s9, s9, 0
	global_load_dwordx4 v[128:131], v1, s[8:9] nt
	global_load_dwordx4 v[132:135], v1, s[8:9] offset:1024 nt
	global_load_dwordx4 v[136:139], v1, s[8:9] offset:2048 nt
	global_load_dwordx4 v[140:143], v1, s[8:9] offset:3072 nt
	s_add_u32 s8, s8, 0x1000
	s_addc_u32 s9, s9, 0
	global_load_dwordx4 v[144:147], v1, s[8:9] nt
	global_load_dwordx4 v[148:151], v1, s[8:9] offset:1024 nt
	global_load_dwordx4 v[152:155], v1, s[8:9] offset:2048 nt
	global_load_dwordx4 v[156:159], v1, s[8:9] offset:3072 nt
	s_add_u32 s8, s8, 0x1000
	s_addc_u32 s9, s9, 0
	s_waitcnt vmcnt(32)
; DI unsigned pk2(float lo, float hi) { return f2bf(lo) | (f2bf(hi) << 16); }
; DI void norm_phase(const Args& A, int wave_s, int l, int which, int rows) {
;     ...
;             float ss = 0.f;
; #pragma unroll
;             for (int j = 0; j < 4; ++j) ss += (xv[rr][j].x * xv[rr][j].x + xv[rr][j].y * xv[rr][j].y) + (xv[rr][j].z * xv[rr][j].z + xv[rr][j].w * xv[rr][j].w);
;             ss = wave_sum(C.lane, ss);
;             const float rs = rsqrtf(ss * (1.f / 1024.f) + EPS);
; #pragma unroll
;             for (int j = 0; j < 4; ++j) { const int col = 4 * (C.lane + 64 * j);
;                 const f32x4 y = xv[rr][j] * rs * g[j] * (sc[j] + 1.f) + sh[j];
;                 v2u o; o.x = pk2(y.x, y.y); o.y = pk2(y.z, y.w);
;                 *(v2u*)(C.H + (size_t)m * 1024 + col) = o; }
	v_mul_f32_e32 v10, v164, v164
	v_fmac_f32_e32 v10, v165, v165
	v_fmac_f32_e32 v10, v166, v166
	v_fmac_f32_e32 v10, v167, v167
	v_fmac_f32_e32 v10, v168, v168
	v_fmac_f32_e32 v10, v169, v169
	v_fmac_f32_e32 v10, v170, v170
	v_fmac_f32_e32 v10, v171, v171
	v_fmac_f32_e32 v10, v172, v172
	v_fmac_f32_e32 v10, v173, v173
	v_fmac_f32_e32 v10, v174, v174
	v_fmac_f32_e32 v10, v175, v175
	v_fmac_f32_e32 v10, v176, v176
	v_fmac_f32_e32 v10, v177, v177
	v_fmac_f32_e32 v10, v178, v178
	v_fmac_f32_e32 v10, v179, v179
	v_mul_f32_e32 v11, v180, v180
	v_fmac_f32_e32 v11, v181, v181
	v_fmac_f32_e32 v11, v182, v182
	v_fmac_f32_e32 v11, v183, v183
	v_fmac_f32_e32 v11, v184, v184
	v_fmac_f32_e32 v11, v185, v185
	v_fmac_f32_e32 v11, v186, v186
	v_fmac_f32_e32 v11, v187, v187
	v_fmac_f32_e32 v11, v188, v188
	v_fmac_f32_e32 v11, v189, v189
	v_fmac_f32_e32 v11, v190, v190
	v_fmac_f32_e32 v11, v191, v191
	v_fmac_f32_e32 v11, v192, v192
	v_fmac_f32_e32 v11, v193, v193
	v_fmac_f32_e32 v11, v194, v194
	v_fmac_f32_e32 v11, v195, v195
	v_mul_f32_e32 v12, v196, v196
	v_fmac_f32_e32 v12, v197, v197
	v_fmac_f32_e32 v12, v198, v198
	v_fmac_f32_e32 v12, v199, v199
	v_fmac_f32_e32 v12, v200, v200
	v_fmac_f32_e32 v12, v201, v201
	v_fmac_f32_e32 v12, v202, v202
	v_fmac_f32_e32 v12, v203, v203
	v_fmac_f32_e32 v12, v204, v204
	v_fmac_f32_e32 v12, v205, v205
	v_fmac_f32_e32 v12, v206, v206
	v_fmac_f32_e32 v12, v207, v207
	v_fmac_f32_e32 v12, v208, v208
	v_fmac_f32_e32 v12, v209, v209
	v_fmac_f32_e32 v12, v210, v210
	v_fmac_f32_e32 v12, v211, v211
	v_mul_f32_e32 v13, v212, v212
	v_fmac_f32_e32 v13, v213, v213
	v_fmac_f32_e32 v13, v214, v214
	v_fmac_f32_e32 v13, v215, v215
	v_fmac_f32_e32 v13, v216, v216
	v_fmac_f32_e32 v13, v217, v217
	v_fmac_f32_e32 v13, v218, v218
	v_fmac_f32_e32 v13, v219, v219
	v_fmac_f32_e32 v13, v220, v220
	v_fmac_f32_e32 v13, v221, v221
	v_fmac_f32_e32 v13, v222, v222
	v_fmac_f32_e32 v13, v223, v223
	v_fmac_f32_e32 v13, v224, v224
	v_fmac_f32_e32 v13, v225, v225
	v_fmac_f32_e32 v13, v226, v226
	v_fmac_f32_e32 v13, v227, v227
	ds_bpermute_b32 v14, v4, v10
	ds_bpermute_b32 v15, v4, v11
	ds_bpermute_b32 v16, v4, v12
	ds_bpermute_b32 v17, v4, v13
	s_waitcnt lgkmcnt(0)
	v_add_f32_e32 v10, v10, v14
	v_add_f32_e32 v11, v11, v15
	v_add_f32_e32 v12, v12, v16
	v_add_f32_e32 v13, v13, v17
	ds_bpermute_b32 v14, v5, v10
	ds_bpermute_b32 v15, v5, v11
	ds_bpermute_b32 v16, v5, v12
	ds_bpermute_b32 v17, v5, v13
	s_waitcnt lgkmcnt(0)
	v_add_f32_e32 v10, v10, v14
	v_add_f32_e32 v11, v11, v15
	v_add_f32_e32 v12, v12, v16
	v_add_f32_e32 v13, v13, v17
	ds_bpermute_b32 v14, v6, v10
	ds_bpermute_b32 v15, v6, v11
	ds_bpermute_b32 v16, v6, v12
	ds_bpermute_b32 v17, v6, v13
	s_waitcnt lgkmcnt(0)
	v_add_f32_e32 v10, v10, v14
	v_add_f32_e32 v11, v11, v15
	v_add_f32_e32 v12, v12, v16
	v_add_f32_e32 v13, v13, v17
	ds_bpermute_b32 v14, v7, v10
	ds_bpermute_b32 v15, v7, v11
	ds_bpermute_b32 v16, v7, v12
	ds_bpermute_b32 v17, v7, v13
	s_waitcnt lgkmcnt(0)
	v_add_f32_e32 v10, v10, v14
	v_add_f32_e32 v11, v11, v15
	v_add_f32_e32 v12, v12, v16
	v_add_f32_e32 v13, v13, v17
	ds_bpermute_b32 v14, v8, v10
	ds_bpermute_b32 v15, v8, v11
	ds_bpermute_b32 v16, v8, v12
	ds_bpermute_b32 v17, v8, v13
	s_waitcnt lgkmcnt(0)
	v_add_f32_e32 v10, v10, v14
	v_add_f32_e32 v11, v11, v15
	v_add_f32_e32 v12, v12, v16
	v_add_f32_e32 v13, v13, v17
	ds_bpermute_b32 v14, v9, v10
	ds_bpermute_b32 v15, v9, v11
	ds_bpermute_b32 v16, v9, v12
	ds_bpermute_b32 v17, v9, v13
	s_waitcnt lgkmcnt(0)
	v_add_f32_e32 v10, v10, v14
	v_add_f32_e32 v11, v11, v15
	v_add_f32_e32 v12, v12, v16
	v_add_f32_e32 v13, v13, v17
	v_fma_f32 v10, v10, s32, v60
	v_fma_f32 v11, v11, s32, v60
	v_fma_f32 v12, v12, s32, v60
	v_fma_f32 v13, v13, s32, v60
	v_rsq_f32_e32 v18, v10
	v_rsq_f32_e32 v20, v11
	v_rsq_f32_e32 v22, v12
	v_rsq_f32_e32 v62, v13
	s_nop 0
	v_pk_mul_f32 v[164:165], v[164:165], v[18:19] op_sel_hi:[1,0]
	v_pk_mul_f32 v[166:167], v[166:167], v[18:19] op_sel_hi:[1,0]
	v_pk_mul_f32 v[168:169], v[168:169], v[18:19] op_sel_hi:[1,0]
	v_pk_mul_f32 v[170:171], v[170:171], v[18:19] op_sel_hi:[1,0]
	v_pk_mul_f32 v[172:173], v[172:173], v[18:19] op_sel_hi:[1,0]
	v_pk_mul_f32 v[174:175], v[174:175], v[18:19] op_sel_hi:[1,0]
	v_pk_mul_f32 v[176:177], v[176:177], v[18:19] op_sel_hi:[1,0]
	v_pk_mul_f32 v[178:179], v[178:179], v[18:19] op_sel_hi:[1,0]
	v_pk_mul_f32 v[164:165], v[24:25], v[164:165]
	v_pk_mul_f32 v[166:167], v[26:27], v[166:167]
	v_pk_mul_f32 v[168:169], v[28:29], v[168:169]
	v_pk_mul_f32 v[170:171], v[30:31], v[170:171]
	v_pk_mul_f32 v[172:173], v[32:33], v[172:173]
	v_pk_mul_f32 v[174:175], v[34:35], v[174:175]
	v_pk_mul_f32 v[176:177], v[36:37], v[176:177]
	v_pk_mul_f32 v[178:179], v[38:39], v[178:179]
	v_pk_fma_f32 v[164:165], v[40:41], v[164:165], v[80:81]
	v_pk_fma_f32 v[166:167], v[42:43], v[166:167], v[82:83]
	v_pk_fma_f32 v[168:169], v[64:65], v[168:169], v[84:85]
	v_pk_fma_f32 v[170:171], v[66:67], v[170:171], v[86:87]
	v_pk_fma_f32 v[172:173], v[68:69], v[172:173], v[88:89]
	v_pk_fma_f32 v[174:175], v[70:71], v[174:175], v[90:91]
	v_pk_fma_f32 v[176:177], v[72:73], v[176:177], v[92:93]
	v_pk_fma_f32 v[178:179], v[74:75], v[178:179], v[94:95]
	v_cvt_pk_bf16_f32 v164, v164, v165
	v_cvt_pk_bf16_f32 v165, v166, v167
	v_cvt_pk_bf16_f32 v168, v168, v169
	v_cvt_pk_bf16_f32 v169, v170, v171
	v_cvt_pk_bf16_f32 v172, v172, v173
	v_cvt_pk_bf16_f32 v173, v174, v175
	v_cvt_pk_bf16_f32 v176, v176, v177
	v_cvt_pk_bf16_f32 v177, v178, v179
	global_store_dwordx2 v2, v[164:165], s[10:11]
	global_store_dwordx2 v2, v[168:169], s[10:11] offset:512
	global_store_dwordx2 v2, v[172:173], s[10:11] offset:1024
	global_store_dwordx2 v2, v[176:177], s[10:11] offset:1536
; DI unsigned pk2(float lo, float hi) { return f2bf(lo) | (f2bf(hi) << 16); }
; DI void norm_phase(const Args& A, int wave_s, int l, int which, int rows) {
;     ...
;         for (int rr = 0; rr < 2; ++rr) {
;             const int m = m0 + rr; const float* xr; int v;
;             if (m < NLAT) { xr = (from_in ? C.x : C.out) + (size_t)m * 1024; v = m >> 13; }
;             else { xr = (from_in ? C.ctx : C.XC) + (size_t)(m - NLAT) * 1024; v = 4; }
;             modp[rr] = C.SM + SM_MOD + (l * 5 + v) * 6144 + (which == 1 ? 0 : 3072);
; #pragma unroll
;             for (int j = 0; j < 4; ++j) xv[rr][j] = ((const f32x4*)xr)[C.lane + 64 * j];
;     ...
; #pragma unroll
;             for (int j = 0; j < 4; ++j) { const int col = 4 * (C.lane + 64 * j);
;                 const f32x4 y = xv[rr][j] * rs * g[j] * (sc[j] + 1.f) + sh[j];
;                 v2u o; o.x = pk2(y.x, y.y); o.y = pk2(y.z, y.w);
;                 *(v2u*)(C.H + (size_t)m * 1024 + col) = o; }
	s_add_u32 s10, s10, 0x800
	s_addc_u32 s11, s11, 0
	v_pk_mul_f32 v[180:181], v[180:181], v[20:21] op_sel_hi:[1,0]
	v_pk_mul_f32 v[182:183], v[182:183], v[20:21] op_sel_hi:[1,0]
	v_pk_mul_f32 v[184:185], v[184:185], v[20:21] op_sel_hi:[1,0]
	v_pk_mul_f32 v[186:187], v[186:187], v[20:21] op_sel_hi:[1,0]
	v_pk_mul_f32 v[188:189], v[188:189], v[20:21] op_sel_hi:[1,0]
	v_pk_mul_f32 v[190:191], v[190:191], v[20:21] op_sel_hi:[1,0]
	v_pk_mul_f32 v[192:193], v[192:193], v[20:21] op_sel_hi:[1,0]
	v_pk_mul_f32 v[194:195], v[194:195], v[20:21] op_sel_hi:[1,0]
	v_pk_mul_f32 v[180:181], v[24:25], v[180:181]
	v_pk_mul_f32 v[182:183], v[26:27], v[182:183]
	v_pk_mul_f32 v[184:185], v[28:29], v[184:185]
	v_pk_mul_f32 v[186:187], v[30:31], v[186:187]
	v_pk_mul_f32 v[188:189], v[32:33], v[188:189]
	v_pk_mul_f32 v[190:191], v[34:35], v[190:191]
	v_pk_mul_f32 v[192:193], v[36:37], v[192:193]
	v_pk_mul_f32 v[194:195], v[38:39], v[194:195]
	v_pk_fma_f32 v[180:181], v[40:41], v[180:181], v[80:81]
	v_pk_fma_f32 v[182:183], v[42:43], v[182:183], v[82:83]
	v_pk_fma_f32 v[184:185], v[64:65], v[184:185], v[84:85]
	v_pk_fma_f32 v[186:187], v[66:67], v[186:187], v[86:87]
	v_pk_fma_f32 v[188:189], v[68:69], v[188:189], v[88:89]
	v_pk_fma_f32 v[190:191], v[70:71], v[190:191], v[90:91]
	v_pk_fma_f32 v[192:193], v[72:73], v[192:193], v[92:93]
	v_pk_fma_f32 v[194:195], v[74:75], v[194:195], v[94:95]
	v_cvt_pk_bf16_f32 v180, v180, v181
	v_cvt_pk_bf16_f32 v181, v182, v183
	v_cvt_pk_bf16_f32 v184, v184, v185
	v_cvt_pk_bf16_f32 v185, v186, v187
	v_cvt_pk_bf16_f32 v188, v188, v189
	v_cvt_pk_bf16_f32 v189, v190, v191
	v_cvt_pk_bf16_f32 v192, v192, v193
	v_cvt_pk_bf16_f32 v193, v194, v195
	global_store_dwordx2 v2, v[180:181], s[10:11]
	global_store_dwordx2 v2, v[184:185], s[10:11] offset:512
	global_store_dwordx2 v2, v[188:189], s[10:11] offset:1024
	global_store_dwordx2 v2, v[192:193], s[10:11] offset:1536
	s_add_u32 s10, s10, 0x800
	s_addc_u32 s11, s11, 0
	v_pk_mul_f32 v[196:197], v[196:197], v[22:23] op_sel_hi:[1,0]
	v_pk_mul_f32 v[198:199], v[198:199], v[22:23] op_sel_hi:[1,0]
	v_pk_mul_f32 v[200:201], v[200:201], v[22:23] op_sel_hi:[1,0]
	v_pk_mul_f32 v[202:203], v[202:203], v[22:23] op_sel_hi:[1,0]
	v_pk_mul_f32 v[204:205], v[204:205], v[22:23] op_sel_hi:[1,0]
	v_pk_mul_f32 v[206:207], v[206:207], v[22:23] op_sel_hi:[1,0]
	v_pk_mul_f32 v[208:209], v[208:209], v[22:23] op_sel_hi:[1,0]
	v_pk_mul_f32 v[210:211], v[210:211], v[22:23] op_sel_hi:[1,0]
	v_pk_mul_f32 v[196:197], v[24:25], v[196:197]
	v_pk_mul_f32 v[198:199], v[26:27], v[198:199]
	v_pk_mul_f32 v[200:201], v[28:29], v[200:201]
	v_pk_mul_f32 v[202:203], v[30:31], v[202:203]
	v_pk_mul_f32 v[204:205], v[32:33], v[204:205]
	v_pk_mul_f32 v[206:207], v[34:35], v[206:207]
	v_pk_mul_f32 v[208:209], v[36:37], v[208:209]
	v_pk_mul_f32 v[210:211], v[38:39], v[210:211]
	v_pk_fma_f32 v[196:197], v[40:41], v[196:197], v[80:81]
	v_pk_fma_f32 v[198:199], v[42:43], v[198:199], v[82:83]
	v_pk_fma_f32 v[200:201], v[64:65], v[200:201], v[84:85]
	v_pk_fma_f32 v[202:203], v[66:67], v[202:203], v[86:87]
	v_pk_fma_f32 v[204:205], v[68:69], v[204:205], v[88:89]
	v_pk_fma_f32 v[206:207], v[70:71], v[206:207], v[90:91]
	v_pk_fma_f32 v[208:209], v[72:73], v[208:209], v[92:93]
	v_pk_fma_f32 v[210:211], v[74:75], v[210:211], v[94:95]
	v_cvt_pk_bf16_f32 v196, v196, v197
	v_cvt_pk_bf16_f32 v197, v198, v199
	v_cvt_pk_bf16_f32 v200, v200, v201
	v_cvt_pk_bf16_f32 v201, v202, v203
	v_cvt_pk_bf16_f32 v204, v204, v205
	v_cvt_pk_bf16_f32 v205, v206, v207
	v_cvt_pk_bf16_f32 v208, v208, v209
	v_cvt_pk_bf16_f32 v209, v210, v211
	global_store_dwordx2 v2, v[196:197], s[10:11]
	global_store_dwordx2 v2, v[200:201], s[10:11] offset:512
	global_store_dwordx2 v2, v[204:205], s[10:11] offset:1024
	global_store_dwordx2 v2, v[208:209], s[10:11] offset:1536
	s_add_u32 s10, s10, 0x800
	s_addc_u32 s11, s11, 0
	v_pk_mul_f32 v[212:213], v[212:213], v[62:63] op_sel_hi:[1,0]
	v_pk_mul_f32 v[214:215], v[214:215], v[62:63] op_sel_hi:[1,0]
	v_pk_mul_f32 v[216:217], v[216:217], v[62:63] op_sel_hi:[1,0]
	v_pk_mul_f32 v[218:219], v[218:219], v[62:63] op_sel_hi:[1,0]
	v_pk_mul_f32 v[220:221], v[220:221], v[62:63] op_sel_hi:[1,0]
	v_pk_mul_f32 v[222:223], v[222:223], v[62:63] op_sel_hi:[1,0]
	v_pk_mul_f32 v[224:225], v[224:225], v[62:63] op_sel_hi:[1,0]
	v_pk_mul_f32 v[226:227], v[226:227], v[62:63] op_sel_hi:[1,0]
	v_pk_mul_f32 v[212:213], v[24:25], v[212:213]
	v_pk_mul_f32 v[214:215], v[26:27], v[214:215]
	v_pk_mul_f32 v[216:217], v[28:29], v[216:217]
	v_pk_mul_f32 v[218:219], v[30:31], v[218:219]
	v_pk_mul_f32 v[220:221], v[32:33], v[220:221]
	v_pk_mul_f32 v[222:223], v[34:35], v[222:223]
	v_pk_mul_f32 v[224:225], v[36:37], v[224:225]
	v_pk_mul_f32 v[226:227], v[38:39], v[226:227]
	v_pk_fma_f32 v[212:213], v[40:41], v[212:213], v[80:81]
	v_pk_fma_f32 v[214:215], v[42:43], v[214:215], v[82:83]
	v_pk_fma_f32 v[216:217], v[64:65], v[216:217], v[84:85]
	v_pk_fma_f32 v[218:219], v[66:67], v[218:219], v[86:87]
	v_pk_fma_f32 v[220:221], v[68:69], v[220:221], v[88:89]
	v_pk_fma_f32 v[222:223], v[70:71], v[222:223], v[90:91]
	v_pk_fma_f32 v[224:225], v[72:73], v[224:225], v[92:93]
	v_pk_fma_f32 v[226:227], v[74:75], v[226:227], v[94:95]
	v_cvt_pk_bf16_f32 v212, v212, v213
	v_cvt_pk_bf16_f32 v213, v214, v215
	v_cvt_pk_bf16_f32 v216, v216, v217
	v_cvt_pk_bf16_f32 v217, v218, v219
	v_cvt_pk_bf16_f32 v220, v220, v221
	v_cvt_pk_bf16_f32 v221, v222, v223
	v_cvt_pk_bf16_f32 v224, v224, v225
	v_cvt_pk_bf16_f32 v225, v226, v227
	global_store_dwordx2 v2, v[212:213], s[10:11]
	global_store_dwordx2 v2, v[216:217], s[10:11] offset:512
	global_store_dwordx2 v2, v[220:221], s[10:11] offset:1024
	global_store_dwordx2 v2, v[224:225], s[10:11] offset:1536
	s_add_u32 s10, s10, 0x800
	s_addc_u32 s11, s11, 0
	global_load_dwordx4 v[164:167], v1, s[8:9] nt
	global_load_dwordx4 v[168:171], v1, s[8:9] offset:1024 nt
	global_load_dwordx4 v[172:175], v1, s[8:9] offset:2048 nt
	global_load_dwordx4 v[176:179], v1, s[8:9] offset:3072 nt
	s_add_u32 s8, s8, 0x1000
	s_addc_u32 s9, s9, 0
	global_load_dwordx4 v[180:183], v1, s[8:9] nt
	global_load_dwordx4 v[184:187], v1, s[8:9] offset:1024 nt
	global_load_dwordx4 v[188:191], v1, s[8:9] offset:2048 nt
	global_load_dwordx4 v[192:195], v1, s[8:9] offset:3072 nt
	s_add_u32 s8, s8, 0x1000
	s_addc_u32 s9, s9, 0
	global_load_dwordx4 v[196:199], v1, s[8:9] nt
	global_load_dwordx4 v[200:203], v1, s[8:9] offset:1024 nt
	global_load_dwordx4 v[204:207], v1, s[8:9] offset:2048 nt
	global_load_dwordx4 v[208:211], v1, s[8:9] offset:3072 nt
	s_add_u32 s8, s8, 0x1000
	s_addc_u32 s9, s9, 0
	global_load_dwordx4 v[212:215], v1, s[8:9] nt
	global_load_dwordx4 v[216:219], v1, s[8:9] offset:1024 nt
	global_load_dwordx4 v[220:223], v1, s[8:9] offset:2048 nt
	global_load_dwordx4 v[224:227], v1, s[8:9] offset:3072 nt
	s_add_u32 s8, s8, 0x1000
	s_addc_u32 s9, s9, 0
	s_waitcnt vmcnt(32)
; DI unsigned pk2(float lo, float hi) { return f2bf(lo) | (f2bf(hi) << 16); }
; DI void norm_phase(const Args& A, int wave_s, int l, int which, int rows) {
;     ...
;             float ss = 0.f;
; #pragma unroll
;             for (int j = 0; j < 4; ++j) ss += (xv[rr][j].x * xv[rr][j].x + xv[rr][j].y * xv[rr][j].y) + (xv[rr][j].z * xv[rr][j].z + xv[rr][j].w * xv[rr][j].w);
;             ss = wave_sum(C.lane, ss);
;             const float rs = rsqrtf(ss * (1.f / 1024.f) + EPS);
; #pragma unroll
;             for (int j = 0; j < 4; ++j) { const int col = 4 * (C.lane + 64 * j);
;                 const f32x4 y = xv[rr][j] * rs * g[j] * (sc[j] + 1.f) + sh[j];
;                 v2u o; o.x = pk2(y.x, y.y); o.y = pk2(y.z, y.w);
;                 *(v2u*)(C.H + (size_t)m * 1024 + col) = o; }
	v_mul_f32_e32 v10, v96, v96
	v_fmac_f32_e32 v10, v97, v97
	v_fmac_f32_e32 v10, v98, v98
	v_fmac_f32_e32 v10, v99, v99
	v_fmac_f32_e32 v10, v100, v100
	v_fmac_f32_e32 v10, v101, v101
	v_fmac_f32_e32 v10, v102, v102
	v_fmac_f32_e32 v10, v103, v103
	v_fmac_f32_e32 v10, v104, v104
	v_fmac_f32_e32 v10, v105, v105
	v_fmac_f32_e32 v10, v106, v106
	v_fmac_f32_e32 v10, v107, v107
	v_fmac_f32_e32 v10, v108, v108
	v_fmac_f32_e32 v10, v109, v109
	v_fmac_f32_e32 v10, v110, v110
	v_fmac_f32_e32 v10, v111, v111
	v_mul_f32_e32 v11, v112, v112
	v_fmac_f32_e32 v11, v113, v113
	v_fmac_f32_e32 v11, v114, v114
	v_fmac_f32_e32 v11, v115, v115
	v_fmac_f32_e32 v11, v116, v116
	v_fmac_f32_e32 v11, v117, v117
	v_fmac_f32_e32 v11, v118, v118
	v_fmac_f32_e32 v11, v119, v119
	v_fmac_f32_e32 v11, v120, v120
	v_fmac_f32_e32 v11, v121, v121
	v_fmac_f32_e32 v11, v122, v122
	v_fmac_f32_e32 v11, v123, v123
	v_fmac_f32_e32 v11, v124, v124
	v_fmac_f32_e32 v11, v125, v125
	v_fmac_f32_e32 v11, v126, v126
	v_fmac_f32_e32 v11, v127, v127
	v_mul_f32_e32 v12, v128, v128
	v_fmac_f32_e32 v12, v129, v129
	v_fmac_f32_e32 v12, v130, v130
	v_fmac_f32_e32 v12, v131, v131
	v_fmac_f32_e32 v12, v132, v132
	v_fmac_f32_e32 v12, v133, v133
	v_fmac_f32_e32 v12, v134, v134
	v_fmac_f32_e32 v12, v135, v135
	v_fmac_f32_e32 v12, v136, v136
	v_fmac_f32_e32 v12, v137, v137
	v_fmac_f32_e32 v12, v138, v138
	v_fmac_f32_e32 v12, v139, v139
	v_fmac_f32_e32 v12, v140, v140
	v_fmac_f32_e32 v12, v141, v141
	v_fmac_f32_e32 v12, v142, v142
	v_fmac_f32_e32 v12, v143, v143
	v_mul_f32_e32 v13, v144, v144
	v_fmac_f32_e32 v13, v145, v145
	v_fmac_f32_e32 v13, v146, v146
	v_fmac_f32_e32 v13, v147, v147
	v_fmac_f32_e32 v13, v148, v148
	v_fmac_f32_e32 v13, v149, v149
	v_fmac_f32_e32 v13, v150, v150
	v_fmac_f32_e32 v13, v151, v151
	v_fmac_f32_e32 v13, v152, v152
	v_fmac_f32_e32 v13, v153, v153
	v_fmac_f32_e32 v13, v154, v154
	v_fmac_f32_e32 v13, v155, v155
	v_fmac_f32_e32 v13, v156, v156
	v_fmac_f32_e32 v13, v157, v157
	v_fmac_f32_e32 v13, v158, v158
	v_fmac_f32_e32 v13, v159, v159
	ds_bpermute_b32 v14, v4, v10
	ds_bpermute_b32 v15, v4, v11
	ds_bpermute_b32 v16, v4, v12
	ds_bpermute_b32 v17, v4, v13
	s_waitcnt lgkmcnt(0)
	v_add_f32_e32 v10, v10, v14
	v_add_f32_e32 v11, v11, v15
	v_add_f32_e32 v12, v12, v16
	v_add_f32_e32 v13, v13, v17
	ds_bpermute_b32 v14, v5, v10
	ds_bpermute_b32 v15, v5, v11
	ds_bpermute_b32 v16, v5, v12
	ds_bpermute_b32 v17, v5, v13
	s_waitcnt lgkmcnt(0)
	v_add_f32_e32 v10, v10, v14
	v_add_f32_e32 v11, v11, v15
	v_add_f32_e32 v12, v12, v16
	v_add_f32_e32 v13, v13, v17
	ds_bpermute_b32 v14, v6, v10
	ds_bpermute_b32 v15, v6, v11
	ds_bpermute_b32 v16, v6, v12
	ds_bpermute_b32 v17, v6, v13
	s_waitcnt lgkmcnt(0)
	v_add_f32_e32 v10, v10, v14
	v_add_f32_e32 v11, v11, v15
	v_add_f32_e32 v12, v12, v16
	v_add_f32_e32 v13, v13, v17
	ds_bpermute_b32 v14, v7, v10
	ds_bpermute_b32 v15, v7, v11
	ds_bpermute_b32 v16, v7, v12
	ds_bpermute_b32 v17, v7, v13
	s_waitcnt lgkmcnt(0)
	v_add_f32_e32 v10, v10, v14
	v_add_f32_e32 v11, v11, v15
	v_add_f32_e32 v12, v12, v16
	v_add_f32_e32 v13, v13, v17
	ds_bpermute_b32 v14, v8, v10
	ds_bpermute_b32 v15, v8, v11
	ds_bpermute_b32 v16, v8, v12
	ds_bpermute_b32 v17, v8, v13
	s_waitcnt lgkmcnt(0)
	v_add_f32_e32 v10, v10, v14
	v_add_f32_e32 v11, v11, v15
	v_add_f32_e32 v12, v12, v16
	v_add_f32_e32 v13, v13, v17
	ds_bpermute_b32 v14, v9, v10
	ds_bpermute_b32 v15, v9, v11
	ds_bpermute_b32 v16, v9, v12
	ds_bpermute_b32 v17, v9, v13
	s_waitcnt lgkmcnt(0)
	v_add_f32_e32 v10, v10, v14
	v_add_f32_e32 v11, v11, v15
	v_add_f32_e32 v12, v12, v16
	v_add_f32_e32 v13, v13, v17
	v_fma_f32 v10, v10, s32, v60
	v_fma_f32 v11, v11, s32, v60
	v_fma_f32 v12, v12, s32, v60
	v_fma_f32 v13, v13, s32, v60
	v_rsq_f32_e32 v18, v10
	v_rsq_f32_e32 v20, v11
	v_rsq_f32_e32 v22, v12
	v_rsq_f32_e32 v62, v13
	s_nop 0
	v_pk_mul_f32 v[96:97], v[96:97], v[18:19] op_sel_hi:[1,0]
	v_pk_mul_f32 v[98:99], v[98:99], v[18:19] op_sel_hi:[1,0]
	v_pk_mul_f32 v[100:101], v[100:101], v[18:19] op_sel_hi:[1,0]
	v_pk_mul_f32 v[102:103], v[102:103], v[18:19] op_sel_hi:[1,0]
	v_pk_mul_f32 v[104:105], v[104:105], v[18:19] op_sel_hi:[1,0]
	v_pk_mul_f32 v[106:107], v[106:107], v[18:19] op_sel_hi:[1,0]
	v_pk_mul_f32 v[108:109], v[108:109], v[18:19] op_sel_hi:[1,0]
	v_pk_mul_f32 v[110:111], v[110:111], v[18:19] op_sel_hi:[1,0]
	v_pk_mul_f32 v[96:97], v[24:25], v[96:97]
	v_pk_mul_f32 v[98:99], v[26:27], v[98:99]
	v_pk_mul_f32 v[100:101], v[28:29], v[100:101]
	v_pk_mul_f32 v[102:103], v[30:31], v[102:103]
	v_pk_mul_f32 v[104:105], v[32:33], v[104:105]
	v_pk_mul_f32 v[106:107], v[34:35], v[106:107]
	v_pk_mul_f32 v[108:109], v[36:37], v[108:109]
	v_pk_mul_f32 v[110:111], v[38:39], v[110:111]
	v_pk_fma_f32 v[96:97], v[40:41], v[96:97], v[80:81]
	v_pk_fma_f32 v[98:99], v[42:43], v[98:99], v[82:83]
	v_pk_fma_f32 v[100:101], v[64:65], v[100:101], v[84:85]
	v_pk_fma_f32 v[102:103], v[66:67], v[102:103], v[86:87]
	v_pk_fma_f32 v[104:105], v[68:69], v[104:105], v[88:89]
	v_pk_fma_f32 v[106:107], v[70:71], v[106:107], v[90:91]
	v_pk_fma_f32 v[108:109], v[72:73], v[108:109], v[92:93]
	v_pk_fma_f32 v[110:111], v[74:75], v[110:111], v[94:95]
	v_cvt_pk_bf16_f32 v96, v96, v97
	v_cvt_pk_bf16_f32 v97, v98, v99
	v_cvt_pk_bf16_f32 v100, v100, v101
	v_cvt_pk_bf16_f32 v101, v102, v103
	v_cvt_pk_bf16_f32 v104, v104, v105
	v_cvt_pk_bf16_f32 v105, v106, v107
	v_cvt_pk_bf16_f32 v108, v108, v109
	v_cvt_pk_bf16_f32 v109, v110, v111
	global_store_dwordx2 v2, v[96:97], s[10:11]
	global_store_dwordx2 v2, v[100:101], s[10:11] offset:512
	global_store_dwordx2 v2, v[104:105], s[10:11] offset:1024
	global_store_dwordx2 v2, v[108:109], s[10:11] offset:1536
	s_add_u32 s10, s10, 0x800
; DI unsigned pk2(float lo, float hi) { return f2bf(lo) | (f2bf(hi) << 16); }
; DI void norm_phase(const Args& A, int wave_s, int l, int which, int rows) {
;     ...
;         for (int rr = 0; rr < 2; ++rr) {
;             const int m = m0 + rr; const float* xr; int v;
;             if (m < NLAT) { xr = (from_in ? C.x : C.out) + (size_t)m * 1024; v = m >> 13; }
;             else { xr = (from_in ? C.ctx : C.XC) + (size_t)(m - NLAT) * 1024; v = 4; }
;             modp[rr] = C.SM + SM_MOD + (l * 5 + v) * 6144 + (which == 1 ? 0 : 3072);
; #pragma unroll
;             for (int j = 0; j < 4; ++j) xv[rr][j] = ((const f32x4*)xr)[C.lane + 64 * j];
;         }
; #pragma unroll
;         for (int rr = 0; rr < 2; ++rr) {
;             const int m = m0 + rr;
;             f32x4 sh[4], sc[4];
; #pragma unroll
;             for (int j = 0; j < 4; ++j) { const int col = 4 * (C.lane + 64 * j); sh[j] = *(const f32x4*)(modp[rr] + col); sc[j] = *(const f32x4*)(modp[rr] + 1024 + col); }
;     ...
; #pragma unroll
;             for (int j = 0; j < 4; ++j) { const int col = 4 * (C.lane + 64 * j);
;                 const f32x4 y = xv[rr][j] * rs * g[j] * (sc[j] + 1.f) + sh[j];
;                 v2u o; o.x = pk2(y.x, y.y); o.y = pk2(y.z, y.w);
;                 *(v2u*)(C.H + (size_t)m * 1024 + col) = o; }
	s_addc_u32 s11, s11, 0
	v_pk_mul_f32 v[112:113], v[112:113], v[20:21] op_sel_hi:[1,0]
	v_pk_mul_f32 v[114:115], v[114:115], v[20:21] op_sel_hi:[1,0]
	v_pk_mul_f32 v[116:117], v[116:117], v[20:21] op_sel_hi:[1,0]
	v_pk_mul_f32 v[118:119], v[118:119], v[20:21] op_sel_hi:[1,0]
	v_pk_mul_f32 v[120:121], v[120:121], v[20:21] op_sel_hi:[1,0]
	v_pk_mul_f32 v[122:123], v[122:123], v[20:21] op_sel_hi:[1,0]
	v_pk_mul_f32 v[124:125], v[124:125], v[20:21] op_sel_hi:[1,0]
	v_pk_mul_f32 v[126:127], v[126:127], v[20:21] op_sel_hi:[1,0]
	v_pk_mul_f32 v[112:113], v[24:25], v[112:113]
	v_pk_mul_f32 v[114:115], v[26:27], v[114:115]
	v_pk_mul_f32 v[116:117], v[28:29], v[116:117]
	v_pk_mul_f32 v[118:119], v[30:31], v[118:119]
	v_pk_mul_f32 v[120:121], v[32:33], v[120:121]
	v_pk_mul_f32 v[122:123], v[34:35], v[122:123]
	v_pk_mul_f32 v[124:125], v[36:37], v[124:125]
	v_pk_mul_f32 v[126:127], v[38:39], v[126:127]
	v_pk_fma_f32 v[112:113], v[40:41], v[112:113], v[80:81]
	v_pk_fma_f32 v[114:115], v[42:43], v[114:115], v[82:83]
	v_pk_fma_f32 v[116:117], v[64:65], v[116:117], v[84:85]
	v_pk_fma_f32 v[118:119], v[66:67], v[118:119], v[86:87]
	v_pk_fma_f32 v[120:121], v[68:69], v[120:121], v[88:89]
	v_pk_fma_f32 v[122:123], v[70:71], v[122:123], v[90:91]
	v_pk_fma_f32 v[124:125], v[72:73], v[124:125], v[92:93]
	v_pk_fma_f32 v[126:127], v[74:75], v[126:127], v[94:95]
	v_cvt_pk_bf16_f32 v112, v112, v113
	v_cvt_pk_bf16_f32 v113, v114, v115
	v_cvt_pk_bf16_f32 v116, v116, v117
	v_cvt_pk_bf16_f32 v117, v118, v119
	v_cvt_pk_bf16_f32 v120, v120, v121
	v_cvt_pk_bf16_f32 v121, v122, v123
	v_cvt_pk_bf16_f32 v124, v124, v125
	v_cvt_pk_bf16_f32 v125, v126, v127
	global_store_dwordx2 v2, v[112:113], s[10:11]
	global_store_dwordx2 v2, v[116:117], s[10:11] offset:512
	global_store_dwordx2 v2, v[120:121], s[10:11] offset:1024
	global_store_dwordx2 v2, v[124:125], s[10:11] offset:1536
	s_add_u32 s10, s10, 0x800
	s_addc_u32 s11, s11, 0
	v_pk_mul_f32 v[128:129], v[128:129], v[22:23] op_sel_hi:[1,0]
	v_pk_mul_f32 v[130:131], v[130:131], v[22:23] op_sel_hi:[1,0]
	v_pk_mul_f32 v[132:133], v[132:133], v[22:23] op_sel_hi:[1,0]
	v_pk_mul_f32 v[134:135], v[134:135], v[22:23] op_sel_hi:[1,0]
	v_pk_mul_f32 v[136:137], v[136:137], v[22:23] op_sel_hi:[1,0]
	v_pk_mul_f32 v[138:139], v[138:139], v[22:23] op_sel_hi:[1,0]
	v_pk_mul_f32 v[140:141], v[140:141], v[22:23] op_sel_hi:[1,0]
	v_pk_mul_f32 v[142:143], v[142:143], v[22:23] op_sel_hi:[1,0]
	v_pk_mul_f32 v[128:129], v[24:25], v[128:129]
	v_pk_mul_f32 v[130:131], v[26:27], v[130:131]
	v_pk_mul_f32 v[132:133], v[28:29], v[132:133]
	v_pk_mul_f32 v[134:135], v[30:31], v[134:135]
	v_pk_mul_f32 v[136:137], v[32:33], v[136:137]
	v_pk_mul_f32 v[138:139], v[34:35], v[138:139]
	v_pk_mul_f32 v[140:141], v[36:37], v[140:141]
	v_pk_mul_f32 v[142:143], v[38:39], v[142:143]
	v_pk_fma_f32 v[128:129], v[40:41], v[128:129], v[80:81]
	v_pk_fma_f32 v[130:131], v[42:43], v[130:131], v[82:83]
	v_pk_fma_f32 v[132:133], v[64:65], v[132:133], v[84:85]
	v_pk_fma_f32 v[134:135], v[66:67], v[134:135], v[86:87]
	v_pk_fma_f32 v[136:137], v[68:69], v[136:137], v[88:89]
	v_pk_fma_f32 v[138:139], v[70:71], v[138:139], v[90:91]
	v_pk_fma_f32 v[140:141], v[72:73], v[140:141], v[92:93]
	v_pk_fma_f32 v[142:143], v[74:75], v[142:143], v[94:95]
	v_cvt_pk_bf16_f32 v128, v128, v129
	v_cvt_pk_bf16_f32 v129, v130, v131
	v_cvt_pk_bf16_f32 v132, v132, v133
	v_cvt_pk_bf16_f32 v133, v134, v135
	v_cvt_pk_bf16_f32 v136, v136, v137
	v_cvt_pk_bf16_f32 v137, v138, v139
	v_cvt_pk_bf16_f32 v140, v140, v141
	v_cvt_pk_bf16_f32 v141, v142, v143
	global_store_dwordx2 v2, v[128:129], s[10:11]
	global_store_dwordx2 v2, v[132:133], s[10:11] offset:512
	global_store_dwordx2 v2, v[136:137], s[10:11] offset:1024
	global_store_dwordx2 v2, v[140:141], s[10:11] offset:1536
	s_add_u32 s10, s10, 0x800
	s_addc_u32 s11, s11, 0
	v_pk_mul_f32 v[144:145], v[144:145], v[62:63] op_sel_hi:[1,0]
	v_pk_mul_f32 v[146:147], v[146:147], v[62:63] op_sel_hi:[1,0]
	v_pk_mul_f32 v[148:149], v[148:149], v[62:63] op_sel_hi:[1,0]
	v_pk_mul_f32 v[150:151], v[150:151], v[62:63] op_sel_hi:[1,0]
	v_pk_mul_f32 v[152:153], v[152:153], v[62:63] op_sel_hi:[1,0]
	v_pk_mul_f32 v[154:155], v[154:155], v[62:63] op_sel_hi:[1,0]
	v_pk_mul_f32 v[156:157], v[156:157], v[62:63] op_sel_hi:[1,0]
	v_pk_mul_f32 v[158:159], v[158:159], v[62:63] op_sel_hi:[1,0]
	v_pk_mul_f32 v[144:145], v[24:25], v[144:145]
	v_pk_mul_f32 v[146:147], v[26:27], v[146:147]
	v_pk_mul_f32 v[148:149], v[28:29], v[148:149]
	v_pk_mul_f32 v[150:151], v[30:31], v[150:151]
	v_pk_mul_f32 v[152:153], v[32:33], v[152:153]
	v_pk_mul_f32 v[154:155], v[34:35], v[154:155]
	v_pk_mul_f32 v[156:157], v[36:37], v[156:157]
	v_pk_mul_f32 v[158:159], v[38:39], v[158:159]
	v_pk_fma_f32 v[144:145], v[40:41], v[144:145], v[80:81]
	v_pk_fma_f32 v[146:147], v[42:43], v[146:147], v[82:83]
	v_pk_fma_f32 v[148:149], v[64:65], v[148:149], v[84:85]
	v_pk_fma_f32 v[150:151], v[66:67], v[150:151], v[86:87]
	v_pk_fma_f32 v[152:153], v[68:69], v[152:153], v[88:89]
	v_pk_fma_f32 v[154:155], v[70:71], v[154:155], v[90:91]
	v_pk_fma_f32 v[156:157], v[72:73], v[156:157], v[92:93]
	v_pk_fma_f32 v[158:159], v[74:75], v[158:159], v[94:95]
	v_cvt_pk_bf16_f32 v144, v144, v145
	v_cvt_pk_bf16_f32 v145, v146, v147
	v_cvt_pk_bf16_f32 v148, v148, v149
	v_cvt_pk_bf16_f32 v149, v150, v151
	v_cvt_pk_bf16_f32 v152, v152, v153
	v_cvt_pk_bf16_f32 v153, v154, v155
	v_cvt_pk_bf16_f32 v156, v156, v157
	v_cvt_pk_bf16_f32 v157, v158, v159
	global_store_dwordx2 v2, v[144:145], s[10:11]
	global_store_dwordx2 v2, v[148:149], s[10:11] offset:512
	global_store_dwordx2 v2, v[152:153], s[10:11] offset:1024
	global_store_dwordx2 v2, v[156:157], s[10:11] offset:1536
	s_add_u32 s10, s10, 0x800
	s_addc_u32 s11, s11, 0
	s_mul_i32 s5, s6, 5
	s_add_u32 s5, s5, 4
	s_mul_i32 s5, s5, 0x6000
	s_add_u32 s24, s88, 0x103000
	s_addc_u32 s25, s89, 0
	s_add_u32 s24, s24, s5
	s_addc_u32 s25, s25, 0
	s_add_u32 s26, s24, 0x1000
	s_addc_u32 s27, s25, 0
	global_load_dwordx4 v[96:99], v1, s[30:31] nt
	global_load_dwordx4 v[100:103], v1, s[30:31] offset:1024 nt
	global_load_dwordx4 v[104:107], v1, s[30:31] offset:2048 nt
	global_load_dwordx4 v[108:111], v1, s[30:31] offset:3072 nt
	global_load_dwordx4 v[112:115], v1, s[26:27]
	global_load_dwordx4 v[116:119], v1, s[26:27] offset:1024
	global_load_dwordx4 v[120:123], v1, s[26:27] offset:2048
	global_load_dwordx4 v[124:127], v1, s[26:27] offset:3072
	global_load_dwordx4 v[128:131], v1, s[24:25]
	global_load_dwordx4 v[132:135], v1, s[24:25] offset:1024
	global_load_dwordx4 v[136:139], v1, s[24:25] offset:2048
	global_load_dwordx4 v[140:143], v1, s[24:25] offset:3072
	s_waitcnt vmcnt(28)
; DI unsigned pk2(float lo, float hi) { return f2bf(lo) | (f2bf(hi) << 16); }
; DI void norm_phase(const Args& A, int wave_s, int l, int which, int rows) {
;     ...
;             float ss = 0.f;
; #pragma unroll
;             for (int j = 0; j < 4; ++j) ss += (xv[rr][j].x * xv[rr][j].x + xv[rr][j].y * xv[rr][j].y) + (xv[rr][j].z * xv[rr][j].z + xv[rr][j].w * xv[rr][j].w);
;             ss = wave_sum(C.lane, ss);
;             const float rs = rsqrtf(ss * (1.f / 1024.f) + EPS);
; #pragma unroll
;             for (int j = 0; j < 4; ++j) { const int col = 4 * (C.lane + 64 * j);
;                 const f32x4 y = xv[rr][j] * rs * g[j] * (sc[j] + 1.f) + sh[j];
;                 v2u o; o.x = pk2(y.x, y.y); o.y = pk2(y.z, y.w);
;                 *(v2u*)(C.H + (size_t)m * 1024 + col) = o; }
	v_mul_f32_e32 v10, v164, v164
	v_fmac_f32_e32 v10, v165, v165
	v_fmac_f32_e32 v10, v166, v166
	v_fmac_f32_e32 v10, v167, v167
	v_fmac_f32_e32 v10, v168, v168
	v_fmac_f32_e32 v10, v169, v169
	v_fmac_f32_e32 v10, v170, v170
	v_fmac_f32_e32 v10, v171, v171
	v_fmac_f32_e32 v10, v172, v172
	v_fmac_f32_e32 v10, v173, v173
	v_fmac_f32_e32 v10, v174, v174
	v_fmac_f32_e32 v10, v175, v175
	v_fmac_f32_e32 v10, v176, v176
	v_fmac_f32_e32 v10, v177, v177
	v_fmac_f32_e32 v10, v178, v178
	v_fmac_f32_e32 v10, v179, v179
	v_mul_f32_e32 v11, v180, v180
	v_fmac_f32_e32 v11, v181, v181
	v_fmac_f32_e32 v11, v182, v182
	v_fmac_f32_e32 v11, v183, v183
	v_fmac_f32_e32 v11, v184, v184
	v_fmac_f32_e32 v11, v185, v185
	v_fmac_f32_e32 v11, v186, v186
	v_fmac_f32_e32 v11, v187, v187
	v_fmac_f32_e32 v11, v188, v188
	v_fmac_f32_e32 v11, v189, v189
	v_fmac_f32_e32 v11, v190, v190
	v_fmac_f32_e32 v11, v191, v191
	v_fmac_f32_e32 v11, v192, v192
	v_fmac_f32_e32 v11, v193, v193
	v_fmac_f32_e32 v11, v194, v194
	v_fmac_f32_e32 v11, v195, v195
	v_mul_f32_e32 v12, v196, v196
	v_fmac_f32_e32 v12, v197, v197
	v_fmac_f32_e32 v12, v198, v198
	v_fmac_f32_e32 v12, v199, v199
	v_fmac_f32_e32 v12, v200, v200
	v_fmac_f32_e32 v12, v201, v201
	v_fmac_f32_e32 v12, v202, v202
	v_fmac_f32_e32 v12, v203, v203
	v_fmac_f32_e32 v12, v204, v204
	v_fmac_f32_e32 v12, v205, v205
	v_fmac_f32_e32 v12, v206, v206
	v_fmac_f32_e32 v12, v207, v207
	v_fmac_f32_e32 v12, v208, v208
	v_fmac_f32_e32 v12, v209, v209
	v_fmac_f32_e32 v12, v210, v210
	v_fmac_f32_e32 v12, v211, v211
	v_mul_f32_e32 v13, v212, v212
	v_fmac_f32_e32 v13, v213, v213
	v_fmac_f32_e32 v13, v214, v214
	v_fmac_f32_e32 v13, v215, v215
	v_fmac_f32_e32 v13, v216, v216
	v_fmac_f32_e32 v13, v217, v217
	v_fmac_f32_e32 v13, v218, v218
	v_fmac_f32_e32 v13, v219, v219
	v_fmac_f32_e32 v13, v220, v220
	v_fmac_f32_e32 v13, v221, v221
	v_fmac_f32_e32 v13, v222, v222
	v_fmac_f32_e32 v13, v223, v223
	v_fmac_f32_e32 v13, v224, v224
	v_fmac_f32_e32 v13, v225, v225
	v_fmac_f32_e32 v13, v226, v226
	v_fmac_f32_e32 v13, v227, v227
	ds_bpermute_b32 v14, v4, v10
	ds_bpermute_b32 v15, v4, v11
	ds_bpermute_b32 v16, v4, v12
	ds_bpermute_b32 v17, v4, v13
	s_waitcnt lgkmcnt(0)
	v_add_f32_e32 v10, v10, v14
	v_add_f32_e32 v11, v11, v15
	v_add_f32_e32 v12, v12, v16
	v_add_f32_e32 v13, v13, v17
	ds_bpermute_b32 v14, v5, v10
	ds_bpermute_b32 v15, v5, v11
	ds_bpermute_b32 v16, v5, v12
	ds_bpermute_b32 v17, v5, v13
	s_waitcnt lgkmcnt(0)
	v_add_f32_e32 v10, v10, v14
	v_add_f32_e32 v11, v11, v15
	v_add_f32_e32 v12, v12, v16
	v_add_f32_e32 v13, v13, v17
	ds_bpermute_b32 v14, v6, v10
	ds_bpermute_b32 v15, v6, v11
	ds_bpermute_b32 v16, v6, v12
	ds_bpermute_b32 v17, v6, v13
	s_waitcnt lgkmcnt(0)
	v_add_f32_e32 v10, v10, v14
	v_add_f32_e32 v11, v11, v15
	v_add_f32_e32 v12, v12, v16
	v_add_f32_e32 v13, v13, v17
	ds_bpermute_b32 v14, v7, v10
	ds_bpermute_b32 v15, v7, v11
	ds_bpermute_b32 v16, v7, v12
	ds_bpermute_b32 v17, v7, v13
	s_waitcnt lgkmcnt(0)
	v_add_f32_e32 v10, v10, v14
	v_add_f32_e32 v11, v11, v15
	v_add_f32_e32 v12, v12, v16
	v_add_f32_e32 v13, v13, v17
	ds_bpermute_b32 v14, v8, v10
	ds_bpermute_b32 v15, v8, v11
	ds_bpermute_b32 v16, v8, v12
	ds_bpermute_b32 v17, v8, v13
	s_waitcnt lgkmcnt(0)
	v_add_f32_e32 v10, v10, v14
	v_add_f32_e32 v11, v11, v15
	v_add_f32_e32 v12, v12, v16
	v_add_f32_e32 v13, v13, v17
	ds_bpermute_b32 v14, v9, v10
	ds_bpermute_b32 v15, v9, v11
	ds_bpermute_b32 v16, v9, v12
	ds_bpermute_b32 v17, v9, v13
	s_waitcnt lgkmcnt(0)
	v_add_f32_e32 v10, v10, v14
	v_add_f32_e32 v11, v11, v15
	v_add_f32_e32 v12, v12, v16
	v_add_f32_e32 v13, v13, v17
	v_fma_f32 v10, v10, s32, v60
	v_fma_f32 v11, v11, s32, v60
	v_fma_f32 v12, v12, s32, v60
	v_fma_f32 v13, v13, s32, v60
	v_rsq_f32_e32 v18, v10
	v_rsq_f32_e32 v20, v11
	v_rsq_f32_e32 v22, v12
	v_rsq_f32_e32 v62, v13
	s_nop 0
	v_pk_mul_f32 v[164:165], v[164:165], v[18:19] op_sel_hi:[1,0]
	v_pk_mul_f32 v[166:167], v[166:167], v[18:19] op_sel_hi:[1,0]
	v_pk_mul_f32 v[168:169], v[168:169], v[18:19] op_sel_hi:[1,0]
	v_pk_mul_f32 v[170:171], v[170:171], v[18:19] op_sel_hi:[1,0]
	v_pk_mul_f32 v[172:173], v[172:173], v[18:19] op_sel_hi:[1,0]
	v_pk_mul_f32 v[174:175], v[174:175], v[18:19] op_sel_hi:[1,0]
	v_pk_mul_f32 v[176:177], v[176:177], v[18:19] op_sel_hi:[1,0]
	v_pk_mul_f32 v[178:179], v[178:179], v[18:19] op_sel_hi:[1,0]
	v_pk_mul_f32 v[164:165], v[24:25], v[164:165]
	v_pk_mul_f32 v[166:167], v[26:27], v[166:167]
	v_pk_mul_f32 v[168:169], v[28:29], v[168:169]
	v_pk_mul_f32 v[170:171], v[30:31], v[170:171]
	v_pk_mul_f32 v[172:173], v[32:33], v[172:173]
	v_pk_mul_f32 v[174:175], v[34:35], v[174:175]
	v_pk_mul_f32 v[176:177], v[36:37], v[176:177]
	v_pk_mul_f32 v[178:179], v[38:39], v[178:179]
	v_pk_fma_f32 v[164:165], v[40:41], v[164:165], v[80:81]
	v_pk_fma_f32 v[166:167], v[42:43], v[166:167], v[82:83]
	v_pk_fma_f32 v[168:169], v[64:65], v[168:169], v[84:85]
	v_pk_fma_f32 v[170:171], v[66:67], v[170:171], v[86:87]
	v_pk_fma_f32 v[172:173], v[68:69], v[172:173], v[88:89]
	v_pk_fma_f32 v[174:175], v[70:71], v[174:175], v[90:91]
	v_pk_fma_f32 v[176:177], v[72:73], v[176:177], v[92:93]
	v_pk_fma_f32 v[178:179], v[74:75], v[178:179], v[94:95]
	v_cvt_pk_bf16_f32 v164, v164, v165
	v_cvt_pk_bf16_f32 v165, v166, v167
	v_cvt_pk_bf16_f32 v168, v168, v169
	v_cvt_pk_bf16_f32 v169, v170, v171
	v_cvt_pk_bf16_f32 v172, v172, v173
	v_cvt_pk_bf16_f32 v173, v174, v175
	v_cvt_pk_bf16_f32 v176, v176, v177
	v_cvt_pk_bf16_f32 v177, v178, v179
	global_store_dwordx2 v2, v[164:165], s[10:11]
	global_store_dwordx2 v2, v[168:169], s[10:11] offset:512
	global_store_dwordx2 v2, v[172:173], s[10:11] offset:1024
	global_store_dwordx2 v2, v[176:177], s[10:11] offset:1536
; DI unsigned pk2(float lo, float hi) { return f2bf(lo) | (f2bf(hi) << 16); }
; DI void norm_phase(const Args& A, int wave_s, int l, int which, int rows) {
;     ...
;         for (int rr = 0; rr < 2; ++rr) {
;             const int m = m0 + rr; const float* xr; int v;
;             if (m < NLAT) { xr = (from_in ? C.x : C.out) + (size_t)m * 1024; v = m >> 13; }
;             else { xr = (from_in ? C.ctx : C.XC) + (size_t)(m - NLAT) * 1024; v = 4; }
;             modp[rr] = C.SM + SM_MOD + (l * 5 + v) * 6144 + (which == 1 ? 0 : 3072);
; #pragma unroll
;             for (int j = 0; j < 4; ++j) xv[rr][j] = ((const f32x4*)xr)[C.lane + 64 * j];
;         }
; #pragma unroll
;         for (int rr = 0; rr < 2; ++rr) {
;             const int m = m0 + rr;
;             f32x4 sh[4], sc[4];
; #pragma unroll
;             for (int j = 0; j < 4; ++j) { const int col = 4 * (C.lane + 64 * j); sh[j] = *(const f32x4*)(modp[rr] + col); sc[j] = *(const f32x4*)(modp[rr] + 1024 + col); }
;     ...
; #pragma unroll
;             for (int j = 0; j < 4; ++j) { const int col = 4 * (C.lane + 64 * j);
;                 const f32x4 y = xv[rr][j] * rs * g[j] * (sc[j] + 1.f) + sh[j];
;                 v2u o; o.x = pk2(y.x, y.y); o.y = pk2(y.z, y.w);
;                 *(v2u*)(C.H + (size_t)m * 1024 + col) = o; }
	s_add_u32 s10, s10, 0x800
	s_addc_u32 s11, s11, 0
	v_pk_mul_f32 v[180:181], v[180:181], v[20:21] op_sel_hi:[1,0]
	v_pk_mul_f32 v[182:183], v[182:183], v[20:21] op_sel_hi:[1,0]
	v_pk_mul_f32 v[184:185], v[184:185], v[20:21] op_sel_hi:[1,0]
	v_pk_mul_f32 v[186:187], v[186:187], v[20:21] op_sel_hi:[1,0]
	v_pk_mul_f32 v[188:189], v[188:189], v[20:21] op_sel_hi:[1,0]
	v_pk_mul_f32 v[190:191], v[190:191], v[20:21] op_sel_hi:[1,0]
	v_pk_mul_f32 v[192:193], v[192:193], v[20:21] op_sel_hi:[1,0]
	v_pk_mul_f32 v[194:195], v[194:195], v[20:21] op_sel_hi:[1,0]
	v_pk_mul_f32 v[180:181], v[24:25], v[180:181]
	v_pk_mul_f32 v[182:183], v[26:27], v[182:183]
	v_pk_mul_f32 v[184:185], v[28:29], v[184:185]
	v_pk_mul_f32 v[186:187], v[30:31], v[186:187]
	v_pk_mul_f32 v[188:189], v[32:33], v[188:189]
	v_pk_mul_f32 v[190:191], v[34:35], v[190:191]
	v_pk_mul_f32 v[192:193], v[36:37], v[192:193]
	v_pk_mul_f32 v[194:195], v[38:39], v[194:195]
	v_pk_fma_f32 v[180:181], v[40:41], v[180:181], v[80:81]
	v_pk_fma_f32 v[182:183], v[42:43], v[182:183], v[82:83]
	v_pk_fma_f32 v[184:185], v[64:65], v[184:185], v[84:85]
	v_pk_fma_f32 v[186:187], v[66:67], v[186:187], v[86:87]
	v_pk_fma_f32 v[188:189], v[68:69], v[188:189], v[88:89]
	v_pk_fma_f32 v[190:191], v[70:71], v[190:191], v[90:91]
	v_pk_fma_f32 v[192:193], v[72:73], v[192:193], v[92:93]
	v_pk_fma_f32 v[194:195], v[74:75], v[194:195], v[94:95]
	v_cvt_pk_bf16_f32 v180, v180, v181
	v_cvt_pk_bf16_f32 v181, v182, v183
	v_cvt_pk_bf16_f32 v184, v184, v185
	v_cvt_pk_bf16_f32 v185, v186, v187
	v_cvt_pk_bf16_f32 v188, v188, v189
	v_cvt_pk_bf16_f32 v189, v190, v191
	v_cvt_pk_bf16_f32 v192, v192, v193
	v_cvt_pk_bf16_f32 v193, v194, v195
	global_store_dwordx2 v2, v[180:181], s[10:11]
	global_store_dwordx2 v2, v[184:185], s[10:11] offset:512
	global_store_dwordx2 v2, v[188:189], s[10:11] offset:1024
	global_store_dwordx2 v2, v[192:193], s[10:11] offset:1536
	s_add_u32 s10, s10, 0x800
	s_addc_u32 s11, s11, 0
	v_pk_mul_f32 v[196:197], v[196:197], v[22:23] op_sel_hi:[1,0]
	v_pk_mul_f32 v[198:199], v[198:199], v[22:23] op_sel_hi:[1,0]
	v_pk_mul_f32 v[200:201], v[200:201], v[22:23] op_sel_hi:[1,0]
	v_pk_mul_f32 v[202:203], v[202:203], v[22:23] op_sel_hi:[1,0]
	v_pk_mul_f32 v[204:205], v[204:205], v[22:23] op_sel_hi:[1,0]
	v_pk_mul_f32 v[206:207], v[206:207], v[22:23] op_sel_hi:[1,0]
	v_pk_mul_f32 v[208:209], v[208:209], v[22:23] op_sel_hi:[1,0]
	v_pk_mul_f32 v[210:211], v[210:211], v[22:23] op_sel_hi:[1,0]
	v_pk_mul_f32 v[196:197], v[24:25], v[196:197]
	v_pk_mul_f32 v[198:199], v[26:27], v[198:199]
	v_pk_mul_f32 v[200:201], v[28:29], v[200:201]
	v_pk_mul_f32 v[202:203], v[30:31], v[202:203]
	v_pk_mul_f32 v[204:205], v[32:33], v[204:205]
	v_pk_mul_f32 v[206:207], v[34:35], v[206:207]
	v_pk_mul_f32 v[208:209], v[36:37], v[208:209]
	v_pk_mul_f32 v[210:211], v[38:39], v[210:211]
	v_pk_fma_f32 v[196:197], v[40:41], v[196:197], v[80:81]
	v_pk_fma_f32 v[198:199], v[42:43], v[198:199], v[82:83]
	v_pk_fma_f32 v[200:201], v[64:65], v[200:201], v[84:85]
	v_pk_fma_f32 v[202:203], v[66:67], v[202:203], v[86:87]
	v_pk_fma_f32 v[204:205], v[68:69], v[204:205], v[88:89]
	v_pk_fma_f32 v[206:207], v[70:71], v[206:207], v[90:91]
	v_pk_fma_f32 v[208:209], v[72:73], v[208:209], v[92:93]
	v_pk_fma_f32 v[210:211], v[74:75], v[210:211], v[94:95]
	v_cvt_pk_bf16_f32 v196, v196, v197
	v_cvt_pk_bf16_f32 v197, v198, v199
	v_cvt_pk_bf16_f32 v200, v200, v201
	v_cvt_pk_bf16_f32 v201, v202, v203
	v_cvt_pk_bf16_f32 v204, v204, v205
	v_cvt_pk_bf16_f32 v205, v206, v207
	v_cvt_pk_bf16_f32 v208, v208, v209
	v_cvt_pk_bf16_f32 v209, v210, v211
	global_store_dwordx2 v2, v[196:197], s[10:11]
	global_store_dwordx2 v2, v[200:201], s[10:11] offset:512
	global_store_dwordx2 v2, v[204:205], s[10:11] offset:1024
	global_store_dwordx2 v2, v[208:209], s[10:11] offset:1536
	s_add_u32 s10, s10, 0x800
	s_addc_u32 s11, s11, 0
	v_pk_mul_f32 v[212:213], v[212:213], v[62:63] op_sel_hi:[1,0]
	v_pk_mul_f32 v[214:215], v[214:215], v[62:63] op_sel_hi:[1,0]
	v_pk_mul_f32 v[216:217], v[216:217], v[62:63] op_sel_hi:[1,0]
	v_pk_mul_f32 v[218:219], v[218:219], v[62:63] op_sel_hi:[1,0]
	v_pk_mul_f32 v[220:221], v[220:221], v[62:63] op_sel_hi:[1,0]
	v_pk_mul_f32 v[222:223], v[222:223], v[62:63] op_sel_hi:[1,0]
	v_pk_mul_f32 v[224:225], v[224:225], v[62:63] op_sel_hi:[1,0]
	v_pk_mul_f32 v[226:227], v[226:227], v[62:63] op_sel_hi:[1,0]
	v_pk_mul_f32 v[212:213], v[24:25], v[212:213]
	v_pk_mul_f32 v[214:215], v[26:27], v[214:215]
	v_pk_mul_f32 v[216:217], v[28:29], v[216:217]
	v_pk_mul_f32 v[218:219], v[30:31], v[218:219]
	v_pk_mul_f32 v[220:221], v[32:33], v[220:221]
	v_pk_mul_f32 v[222:223], v[34:35], v[222:223]
	v_pk_mul_f32 v[224:225], v[36:37], v[224:225]
	v_pk_mul_f32 v[226:227], v[38:39], v[226:227]
	v_pk_fma_f32 v[212:213], v[40:41], v[212:213], v[80:81]
	v_pk_fma_f32 v[214:215], v[42:43], v[214:215], v[82:83]
	v_pk_fma_f32 v[216:217], v[64:65], v[216:217], v[84:85]
	v_pk_fma_f32 v[218:219], v[66:67], v[218:219], v[86:87]
	v_pk_fma_f32 v[220:221], v[68:69], v[220:221], v[88:89]
	v_pk_fma_f32 v[222:223], v[70:71], v[222:223], v[90:91]
	v_pk_fma_f32 v[224:225], v[72:73], v[224:225], v[92:93]
	v_pk_fma_f32 v[226:227], v[74:75], v[226:227], v[94:95]
	v_cvt_pk_bf16_f32 v212, v212, v213
	v_cvt_pk_bf16_f32 v213, v214, v215
	v_cvt_pk_bf16_f32 v216, v216, v217
	v_cvt_pk_bf16_f32 v217, v218, v219
	v_cvt_pk_bf16_f32 v220, v220, v221
	v_cvt_pk_bf16_f32 v221, v222, v223
	v_cvt_pk_bf16_f32 v224, v224, v225
	v_cvt_pk_bf16_f32 v225, v226, v227
	global_store_dwordx2 v2, v[212:213], s[10:11]
	global_store_dwordx2 v2, v[216:217], s[10:11] offset:512
	global_store_dwordx2 v2, v[220:221], s[10:11] offset:1024
	global_store_dwordx2 v2, v[224:225], s[10:11] offset:1536
	s_add_u32 s10, s10, 0x800
	s_addc_u32 s11, s11, 0
	s_add_u32 s10, s88, 0x3800000
	s_addc_u32 s11, s89, 0
	s_add_u32 s10, s10, 0x4000000
	s_addc_u32 s11, s11, 0
	s_lshl_b32 s5, s7, 11
	s_add_u32 s10, s10, s5
	s_addc_u32 s11, s11, 0
	s_waitcnt vmcnt(16)
	v_pk_add_f32 v[112:113], v[112:113], 1.0 op_sel_hi:[1,0]
	v_pk_add_f32 v[114:115], v[114:115], 1.0 op_sel_hi:[1,0]
	v_pk_add_f32 v[116:117], v[116:117], 1.0 op_sel_hi:[1,0]
	v_pk_add_f32 v[118:119], v[118:119], 1.0 op_sel_hi:[1,0]
	v_pk_add_f32 v[120:121], v[120:121], 1.0 op_sel_hi:[1,0]
	v_pk_add_f32 v[122:123], v[122:123], 1.0 op_sel_hi:[1,0]
	v_pk_add_f32 v[124:125], v[124:125], 1.0 op_sel_hi:[1,0]
	v_pk_add_f32 v[126:127], v[126:127], 1.0 op_sel_hi:[1,0]
	s_cmp_eq_u32 s2, 0
	s_cbranch_scc1 .Lnorm_n2_done
; DI unsigned pk2(float lo, float hi) { return f2bf(lo) | (f2bf(hi) << 16); }
; DI void norm_phase(const Args& A, int wave_s, int l, int which, int rows) {
;     ...
;         for (int rr = 0; rr < 2; ++rr) {
;             const int m = m0 + rr;
;             f32x4 sh[4], sc[4];
; #pragma unroll
;             for (int j = 0; j < 4; ++j) { const int col = 4 * (C.lane + 64 * j); sh[j] = *(const f32x4*)(modp[rr] + col); sc[j] = *(const f32x4*)(modp[rr] + 1024 + col); }
;             float ss = 0.f;
; #pragma unroll
;             for (int j = 0; j < 4; ++j) ss += (xv[rr][j].x * xv[rr][j].x + xv[rr][j].y * xv[rr][j].y) + (xv[rr][j].z * xv[rr][j].z + xv[rr][j].w * xv[rr][j].w);
;             ss = wave_sum(C.lane, ss);
;             const float rs = rsqrtf(ss * (1.f / 1024.f) + EPS);
; #pragma unroll
;             for (int j = 0; j < 4; ++j) { const int col = 4 * (C.lane + 64 * j);
;                 const f32x4 y = xv[rr][j] * rs * g[j] * (sc[j] + 1.f) + sh[j];
;                 v2u o; o.x = pk2(y.x, y.y); o.y = pk2(y.z, y.w);
;                 *(v2u*)(C.H + (size_t)m * 1024 + col) = o; }
	v_mul_f32_e32 v10, v96, v96
	v_fmac_f32_e32 v10, v97, v97
	v_fmac_f32_e32 v10, v98, v98
	v_fmac_f32_e32 v10, v99, v99
	v_fmac_f32_e32 v10, v100, v100
	v_fmac_f32_e32 v10, v101, v101
	v_fmac_f32_e32 v10, v102, v102
	v_fmac_f32_e32 v10, v103, v103
	v_fmac_f32_e32 v10, v104, v104
	v_fmac_f32_e32 v10, v105, v105
	v_fmac_f32_e32 v10, v106, v106
	v_fmac_f32_e32 v10, v107, v107
	v_fmac_f32_e32 v10, v108, v108
	v_fmac_f32_e32 v10, v109, v109
	v_fmac_f32_e32 v10, v110, v110
	v_fmac_f32_e32 v10, v111, v111
	ds_bpermute_b32 v14, v4, v10
	s_waitcnt lgkmcnt(0)
	v_add_f32_e32 v10, v10, v14
	ds_bpermute_b32 v14, v5, v10
	s_waitcnt lgkmcnt(0)
	v_add_f32_e32 v10, v10, v14
	ds_bpermute_b32 v14, v6, v10
	s_waitcnt lgkmcnt(0)
	v_add_f32_e32 v10, v10, v14
	ds_bpermute_b32 v14, v7, v10
	s_waitcnt lgkmcnt(0)
	v_add_f32_e32 v10, v10, v14
	ds_bpermute_b32 v14, v8, v10
	s_waitcnt lgkmcnt(0)
	v_add_f32_e32 v10, v10, v14
	ds_bpermute_b32 v14, v9, v10
	s_waitcnt lgkmcnt(0)
	v_add_f32_e32 v10, v10, v14
	v_fma_f32 v10, v10, s32, v60
	v_rsq_f32_e32 v18, v10
	s_nop 0
	v_pk_mul_f32 v[96:97], v[96:97], v[18:19] op_sel_hi:[1,0]
	v_pk_mul_f32 v[98:99], v[98:99], v[18:19] op_sel_hi:[1,0]
	v_pk_mul_f32 v[100:101], v[100:101], v[18:19] op_sel_hi:[1,0]
	v_pk_mul_f32 v[102:103], v[102:103], v[18:19] op_sel_hi:[1,0]
	v_pk_mul_f32 v[104:105], v[104:105], v[18:19] op_sel_hi:[1,0]
	v_pk_mul_f32 v[106:107], v[106:107], v[18:19] op_sel_hi:[1,0]
	v_pk_mul_f32 v[108:109], v[108:109], v[18:19] op_sel_hi:[1,0]
	v_pk_mul_f32 v[110:111], v[110:111], v[18:19] op_sel_hi:[1,0]
	v_pk_mul_f32 v[96:97], v[24:25], v[96:97]
	v_pk_mul_f32 v[98:99], v[26:27], v[98:99]
	v_pk_mul_f32 v[100:101], v[28:29], v[100:101]
	v_pk_mul_f32 v[102:103], v[30:31], v[102:103]
	v_pk_mul_f32 v[104:105], v[32:33], v[104:105]
	v_pk_mul_f32 v[106:107], v[34:35], v[106:107]
	v_pk_mul_f32 v[108:109], v[36:37], v[108:109]
	v_pk_mul_f32 v[110:111], v[38:39], v[110:111]
	v_pk_fma_f32 v[96:97], v[112:113], v[96:97], v[128:129]
	v_pk_fma_f32 v[98:99], v[114:115], v[98:99], v[130:131]
	v_pk_fma_f32 v[100:101], v[116:117], v[100:101], v[132:133]
	v_pk_fma_f32 v[102:103], v[118:119], v[102:103], v[134:135]
	v_pk_fma_f32 v[104:105], v[120:121], v[104:105], v[136:137]
	v_pk_fma_f32 v[106:107], v[122:123], v[106:107], v[138:139]
	v_pk_fma_f32 v[108:109], v[124:125], v[108:109], v[140:141]
	v_pk_fma_f32 v[110:111], v[126:127], v[110:111], v[142:143]
	v_cvt_pk_bf16_f32 v96, v96, v97
	v_cvt_pk_bf16_f32 v97, v98, v99
	v_cvt_pk_bf16_f32 v100, v100, v101
	v_cvt_pk_bf16_f32 v101, v102, v103
	v_cvt_pk_bf16_f32 v104, v104, v105
	v_cvt_pk_bf16_f32 v105, v106, v107
	v_cvt_pk_bf16_f32 v108, v108, v109
	v_cvt_pk_bf16_f32 v109, v110, v111
	global_store_dwordx2 v2, v[96:97], s[10:11]
	global_store_dwordx2 v2, v[100:101], s[10:11] offset:512
	global_store_dwordx2 v2, v[104:105], s[10:11] offset:1024
	global_store_dwordx2 v2, v[108:109], s[10:11] offset:1536
